# merged pre-barrier waits, dropped redundant post-barrier lgkmcnt wait in K-loops; SwiGLU epilogue row-scale loads batched; redundant max canonicalisation removed in attention loop
# speedup vs baseline: 1.0083x; 1.0083x over previous
; #define PG8_STAGE(bufoff, gbase, voff) do { _Pragma("unroll") for (int _i = 0; _i < 2; ++_i) \
;         __builtin_amdgcn_global_load_lds((const unsigned*)((const char*)(gbase) + (voff)[_i]), (PG8_LAS unsigned*)(lds + (bufoff) + ldsw + _i * 8192), 16, 0, 0); } while (0)
; #define PG8_LDA(dst, b, h) do { _Pragma("unroll") for (int m = 0; m < 4; ++m) _Pragma("unroll") for (int k = 0; k < 2; ++k) dst[m][k] = *(const PG8_LAS bf16x8*)(lds + PG8_SA(b, h) + aoff + m * 2048 + k * 1024); } while (0)
; #define PG8_LDB(dst, b, h) do { _Pragma("unroll") for (int n = 0; n < 2; ++n) _Pragma("unroll") for (int k = 0; k < 2; ++k) dst[n][k] = *(const PG8_LAS bf16x8*)(lds + PG8_SB(b, h) + boff + n * 2048 + k * 1024); } while (0)
; #define PG8_MMA(ai, bj, At, Bt) do { __builtin_amdgcn_s_setprio(1); _Pragma("unroll") for (int m = 0; m < 4; ++m) _Pragma("unroll") for (int n = 0; n < 2; ++n) _Pragma("unroll") for (int k = 0; k < 2; ++k) \
;         acc[ai][bj][m][n] = __builtin_amdgcn_mfma_f32_16x16x32_bf16(Bt[n][k], At[m][k], acc[ai][bj][m][n], 0, 0, 0); __builtin_amdgcn_s_setprio(0); } while (0)
; #define PG8_WAIT_V(n) asm volatile("s_waitcnt vmcnt(" #n ")" ::: "memory")
; #define PG8_WAIT_L(n) asm volatile("s_waitcnt lgkmcnt(" #n ")" ::: "memory")
; #define PG8_BAR __builtin_amdgcn_s_barrier()
; #define PG8_SCHED __builtin_amdgcn_sched_barrier(0)
; template <class Epi, class Sched, bool ALIGN_EPI = false, bool SP2 = false, bool KSEG = false>
; __device__ __forceinline__ void gemm_phase(PG8_LAS unsigned char* lds, const Gemm g, const Sched& S, const Epi& E) {
;     ...
;             PG8_LDB(B0, 0, 0); PG8_LDB(B1, 0, 1); PG8_SCHED; PG8_LDA(At, 0, 0); PG8_STAGE(PG8_SA(1, 1), a1 + hstep, voffA);
;             PG8_WAIT_V(8); PG8_WAIT_L(0); PG8_BAR; PG8_MMA(0, 0, At, B0); PG8_MMA(0, 1, At, B1); PG8_BAR; PG8_SCHED;
;             PG8_LDA(At, 0, 1); PG8_STAGE(PG8_SB(0, 0), b2, voffB); PG8_STAGE(PG8_SB(0, 1), b2 + hstep, voffB); PG8_STAGE(PG8_SA(0, 0), a2, voffA);
;             PG8_WAIT_V(8); PG8_WAIT_L(0); PG8_BAR; PG8_MMA(1, 0, At, B0); PG8_MMA(1, 1, At, B1); PG8_BAR; PG8_SCHED;
.LBB0_120:
	ds_read_b128 v[146:149], v156
	ds_read_b128 v[150:153], v156 offset:1024
	ds_read_b128 v[160:163], v156 offset:2048
	ds_read_b128 v[164:167], v156 offset:3072
	ds_read_b128 v[168:171], v157
	ds_read_b128 v[172:175], v157 offset:1024
	ds_read_b128 v[176:179], v157 offset:2048
	ds_read_b128 v[180:183], v157 offset:3072
	s_add_u32 s30, s28, 0xfff80080
	s_addc_u32 s31, s29, -1
	s_cmp_eq_u32 s80, 28
	s_cselect_b32 s43, s21, s31
	s_cselect_b32 s42, s64, s30
	s_cselect_b32 s31, s19, s67
	s_cselect_b32 s30, s65, s66
	s_add_u32 s98, s28, 0xfff80000
	s_addc_u32 s99, s29, -1
	s_mov_b32 m0, s51
	v_lshl_add_u64 v[216:217], s[98:99], 0, v[136:137]
	global_load_lds_dwordx4 v[216:217], off
	s_mov_b32 m0, s58
	v_lshl_add_u64 v[216:217], s[98:99], 0, v[132:133]
	global_load_lds_dwordx4 v[216:217], off
	v_lshl_add_u64 v[216:217], s[28:29], 0, v[138:139]
	s_add_i32 m0, s27, 0xc000
	ds_read_b128 v[184:187], v158
	ds_read_b128 v[188:191], v158 offset:1024
	ds_read_b128 v[192:195], v158 offset:2048
	ds_read_b128 v[196:199], v158 offset:3072
	ds_read_b128 v[200:203], v158 offset:4096
	ds_read_b128 v[204:207], v158 offset:5120
	ds_read_b128 v[208:211], v158 offset:6144
	ds_read_b128 v[212:215], v158 offset:7168
	global_load_lds_dwordx4 v[216:217], off
	s_add_i32 m0, s27, 0xe000
	v_lshl_add_u64 v[216:217], s[28:29], 0, v[140:141]
	global_load_lds_dwordx4 v[216:217], off
	s_waitcnt vmcnt(8) lgkmcnt(0)
	s_barrier
	s_setprio 1
	v_mfma_f32_16x16x32_bf16 v[126:129], v[146:149], v[184:187], v[126:129]
	v_mfma_f32_16x16x32_bf16 v[122:125], v[160:163], v[184:187], v[122:125]
	v_mfma_f32_16x16x32_bf16 v[110:113], v[146:149], v[192:195], v[110:113]
	v_mfma_f32_16x16x32_bf16 v[106:109], v[160:163], v[192:195], v[106:109]
	v_mfma_f32_16x16x32_bf16 v[94:97], v[146:149], v[200:203], v[94:97]
	v_mfma_f32_16x16x32_bf16 v[90:93], v[160:163], v[200:203], v[90:93]
	v_mfma_f32_16x16x32_bf16 v[78:81], v[146:149], v[208:211], v[78:81]
	v_mfma_f32_16x16x32_bf16 v[74:77], v[160:163], v[208:211], v[74:77]
	v_mfma_f32_16x16x32_bf16 v[126:129], v[150:153], v[188:191], v[126:129]
	v_mfma_f32_16x16x32_bf16 v[122:125], v[164:167], v[188:191], v[122:125]
	v_mfma_f32_16x16x32_bf16 v[110:113], v[150:153], v[196:199], v[110:113]
	v_mfma_f32_16x16x32_bf16 v[106:109], v[164:167], v[196:199], v[106:109]
	v_mfma_f32_16x16x32_bf16 v[94:97], v[150:153], v[204:207], v[94:97]
	v_mfma_f32_16x16x32_bf16 v[90:93], v[164:167], v[204:207], v[90:93]
	v_mfma_f32_16x16x32_bf16 v[78:81], v[150:153], v[212:215], v[78:81]
	v_mfma_f32_16x16x32_bf16 v[74:77], v[164:167], v[212:215], v[74:77]
	s_setprio 0
	s_setprio 1
	v_mfma_f32_16x16x32_bf16 v[118:121], v[168:171], v[184:187], v[118:121]
	v_mfma_f32_16x16x32_bf16 v[114:117], v[176:179], v[184:187], v[114:117]
	v_mfma_f32_16x16x32_bf16 v[102:105], v[168:171], v[192:195], v[102:105]
	v_mfma_f32_16x16x32_bf16 v[98:101], v[176:179], v[192:195], v[98:101]
	v_mfma_f32_16x16x32_bf16 v[86:89], v[168:171], v[200:203], v[86:89]
	v_mfma_f32_16x16x32_bf16 v[82:85], v[176:179], v[200:203], v[82:85]
	v_mfma_f32_16x16x32_bf16 v[70:73], v[168:171], v[208:211], v[70:73]
	v_mfma_f32_16x16x32_bf16 v[66:69], v[176:179], v[208:211], v[66:69]
	v_mfma_f32_16x16x32_bf16 v[118:121], v[172:175], v[188:191], v[118:121]
	v_mfma_f32_16x16x32_bf16 v[114:117], v[180:183], v[188:191], v[114:117]
	v_mfma_f32_16x16x32_bf16 v[102:105], v[172:175], v[196:199], v[102:105]
	v_mfma_f32_16x16x32_bf16 v[98:101], v[180:183], v[196:199], v[98:101]
	v_mfma_f32_16x16x32_bf16 v[86:89], v[172:175], v[204:207], v[86:89]
	v_mfma_f32_16x16x32_bf16 v[82:85], v[180:183], v[204:207], v[82:85]
	v_mfma_f32_16x16x32_bf16 v[70:73], v[172:175], v[212:215], v[70:73]
	v_mfma_f32_16x16x32_bf16 v[66:69], v[180:183], v[212:215], v[66:69]
	s_setprio 0
	s_barrier
	s_add_i32 s33, s60, s44
	v_lshl_add_u64 v[216:217], s[30:31], 0, v[134:135]
	s_mov_b32 m0, s33
	ds_read_b128 v[184:187], v158 offset:16384
	ds_read_b128 v[188:191], v158 offset:17408
	ds_read_b128 v[192:195], v158 offset:18432
	ds_read_b128 v[196:199], v158 offset:19456
	ds_read_b128 v[200:203], v158 offset:20480
	ds_read_b128 v[204:207], v158 offset:21504
	ds_read_b128 v[208:211], v158 offset:22528
	ds_read_b128 v[212:215], v158 offset:23552
	global_load_lds_dwordx4 v[216:217], off
	s_add_i32 m0, s33, 0x2000
	s_add_u32 s84, s30, 0x80000
	v_lshl_add_u64 v[218:219], s[30:31], 0, v[130:131]
	s_addc_u32 s85, s31, 0
	s_add_i32 s33, s61, s44
	global_load_lds_dwordx4 v[218:219], off
	s_mov_b32 m0, s33
	v_lshl_add_u64 v[220:221], s[84:85], 0, v[134:135]
	global_load_lds_dwordx4 v[220:221], off
	s_add_i32 m0, s33, 0x2000
	v_lshl_add_u64 v[220:221], s[84:85], 0, v[130:131]
	global_load_lds_dwordx4 v[220:221], off
	s_waitcnt vmcnt(6) lgkmcnt(0)
	s_barrier
; #define PG8_STAGE(bufoff, gbase, voff) do { _Pragma("unroll") for (int _i = 0; _i < 2; ++_i) \
;         __builtin_amdgcn_global_load_lds((const unsigned*)((const char*)(gbase) + (voff)[_i]), (PG8_LAS unsigned*)(lds + (bufoff) + ldsw + _i * 8192), 16, 0, 0); } while (0)
; #define PG8_LDA(dst, b, h) do { _Pragma("unroll") for (int m = 0; m < 4; ++m) _Pragma("unroll") for (int k = 0; k < 2; ++k) dst[m][k] = *(const PG8_LAS bf16x8*)(lds + PG8_SA(b, h) + aoff + m * 2048 + k * 1024); } while (0)
; #define PG8_LDB(dst, b, h) do { _Pragma("unroll") for (int n = 0; n < 2; ++n) _Pragma("unroll") for (int k = 0; k < 2; ++k) dst[n][k] = *(const PG8_LAS bf16x8*)(lds + PG8_SB(b, h) + boff + n * 2048 + k * 1024); } while (0)
; #define PG8_MMA(ai, bj, At, Bt) do { __builtin_amdgcn_s_setprio(1); _Pragma("unroll") for (int m = 0; m < 4; ++m) _Pragma("unroll") for (int n = 0; n < 2; ++n) _Pragma("unroll") for (int k = 0; k < 2; ++k) \
;         acc[ai][bj][m][n] = __builtin_amdgcn_mfma_f32_16x16x32_bf16(Bt[n][k], At[m][k], acc[ai][bj][m][n], 0, 0, 0); __builtin_amdgcn_s_setprio(0); } while (0)
; #define PG8_WAIT_V(n) asm volatile("s_waitcnt vmcnt(" #n ")" ::: "memory")
; #define PG8_WAIT_L(n) asm volatile("s_waitcnt lgkmcnt(" #n ")" ::: "memory")
; #define PG8_BAR __builtin_amdgcn_s_barrier()
; #define PG8_SCHED __builtin_amdgcn_sched_barrier(0)
; template <class Epi, class Sched, bool ALIGN_EPI = false, bool SP2 = false, bool KSEG = false>
; __device__ __forceinline__ void gemm_phase(PG8_LAS unsigned char* lds, const Gemm g, const Sched& S, const Epi& E) {
;     ...
;             PG8_WAIT_V(8); PG8_WAIT_L(0); PG8_BAR; PG8_MMA(0, 0, At, B0); PG8_MMA(0, 1, At, B1); PG8_BAR; PG8_SCHED;
;             PG8_LDA(At, 0, 1); PG8_STAGE(PG8_SB(0, 0), b2, voffB); PG8_STAGE(PG8_SB(0, 1), b2 + hstep, voffB); PG8_STAGE(PG8_SA(0, 0), a2, voffA);
;             PG8_WAIT_V(8); PG8_WAIT_L(0); PG8_BAR; PG8_MMA(1, 0, At, B0); PG8_MMA(1, 1, At, B1); PG8_BAR; PG8_SCHED;
;             PG8_LDB(B0, 1, 0); PG8_LDB(B1, 1, 1); PG8_SCHED; PG8_LDA(At, 1, 0); PG8_STAGE(PG8_SA(0, 1), a2 + hstep, voffA);
;             PG8_WAIT_V(8); PG8_WAIT_L(0); PG8_BAR; PG8_MMA(0, 0, At, B0); PG8_MMA(0, 1, At, B1); PG8_BAR; PG8_SCHED;
;             PG8_LDA(At, 1, 1); PG8_STAGE(PG8_SB(1, 0), b3, voffB); PG8_STAGE(PG8_SB(1, 1), b3 + hstep, voffB); PG8_STAGE(PG8_SA(1, 0), a3, voffA);
	s_setprio 1
	v_mfma_f32_16x16x32_bf16 v[62:65], v[146:149], v[184:187], v[62:65]
	v_mfma_f32_16x16x32_bf16 v[58:61], v[160:163], v[184:187], v[58:61]
	v_mfma_f32_16x16x32_bf16 v[46:49], v[146:149], v[192:195], v[46:49]
	v_mfma_f32_16x16x32_bf16 v[42:45], v[160:163], v[192:195], v[42:45]
	v_mfma_f32_16x16x32_bf16 v[30:33], v[146:149], v[200:203], v[30:33]
	v_mfma_f32_16x16x32_bf16 v[26:29], v[160:163], v[200:203], v[26:29]
	v_mfma_f32_16x16x32_bf16 v[14:17], v[146:149], v[208:211], v[14:17]
	v_mfma_f32_16x16x32_bf16 v[10:13], v[160:163], v[208:211], v[10:13]
	v_mfma_f32_16x16x32_bf16 v[62:65], v[150:153], v[188:191], v[62:65]
	v_mfma_f32_16x16x32_bf16 v[58:61], v[164:167], v[188:191], v[58:61]
	v_mfma_f32_16x16x32_bf16 v[46:49], v[150:153], v[196:199], v[46:49]
	v_mfma_f32_16x16x32_bf16 v[42:45], v[164:167], v[196:199], v[42:45]
	v_mfma_f32_16x16x32_bf16 v[30:33], v[150:153], v[204:207], v[30:33]
	v_mfma_f32_16x16x32_bf16 v[26:29], v[164:167], v[204:207], v[26:29]
	v_mfma_f32_16x16x32_bf16 v[14:17], v[150:153], v[212:215], v[14:17]
	v_mfma_f32_16x16x32_bf16 v[10:13], v[164:167], v[212:215], v[10:13]
	s_setprio 0
	s_setprio 1
	v_mfma_f32_16x16x32_bf16 v[54:57], v[168:171], v[184:187], v[54:57]
	v_mfma_f32_16x16x32_bf16 v[50:53], v[176:179], v[184:187], v[50:53]
	v_mfma_f32_16x16x32_bf16 v[38:41], v[168:171], v[192:195], v[38:41]
	v_mfma_f32_16x16x32_bf16 v[34:37], v[176:179], v[192:195], v[34:37]
	v_mfma_f32_16x16x32_bf16 v[22:25], v[168:171], v[200:203], v[22:25]
	v_mfma_f32_16x16x32_bf16 v[18:21], v[176:179], v[200:203], v[18:21]
	v_mfma_f32_16x16x32_bf16 v[6:9], v[168:171], v[208:211], v[6:9]
	v_mfma_f32_16x16x32_bf16 v[2:5], v[176:179], v[208:211], v[2:5]
	v_mfma_f32_16x16x32_bf16 v[54:57], v[172:175], v[188:191], v[54:57]
	v_mfma_f32_16x16x32_bf16 v[50:53], v[180:183], v[188:191], v[50:53]
	v_mfma_f32_16x16x32_bf16 v[38:41], v[172:175], v[196:199], v[38:41]
	v_mfma_f32_16x16x32_bf16 v[34:37], v[180:183], v[196:199], v[34:37]
	v_mfma_f32_16x16x32_bf16 v[22:25], v[172:175], v[204:207], v[22:25]
	v_mfma_f32_16x16x32_bf16 v[18:21], v[180:183], v[204:207], v[18:21]
	v_mfma_f32_16x16x32_bf16 v[6:9], v[172:175], v[212:215], v[6:9]
	v_mfma_f32_16x16x32_bf16 v[2:5], v[180:183], v[212:215], v[2:5]
	s_setprio 0
	s_barrier
	s_add_i32 s33, 0, 0x18000
	v_add_u32_e32 v159, s33, v154
	s_add_i32 s81, 0, 0x1c000
	ds_read_b128 v[146:149], v159
	ds_read_b128 v[150:153], v159 offset:1024
	ds_read_b128 v[160:163], v159 offset:2048
	ds_read_b128 v[164:167], v159 offset:3072
	v_add_u32_e32 v159, s81, v154
	ds_read_b128 v[168:171], v159
	ds_read_b128 v[172:175], v159 offset:1024
	ds_read_b128 v[176:179], v159 offset:2048
	ds_read_b128 v[180:183], v159 offset:3072
	s_mov_b32 m0, s27
	v_lshl_add_u64 v[224:225], s[42:43], 0, v[136:137]
	global_load_lds_dwordx4 v[224:225], off
	s_mov_b32 m0, s47
	v_lshl_add_u64 v[224:225], s[42:43], 0, v[132:133]
	global_load_lds_dwordx4 v[224:225], off
	s_add_u32 s42, s42, 0x80000
	s_addc_u32 s43, s43, 0
	s_mov_b32 m0, s48
	v_lshl_add_u64 v[224:225], s[42:43], 0, v[136:137]
	ds_read_b128 v[184:187], v158 offset:32768
	ds_read_b128 v[188:191], v158 offset:33792
	ds_read_b128 v[192:195], v158 offset:34816
	ds_read_b128 v[196:199], v158 offset:35840
	ds_read_b128 v[200:203], v158 offset:36864
	ds_read_b128 v[204:207], v158 offset:37888
	ds_read_b128 v[208:211], v158 offset:38912
	ds_read_b128 v[212:215], v158 offset:39936
	global_load_lds_dwordx4 v[224:225], off
	s_mov_b32 m0, s49
	v_lshl_add_u64 v[224:225], s[42:43], 0, v[132:133]
	global_load_lds_dwordx4 v[224:225], off
	s_waitcnt vmcnt(8) lgkmcnt(0)
	s_barrier
; #define PG8_STAGE(bufoff, gbase, voff) do { _Pragma("unroll") for (int _i = 0; _i < 2; ++_i) \
;         __builtin_amdgcn_global_load_lds((const unsigned*)((const char*)(gbase) + (voff)[_i]), (PG8_LAS unsigned*)(lds + (bufoff) + ldsw + _i * 8192), 16, 0, 0); } while (0)
; #define PG8_LDA(dst, b, h) do { _Pragma("unroll") for (int m = 0; m < 4; ++m) _Pragma("unroll") for (int k = 0; k < 2; ++k) dst[m][k] = *(const PG8_LAS bf16x8*)(lds + PG8_SA(b, h) + aoff + m * 2048 + k * 1024); } while (0)
; #define PG8_LDB(dst, b, h) do { _Pragma("unroll") for (int n = 0; n < 2; ++n) _Pragma("unroll") for (int k = 0; k < 2; ++k) dst[n][k] = *(const PG8_LAS bf16x8*)(lds + PG8_SB(b, h) + boff + n * 2048 + k * 1024); } while (0)
; #define PG8_MMA(ai, bj, At, Bt) do { __builtin_amdgcn_s_setprio(1); _Pragma("unroll") for (int m = 0; m < 4; ++m) _Pragma("unroll") for (int n = 0; n < 2; ++n) _Pragma("unroll") for (int k = 0; k < 2; ++k) \
;         acc[ai][bj][m][n] = __builtin_amdgcn_mfma_f32_16x16x32_bf16(Bt[n][k], At[m][k], acc[ai][bj][m][n], 0, 0, 0); __builtin_amdgcn_s_setprio(0); } while (0)
; #define PG8_WAIT_V(n) asm volatile("s_waitcnt vmcnt(" #n ")" ::: "memory")
; #define PG8_WAIT_L(n) asm volatile("s_waitcnt lgkmcnt(" #n ")" ::: "memory")
; #define PG8_BAR __builtin_amdgcn_s_barrier()
; #define PG8_SCHED __builtin_amdgcn_sched_barrier(0)
; template <class Epi, class Sched, bool ALIGN_EPI = false, bool SP2 = false, bool KSEG = false>
; __device__ __forceinline__ void gemm_phase(PG8_LAS unsigned char* lds, const Gemm g, const Sched& S, const Epi& E) {
;     ...
;             PG8_WAIT_V(8); PG8_WAIT_L(0); PG8_BAR; PG8_MMA(1, 0, At, B0); PG8_MMA(1, 1, At, B1); PG8_BAR; PG8_SCHED;
;             PG8_LDB(B0, 1, 0); PG8_LDB(B1, 1, 1); PG8_SCHED; PG8_LDA(At, 1, 0); PG8_STAGE(PG8_SA(0, 1), a2 + hstep, voffA);
;             PG8_WAIT_V(8); PG8_WAIT_L(0); PG8_BAR; PG8_MMA(0, 0, At, B0); PG8_MMA(0, 1, At, B1); PG8_BAR; PG8_SCHED;
;             PG8_LDA(At, 1, 1); PG8_STAGE(PG8_SB(1, 0), b3, voffB); PG8_STAGE(PG8_SB(1, 1), b3 + hstep, voffB); PG8_STAGE(PG8_SA(1, 0), a3, voffA);
;             PG8_WAIT_V(8); PG8_WAIT_L(0); PG8_BAR; PG8_MMA(1, 0, At, B0); PG8_MMA(1, 1, At, B1); PG8_BAR; PG8_SCHED;
;     ...
;             if constexpr (KSEG) { if (t == 14 || t == 22) E.kscale(acc, ui, t == 14 ? 0 : 1, wr, fr); }
;         }
;         if constexpr (ALIGN_EPI) { if (wr == 0) PG8_BAR; }
	s_setprio 1
	v_mfma_f32_16x16x32_bf16 v[126:129], v[146:149], v[184:187], v[126:129]
	v_mfma_f32_16x16x32_bf16 v[122:125], v[160:163], v[184:187], v[122:125]
	v_mfma_f32_16x16x32_bf16 v[110:113], v[146:149], v[192:195], v[110:113]
	v_mfma_f32_16x16x32_bf16 v[106:109], v[160:163], v[192:195], v[106:109]
	v_mfma_f32_16x16x32_bf16 v[94:97], v[146:149], v[200:203], v[94:97]
	v_mfma_f32_16x16x32_bf16 v[90:93], v[160:163], v[200:203], v[90:93]
	v_mfma_f32_16x16x32_bf16 v[78:81], v[146:149], v[208:211], v[78:81]
	v_mfma_f32_16x16x32_bf16 v[74:77], v[160:163], v[208:211], v[74:77]
	v_mfma_f32_16x16x32_bf16 v[126:129], v[150:153], v[188:191], v[126:129]
	v_mfma_f32_16x16x32_bf16 v[122:125], v[164:167], v[188:191], v[122:125]
	v_mfma_f32_16x16x32_bf16 v[110:113], v[150:153], v[196:199], v[110:113]
	v_mfma_f32_16x16x32_bf16 v[106:109], v[164:167], v[196:199], v[106:109]
	v_mfma_f32_16x16x32_bf16 v[94:97], v[150:153], v[204:207], v[94:97]
	v_mfma_f32_16x16x32_bf16 v[90:93], v[164:167], v[204:207], v[90:93]
	v_mfma_f32_16x16x32_bf16 v[78:81], v[150:153], v[212:215], v[78:81]
	v_mfma_f32_16x16x32_bf16 v[74:77], v[164:167], v[212:215], v[74:77]
	s_setprio 0
	s_setprio 1
	v_mfma_f32_16x16x32_bf16 v[118:121], v[168:171], v[184:187], v[118:121]
	v_mfma_f32_16x16x32_bf16 v[114:117], v[176:179], v[184:187], v[114:117]
	v_mfma_f32_16x16x32_bf16 v[102:105], v[168:171], v[192:195], v[102:105]
	v_mfma_f32_16x16x32_bf16 v[98:101], v[176:179], v[192:195], v[98:101]
	v_mfma_f32_16x16x32_bf16 v[86:89], v[168:171], v[200:203], v[86:89]
	v_mfma_f32_16x16x32_bf16 v[82:85], v[176:179], v[200:203], v[82:85]
	v_mfma_f32_16x16x32_bf16 v[70:73], v[168:171], v[208:211], v[70:73]
	v_mfma_f32_16x16x32_bf16 v[66:69], v[176:179], v[208:211], v[66:69]
	v_mfma_f32_16x16x32_bf16 v[118:121], v[172:175], v[188:191], v[118:121]
	v_mfma_f32_16x16x32_bf16 v[114:117], v[180:183], v[188:191], v[114:117]
	v_mfma_f32_16x16x32_bf16 v[102:105], v[172:175], v[196:199], v[102:105]
	v_mfma_f32_16x16x32_bf16 v[98:101], v[180:183], v[196:199], v[98:101]
	v_mfma_f32_16x16x32_bf16 v[86:89], v[172:175], v[204:207], v[86:89]
	v_mfma_f32_16x16x32_bf16 v[82:85], v[180:183], v[204:207], v[82:85]
	v_mfma_f32_16x16x32_bf16 v[70:73], v[172:175], v[212:215], v[70:73]
	v_mfma_f32_16x16x32_bf16 v[66:69], v[180:183], v[212:215], v[66:69]
	s_setprio 0
	s_barrier
	s_add_i32 s33, s33, s44
	v_lshl_add_u64 v[216:217], v[216:217], 0, s[12:13]
	s_mov_b32 m0, s33
	ds_read_b128 v[184:187], v158 offset:49152
	ds_read_b128 v[188:191], v158 offset:50176
	ds_read_b128 v[192:195], v158 offset:51200
	ds_read_b128 v[196:199], v158 offset:52224
	ds_read_b128 v[200:203], v158 offset:53248
	ds_read_b128 v[204:207], v158 offset:54272
	ds_read_b128 v[208:211], v158 offset:55296
	ds_read_b128 v[212:215], v158 offset:56320
	global_load_lds_dwordx4 v[216:217], off
	s_add_i32 m0, s33, 0x2000
	s_add_u32 s30, s30, 0x80080
	v_lshl_add_u64 v[216:217], v[218:219], 0, s[12:13]
	s_addc_u32 s31, s31, 0
	s_add_i32 s33, s81, s44
	global_load_lds_dwordx4 v[216:217], off
	s_mov_b32 m0, s33
	v_lshl_add_u64 v[216:217], s[30:31], 0, v[134:135]
	global_load_lds_dwordx4 v[216:217], off
	s_add_i32 m0, s33, 0x2000
	v_lshl_add_u64 v[216:217], s[30:31], 0, v[130:131]
	global_load_lds_dwordx4 v[216:217], off
	s_waitcnt vmcnt(6) lgkmcnt(0)
	s_barrier
	s_setprio 1
	v_mfma_f32_16x16x32_bf16 v[62:65], v[146:149], v[184:187], v[62:65]
	v_mfma_f32_16x16x32_bf16 v[58:61], v[160:163], v[184:187], v[58:61]
	v_mfma_f32_16x16x32_bf16 v[46:49], v[146:149], v[192:195], v[46:49]
	v_mfma_f32_16x16x32_bf16 v[42:45], v[160:163], v[192:195], v[42:45]
	v_mfma_f32_16x16x32_bf16 v[30:33], v[146:149], v[200:203], v[30:33]
	v_mfma_f32_16x16x32_bf16 v[26:29], v[160:163], v[200:203], v[26:29]
	v_mfma_f32_16x16x32_bf16 v[14:17], v[146:149], v[208:211], v[14:17]
	v_mfma_f32_16x16x32_bf16 v[10:13], v[160:163], v[208:211], v[10:13]
	v_mfma_f32_16x16x32_bf16 v[62:65], v[150:153], v[188:191], v[62:65]
	v_mfma_f32_16x16x32_bf16 v[58:61], v[164:167], v[188:191], v[58:61]
	v_mfma_f32_16x16x32_bf16 v[46:49], v[150:153], v[196:199], v[46:49]
	v_mfma_f32_16x16x32_bf16 v[42:45], v[164:167], v[196:199], v[42:45]
	v_mfma_f32_16x16x32_bf16 v[30:33], v[150:153], v[204:207], v[30:33]
	v_mfma_f32_16x16x32_bf16 v[26:29], v[164:167], v[204:207], v[26:29]
	v_mfma_f32_16x16x32_bf16 v[14:17], v[150:153], v[212:215], v[14:17]
	v_mfma_f32_16x16x32_bf16 v[10:13], v[164:167], v[212:215], v[10:13]
	s_setprio 0
	s_setprio 1
	v_mfma_f32_16x16x32_bf16 v[54:57], v[168:171], v[184:187], v[54:57]
	v_mfma_f32_16x16x32_bf16 v[50:53], v[176:179], v[184:187], v[50:53]
	v_mfma_f32_16x16x32_bf16 v[38:41], v[168:171], v[192:195], v[38:41]
	v_mfma_f32_16x16x32_bf16 v[34:37], v[176:179], v[192:195], v[34:37]
	v_mfma_f32_16x16x32_bf16 v[22:25], v[168:171], v[200:203], v[22:25]
	v_mfma_f32_16x16x32_bf16 v[18:21], v[176:179], v[200:203], v[18:21]
	v_mfma_f32_16x16x32_bf16 v[6:9], v[168:171], v[208:211], v[6:9]
	v_mfma_f32_16x16x32_bf16 v[2:5], v[176:179], v[208:211], v[2:5]
	v_mfma_f32_16x16x32_bf16 v[54:57], v[172:175], v[188:191], v[54:57]
	v_mfma_f32_16x16x32_bf16 v[50:53], v[180:183], v[188:191], v[50:53]
	v_mfma_f32_16x16x32_bf16 v[38:41], v[172:175], v[196:199], v[38:41]
	v_mfma_f32_16x16x32_bf16 v[34:37], v[180:183], v[196:199], v[34:37]
	v_mfma_f32_16x16x32_bf16 v[22:25], v[172:175], v[204:207], v[22:25]
	v_mfma_f32_16x16x32_bf16 v[18:21], v[180:183], v[204:207], v[18:21]
	v_mfma_f32_16x16x32_bf16 v[6:9], v[172:175], v[212:215], v[6:9]
	v_mfma_f32_16x16x32_bf16 v[2:5], v[180:183], v[212:215], v[2:5]
	s_setprio 0
	s_barrier
	s_add_i32 s80, s80, 2
	s_add_u32 s28, s28, 0x100
	s_addc_u32 s29, s29, 0
	s_add_u32 s66, s66, 0x100
	s_addc_u32 s67, s67, 0
	s_cmp_gt_u32 s80, 29
	s_cbranch_scc0 .LBB0_120
	s_and_b64 vcc, exec, s[16:17]
	s_cbranch_vccz .LBB0_123
	s_barrier

; __device__ __forceinline__ void finishSM(f32x16& p0, f32x16& p1, float alpha, float& l_reg, bf16x8& pa0, bf16x8& pa1, bf16x8& pa2, bf16x8& pa3) {
;   for (int r = 0; r < 16; ++r) p1[r] = __builtin_amdgcn_exp2f(p1[r]);
;   float ps = 0; for (int r = 0; r < 16; ++r) ps += p0[r]; for (int r = 0; r < 16; ++r) ps += p1[r];
;   { auto rr = __builtin_amdgcn_permlane32_swap(__float_as_uint(ps), __float_as_uint(ps), false, false);
;     ps = __uint_as_float(rr[0]) + __uint_as_float(rr[1]); }
;   l_reg = l_reg * alpha + ps;
;     ...
;   PK4(p0, 0, pa0); PK4(p0, 8, pa1); PK4(p1, 0, pa2); PK4(p1, 8, pa3);
;     ...
; }
; __device__ __forceinline__ void qkt(f32x16& p0, f32x16& p1, const bf16* Ks, const bf16x8* qr, int r32, int hi) {
;   p0 = f32x16{}; p1 = f32x16{};
;   for (int d0 = 0; d0 < 8; ++d0) { int cb = (d0 * 16 + hi * 8) * 2;
;     bf16x8 b0 = *reinterpret_cast<const bf16x8*>((const char*)Ks + KSWZ(r32, cb));
;     bf16x8 b1 = *reinterpret_cast<const bf16x8*>((const char*)Ks + KSWZ(32 + r32, cb));
;     p0 = __builtin_amdgcn_mfma_f32_32x32x16_bf16(b0, qr[d0], p0, 0, 0, 0);
;     p1 = __builtin_amdgcn_mfma_f32_32x32x16_bf16(b1, qr[d0], p1, 0, 0, 0); }
.LBB0_171:
	ds_read_b128 v[98:101], v218 offset:49152
	ds_read_b128 v[102:105], v218 offset:57344
	ds_read_b128 v[178:181], v223 offset:49152
	ds_read_b128 v[182:185], v223 offset:57344
	ds_read_b128 v[186:189], v227 offset:49152
	ds_read_b128 v[190:193], v227 offset:57344
	v_exp_f32_e32 v82, v82
	v_exp_f32_e32 v83, v83
	s_waitcnt lgkmcnt(5)
	v_mfma_f32_32x32x16_bf16 v[114:129], v[98:101], v[134:137], 0
	v_exp_f32_e32 v84, v84
	v_exp_f32_e32 v85, v85
	v_exp_f32_e32 v86, v86
	v_exp_f32_e32 v87, v87
	v_exp_f32_e32 v88, v88
	v_exp_f32_e32 v89, v89
	v_exp_f32_e32 v90, v90
	s_waitcnt lgkmcnt(4)
	v_mfma_f32_32x32x16_bf16 v[98:113], v[102:105], v[134:137], 0
	v_exp_f32_e32 v91, v91
	v_exp_f32_e32 v92, v92
	v_exp_f32_e32 v93, v93
	v_exp_f32_e32 v94, v94
	v_exp_f32_e32 v95, v95
	v_exp_f32_e32 v96, v96
	v_exp_f32_e32 v97, v97
	s_waitcnt lgkmcnt(2)
	v_mfma_f32_32x32x16_bf16 v[98:113], v[182:185], v[142:145], v[98:113]
	v_mfma_f32_32x32x16_bf16 v[114:129], v[178:181], v[142:145], v[114:129]
	ds_read_b128 v[178:181], v228 offset:49152
	ds_read_b128 v[194:197], v228 offset:57344
	ds_read_b128 v[198:201], v229 offset:49152
	ds_read_b128 v[202:205], v229 offset:57344
	ds_read_b128 v[206:209], v231 offset:49152
	ds_read_b128 v[238:241], v231 offset:57344
	ds_read_b128 v[242:245], v230 offset:49152
	ds_read_b128 v[246:249], v230 offset:57344
	ds_read_b128 v[182:185], v232 offset:49152
	ds_read_b128 v[250:253], v232 offset:57344
	s_waitcnt lgkmcnt(10)
	v_mfma_f32_32x32x16_bf16 v[98:113], v[190:193], v[130:133], v[98:113]
	v_mfma_f32_32x32x16_bf16 v[114:129], v[186:189], v[130:133], v[114:129]
	v_add_f32_e32 v186, 0, v66
	v_add_f32_e32 v186, v67, v186
	v_add_f32_e32 v186, v68, v186
	s_waitcnt lgkmcnt(8)
	v_mfma_f32_32x32x16_bf16 v[98:113], v[194:197], v[138:141], v[98:113]
	v_cvt_pk_bf16_f32 v194, v66, v67
	v_cvt_pk_bf16_f32 v195, v68, v69
	v_cvt_pk_bf16_f32 v196, v70, v71
	v_cvt_pk_bf16_f32 v197, v72, v73
	s_nop 0
	v_permlane32_swap_b32_e32 v194, v196
	v_mfma_f32_32x32x16_bf16 v[114:129], v[178:181], v[138:141], v[114:129]
	v_add_f32_e32 v178, v69, v186
	v_add_f32_e32 v178, v70, v178
	v_add_f32_e32 v178, v71, v178
	v_add_f32_e32 v178, v72, v178
	v_add_f32_e32 v178, v73, v178
	v_add_f32_e32 v178, v74, v178
	v_add_f32_e32 v178, v75, v178
	s_waitcnt lgkmcnt(6)
	v_mfma_f32_32x32x16_bf16 v[98:113], v[202:205], v[150:153], v[98:113]
	v_add_f32_e32 v178, v76, v178
	v_add_f32_e32 v178, v77, v178
	v_add_f32_e32 v178, v78, v178
	v_add_f32_e32 v178, v79, v178
	v_add_f32_e32 v178, v80, v178
	v_add_f32_e32 v178, v81, v178
	v_add_f32_e32 v178, v82, v178
	v_mfma_f32_32x32x16_bf16 v[114:129], v[198:201], v[150:153], v[114:129]
	v_add_f32_e32 v178, v83, v178
	v_add_f32_e32 v178, v84, v178
	v_add_f32_e32 v178, v85, v178
	v_add_f32_e32 v178, v86, v178
	v_add_f32_e32 v178, v87, v178
	v_add_f32_e32 v178, v88, v178
	v_add_f32_e32 v178, v89, v178
	s_waitcnt lgkmcnt(4)
	v_mfma_f32_32x32x16_bf16 v[98:113], v[238:241], v[158:161], v[98:113]
	v_add_f32_e32 v178, v90, v178
	v_add_f32_e32 v178, v91, v178
	v_add_f32_e32 v178, v92, v178
	v_add_f32_e32 v178, v93, v178
	v_add_f32_e32 v178, v94, v178
	v_add_f32_e32 v178, v95, v178
	v_add_f32_e32 v178, v96, v178
	v_mfma_f32_32x32x16_bf16 v[114:129], v[206:209], v[158:161], v[114:129]
	v_add_f32_e32 v233, v97, v178
	v_mov_b32_e32 v235, v233
	s_nop 1
	v_permlane32_swap_b32_e32 v233, v235
	v_cvt_pk_bf16_f32 v198, v74, v75
	v_cvt_pk_bf16_f32 v199, v76, v77
	v_cvt_pk_bf16_f32 v200, v78, v79
	s_waitcnt lgkmcnt(2)
	v_mfma_f32_32x32x16_bf16 v[98:113], v[246:249], v[146:149], v[98:113]
	v_cvt_pk_bf16_f32 v201, v80, v81
	v_cvt_pk_bf16_f32 v206, v82, v83
	v_cvt_pk_bf16_f32 v207, v84, v85
	v_cvt_pk_bf16_f32 v208, v86, v87
	v_cvt_pk_bf16_f32 v209, v88, v89
	v_cvt_pk_bf16_f32 v202, v90, v91
	v_cvt_pk_bf16_f32 v203, v92, v93
	v_mfma_f32_32x32x16_bf16 v[114:129], v[242:245], v[146:149], v[114:129]
	v_cvt_pk_bf16_f32 v204, v94, v95
	v_cvt_pk_bf16_f32 v205, v96, v97
	v_permlane32_swap_b32_e32 v195, v197
	v_permlane32_swap_b32_e32 v198, v200
	v_permlane32_swap_b32_e32 v199, v201
	s_waitcnt lgkmcnt(0)
	v_mfma_f32_32x32x16_bf16 v[98:113], v[250:253], v[154:157], v[98:113]
	v_permlane32_swap_b32_e32 v206, v208
	v_permlane32_swap_b32_e32 v207, v209
	v_permlane32_swap_b32_e32 v202, v204
	v_permlane32_swap_b32_e32 v203, v205
	v_mfma_f32_32x32x16_bf16 v[114:129], v[182:185], v[154:157], v[114:129]
	v_add_co_u32_e32 v66, vcc, s67, v212
	s_nop 1
	v_addc_co_u32_e32 v67, vcc, -1, v213, vcc
	v_add_co_u32_e32 v68, vcc, s80, v212
	s_nop 1
	v_addc_co_u32_e32 v69, vcc, -1, v213, vcc
	global_load_dwordx4 v[178:181], v[66:67], off
	global_load_dwordx4 v[182:185], v[66:67], off offset:-512
	global_load_dwordx4 v[190:193], v[68:69], off
	global_load_dwordx4 v[186:189], v[68:69], off offset:-512
	ds_read_b64_tr_b16 v[66:67], v217 offset:0
	ds_read_b64_tr_b16 v[68:69], v217 offset:0x800
	ds_read_b64_tr_b16 v[70:71], v217 offset:0x1000
	ds_read_b64_tr_b16 v[72:73], v217 offset:0x1800
	ds_read_b64_tr_b16 v[74:75], v217 offset:0x2000
	ds_read_b64_tr_b16 v[76:77], v217 offset:0x2800
	ds_read_b64_tr_b16 v[78:79], v217 offset:0x3000
	ds_read_b64_tr_b16 v[80:81], v217 offset:0x3800
	s_waitcnt lgkmcnt(0)
	s_nop 0
	v_mfma_f32_32x32x16_bf16 v[50:65], v[194:197], v[66:69], v[50:65]
	v_max_f32_e32 v66, v114, v115
	v_max3_f32 v66, v66, v116, v117
	v_max3_f32 v66, v66, v118, v119
	v_max3_f32 v66, v66, v120, v121
	v_max3_f32 v66, v66, v122, v123
	v_mfma_f32_32x32x16_bf16 v[50:65], v[198:201], v[70:73], v[50:65]
	v_max3_f32 v66, v66, v124, v125
	v_max3_f32 v68, v66, v126, v127
	ds_read_b64_tr_b16 v[66:67], v217 offset:0x200
	v_max3_f32 v86, v68, v128, v129
	ds_read_b64_tr_b16 v[68:69], v217 offset:0xa00
	ds_read_b64_tr_b16 v[70:71], v217 offset:0x1200
	ds_read_b64_tr_b16 v[72:73], v217 offset:0x1a00
	v_mfma_f32_32x32x16_bf16 v[50:65], v[206:209], v[74:77], v[50:65]
	ds_read_b64_tr_b16 v[74:75], v217 offset:0x2200
	ds_read_b64_tr_b16 v[76:77], v217 offset:0x2a00
	ds_read_b64_tr_b16 v[82:83], v217 offset:0x3200
	ds_read_b64_tr_b16 v[84:85], v217 offset:0x3a00
	s_waitcnt lgkmcnt(0)
; #define SBAR() __builtin_amdgcn_sched_barrier(0)
; #define SLOAD(i, k0) do { const long to_ = (long)(k0) * ldk * 2; const char* vt_ = (const char*)Vh + to_; const char* kt_ = (const char*)Kh + to_; \
;     sr_[i].vs0 = *(const bf16x8*)(vt_ + toff); sr_[i].vs1 = *(const bf16x8*)(vt_ + h32 + toff); \
;     sr_[i].ks0 = *(const bf16x8*)(kt_ + toff); sr_[i].ks1 = *(const bf16x8*)(kt_ + h32 + toff); } while (0)
; #define SWAIT() do { if constexpr (SDEPTH == 2) asm volatile("s_waitcnt vmcnt(4)" ::: "memory"); else asm volatile("s_waitcnt vmcnt(0)" ::: "memory"); } while (0)
; __device__ __forceinline__ void psm_decide(float pmax, const f32x16& p1, float& m_reg, float& mn, float& alpha) {
;   constexpr float C = SCALE * 1.4426950408889634f;
;   for (int r = 0; r < 16; ++r) pmax = fmaxf(pmax, p1[r]);
;   { auto rr = __builtin_amdgcn_permlane32_swap(__float_as_uint(pmax), __float_as_uint(pmax), false, false);
;     pmax = fmaxf(__uint_as_float(rr[0]), __uint_as_float(rr[1])); }
;   if (__builtin_expect(__all(pmax - m_reg <= THR / SCALE), 1)) { mn = m_reg; alpha = 1.f; }
;   else { mn = fmaxf(m_reg, pmax); alpha = __builtin_amdgcn_exp2f((m_reg - mn) * C); m_reg = mn; }
; }
; __device__ __forceinline__ void psm_scale(f32x16& p0, f32x16& p1, float mn) {
;   constexpr float C = SCALE * 1.4426950408889634f; const float mnC = -mn * C;
;   for (int r = 0; r < 16; ++r) p0[r] = fmaf(p0[r], C, mnC); for (int r = 0; r < 16; ++r) p1[r] = fmaf(p1[r], C, mnC);
; }
; template <int MODE, int QMODE> ...
;     ...
;   if (wid >= 4) __builtin_amdgcn_s_setprio(1);
;   f32x16 pA0, pA1, pB0, pB1; float mnA, mnB, alA, alB; bf16x8 pa0, pa1, pa2, pa3; const int NT = seq / KVBLK;
;   constexpr int SE = 0, SO = SDEPTH - 1;
;   SLOAD(SE, 0); asm volatile("s_waitcnt vmcnt(0)" ::: "memory"); SWRITE(0, SE); __syncthreads();
;   qkt(pA0, pA1, K_lds, qr, r32, hi); MASK(pA0, pA1, 0); partialSM(pA0, pA1, m_reg, mnA, alA);
;   SLOAD(SO, KVBLK); if constexpr (SDEPTH == 2) { if (2 < NT) SLOAD(SE, 2 * KVBLK); }
;   SWAIT(); SWRITE(1, SO); __syncthreads();
;   for (int j = 1; j + 1 < NT; j += 2) {
;     SBAR(); qkt(pB0, pB1, (bf16*)((char*)K_lds + SHM_K), qr, r32, hi);
;     finishSM(pA0, pA1, alA, l_reg, pa0, pa1, pa2, pa3); SBAR();
;     SLOAD(SO, (j + SDEPTH) * KVBLK); SBAR();
;     PVSM(vb0, pB0, pB1, j * KVBLK, mnB, alB);
;     __syncthreads(); SWAIT(); SWRITE(0, SE);
;     RESC(alB); __syncthreads();
	v_mfma_f32_32x32x16_bf16 v[50:65], v[202:205], v[78:81], v[50:65]
	v_mfma_f32_32x32x16_bf16 v[34:49], v[194:197], v[66:69], v[34:49]
	v_max3_f32 v78, v86, v98, v99
	v_max3_f32 v78, v78, v100, v101
	v_max3_f32 v78, v78, v102, v103
	v_max3_f32 v78, v78, v104, v105
	v_max3_f32 v78, v78, v106, v107
	v_max3_f32 v78, v78, v108, v109
	v_max3_f32 v66, v78, v110, v111
	v_max3_f32 v66, v66, v112, v113
	v_mfma_f32_32x32x16_bf16 v[34:49], v[198:201], v[70:73], v[34:49]
	v_mov_b32_e32 v67, v66
	s_nop 1
	v_permlane32_swap_b32_e32 v66, v67
	v_max_f32_e32 v66, v66, v67
	v_sub_f32_e32 v67, v66, v237
	v_cmp_ge_f32_e32 vcc, s62, v67
	v_max_f32_e32 v66, v237, v66
	v_sub_f32_e32 v67, v237, v66
	v_mfma_f32_32x32x16_bf16 v[34:49], v[206:209], v[74:77], v[34:49]
	v_mul_f32_e32 v67, 0x3e0293ee, v67
	v_exp_f32_e32 v67, v67
	s_cmp_eq_u64 vcc, exec
	s_cselect_b64 vcc, -1, 0
	v_cndmask_b32_e32 v236, v66, v237, vcc
	v_cndmask_b32_e64 v238, v67, 1.0, vcc
	ds_read_b64_tr_b16 v[66:67], v217 offset:0x400
	ds_read_b64_tr_b16 v[68:69], v217 offset:0xc00
	v_mfma_f32_32x32x16_bf16 v[34:49], v[202:205], v[82:85], v[34:49]
	ds_read_b64_tr_b16 v[82:83], v217 offset:0x1400
	ds_read_b64_tr_b16 v[84:85], v217 offset:0x1c00
	ds_read_b64_tr_b16 v[240:241], v217 offset:0x2400
	ds_read_b64_tr_b16 v[242:243], v217 offset:0x2c00
	ds_read_b64_tr_b16 v[244:245], v217 offset:0x3400
	ds_read_b64_tr_b16 v[246:247], v217 offset:0x3c00
	s_waitcnt lgkmcnt(0)
	v_mfma_f32_32x32x16_bf16 v[18:33], v[194:197], v[66:69], v[18:33]
	v_mul_f32_e32 v248, 0xbe0293ee, v236
	v_fma_f32 v80, v128, s12, v248
	v_fma_f32 v81, v129, s12, v248
	v_fma_f32 v78, v126, s12, v248
	v_fma_f32 v79, v127, s12, v248
	v_pk_fma_f32 v[76:77], v[124:125], s[12:13], v[248:249] op_sel_hi:[1,0,0]
	v_pk_fma_f32 v[74:75], v[122:123], s[12:13], v[248:249] op_sel_hi:[1,0,0]
	v_pk_fma_f32 v[72:73], v[120:121], s[12:13], v[248:249] op_sel_hi:[1,0,0]
	v_pk_fma_f32 v[70:71], v[118:119], s[12:13], v[248:249] op_sel_hi:[1,0,0]
	v_mfma_f32_32x32x16_bf16 v[18:33], v[198:201], v[82:85], v[18:33]
	v_fma_f32 v68, v116, s12, v248
	v_fma_f32 v69, v117, s12, v248
	v_fma_f32 v66, v114, s12, v248
	v_fma_f32 v67, v115, s12, v248
	v_fma_f32 v96, v112, s12, v248
	v_fma_f32 v97, v113, s12, v248
	v_pk_fma_f32 v[94:95], v[110:111], s[12:13], v[248:249] op_sel_hi:[1,0,0]
	v_pk_fma_f32 v[92:93], v[108:109], s[12:13], v[248:249] op_sel_hi:[1,0,0]
	v_pk_fma_f32 v[90:91], v[106:107], s[12:13], v[248:249] op_sel_hi:[1,0,0]
	v_pk_fma_f32 v[88:89], v[104:105], s[12:13], v[248:249] op_sel_hi:[1,0,0]
	v_mfma_f32_32x32x16_bf16 v[18:33], v[206:209], v[240:243], v[18:33]
	v_fma_f32 v86, v102, s12, v248
	v_fma_f32 v87, v103, s12, v248
	v_fma_f32 v84, v100, s12, v248
	v_fma_f32 v85, v101, s12, v248
	v_fma_f32 v82, v98, s12, v248
	v_fma_f32 v83, v99, s12, v248
	ds_read_b64_tr_b16 v[98:99], v217 offset:0x600
	ds_read_b64_tr_b16 v[100:101], v217 offset:0xe00
	ds_read_b64_tr_b16 v[102:103], v217 offset:0x1600
	ds_read_b64_tr_b16 v[104:105], v217 offset:0x1e00
	v_mfma_f32_32x32x16_bf16 v[18:33], v[202:205], v[244:247], v[18:33]
	ds_read_b64_tr_b16 v[108:109], v217 offset:0x2600
	ds_read_b64_tr_b16 v[110:111], v217 offset:0x2e00
	ds_read_b64_tr_b16 v[114:115], v217 offset:0x3600
	ds_read_b64_tr_b16 v[116:117], v217 offset:0x3e00
	s_waitcnt lgkmcnt(0)
	v_mfma_f32_32x32x16_bf16 v[2:17], v[194:197], v[98:101], v[2:17]
	v_exp_f32_e32 v98, v66
	v_exp_f32_e32 v99, v67
	v_exp_f32_e32 v100, v68
	v_exp_f32_e32 v101, v69
	v_exp_f32_e32 v106, v74
	v_exp_f32_e32 v107, v75
	v_exp_f32_e32 v112, v80
	v_mfma_f32_32x32x16_bf16 v[2:17], v[198:201], v[102:105], v[2:17]
	v_exp_f32_e32 v102, v70
	v_exp_f32_e32 v103, v71
	v_exp_f32_e32 v104, v72
	v_exp_f32_e32 v105, v73
	v_exp_f32_e32 v113, v81
	v_mfma_f32_32x32x16_bf16 v[2:17], v[206:209], v[108:111], v[2:17]
	v_exp_f32_e32 v108, v76
	v_exp_f32_e32 v109, v77
	v_exp_f32_e32 v110, v78
	v_exp_f32_e32 v111, v79
	v_mfma_f32_32x32x16_bf16 v[2:17], v[202:205], v[114:117], v[2:17]
	s_waitcnt vmcnt(4)
	v_cmp_gt_f32_e32 vcc, 1.0, v238
	ds_write_b128 v219, v[174:177] offset:32768
	ds_write_b128 v220, v[162:165] offset:32768
	s_cbranch_vccz .LBB0_175
	s_and_saveexec_b64 s[16:17], s[2:3]
	ds_write_b32 v214, v238 offset:128
	s_or_b64 exec, exec, s[16:17]
	s_waitcnt lgkmcnt(0)
	v_add_u32_e32 v78, s95, v210
	ds_read_b128 v[66:69], v78 offset:224
	ds_read_b128 v[70:73], v78 offset:192
	ds_read_b128 v[74:77], v78 offset:160
	ds_read_b128 v[78:81], v78 offset:128
	s_waitcnt lgkmcnt(3)
	v_pk_mul_f32 v[62:63], v[62:63], v[66:67]
	s_waitcnt lgkmcnt(2)
	v_pk_mul_f32 v[58:59], v[58:59], v[70:71]
	s_waitcnt lgkmcnt(1)
	v_pk_mul_f32 v[54:55], v[54:55], v[74:75]
	v_pk_mul_f32 v[64:65], v[64:65], v[68:69]
	v_pk_mul_f32 v[60:61], v[60:61], v[72:73]
	v_pk_mul_f32 v[56:57], v[56:57], v[76:77]
	s_waitcnt lgkmcnt(0)
	v_pk_mul_f32 v[52:53], v[52:53], v[80:81]
	v_pk_mul_f32 v[50:51], v[50:51], v[78:79]
	v_pk_mul_f32 v[46:47], v[46:47], v[66:67]
	v_pk_mul_f32 v[42:43], v[42:43], v[70:71]
	v_pk_mul_f32 v[38:39], v[38:39], v[74:75]
	v_pk_mul_f32 v[48:49], v[48:49], v[68:69]
	v_pk_mul_f32 v[44:45], v[44:45], v[72:73]
	v_pk_mul_f32 v[40:41], v[40:41], v[76:77]
	v_pk_mul_f32 v[36:37], v[36:37], v[80:81]
	v_pk_mul_f32 v[34:35], v[34:35], v[78:79]
	v_pk_mul_f32 v[30:31], v[30:31], v[66:67]
	v_pk_mul_f32 v[26:27], v[26:27], v[70:71]
	v_pk_mul_f32 v[22:23], v[22:23], v[74:75]
	v_pk_mul_f32 v[32:33], v[32:33], v[68:69]
	v_pk_mul_f32 v[28:29], v[28:29], v[72:73]
	v_pk_mul_f32 v[24:25], v[24:25], v[76:77]
	v_pk_mul_f32 v[20:21], v[20:21], v[80:81]
	v_pk_mul_f32 v[18:19], v[18:19], v[78:79]
	v_pk_mul_f32 v[14:15], v[14:15], v[66:67]
	v_pk_mul_f32 v[10:11], v[10:11], v[70:71]
	v_pk_mul_f32 v[6:7], v[6:7], v[74:75]
	v_pk_mul_f32 v[16:17], v[16:17], v[68:69]
	v_pk_mul_f32 v[12:13], v[12:13], v[72:73]
	v_pk_mul_f32 v[8:9], v[8:9], v[76:77]
	v_pk_mul_f32 v[4:5], v[4:5], v[80:81]
	v_pk_mul_f32 v[2:3], v[2:3], v[78:79]

; #define SBAR() __builtin_amdgcn_sched_barrier(0)
; #define SLOAD(i, k0) do { const long to_ = (long)(k0) * ldk * 2; const char* vt_ = (const char*)Vh + to_; const char* kt_ = (const char*)Kh + to_; \
;     sr_[i].vs0 = *(const bf16x8*)(vt_ + toff); sr_[i].vs1 = *(const bf16x8*)(vt_ + h32 + toff); \
;     sr_[i].ks0 = *(const bf16x8*)(kt_ + toff); sr_[i].ks1 = *(const bf16x8*)(kt_ + h32 + toff); } while (0)
; #define SWAIT() do { if constexpr (SDEPTH == 2) asm volatile("s_waitcnt vmcnt(4)" ::: "memory"); else asm volatile("s_waitcnt vmcnt(0)" ::: "memory"); } while (0)
; __device__ __forceinline__ void psm_decide(float pmax, const f32x16& p1, float& m_reg, float& mn, float& alpha) {
;   constexpr float C = SCALE * 1.4426950408889634f;
;   for (int r = 0; r < 16; ++r) pmax = fmaxf(pmax, p1[r]);
;   { auto rr = __builtin_amdgcn_permlane32_swap(__float_as_uint(pmax), __float_as_uint(pmax), false, false);
;     pmax = fmaxf(__uint_as_float(rr[0]), __uint_as_float(rr[1])); }
;   if (__builtin_expect(__all(pmax - m_reg <= THR / SCALE), 1)) { mn = m_reg; alpha = 1.f; }
;   else { mn = fmaxf(m_reg, pmax); alpha = __builtin_amdgcn_exp2f((m_reg - mn) * C); m_reg = mn; }
; }
; __device__ __forceinline__ void psm_scale(f32x16& p0, f32x16& p1, float mn) {
;   constexpr float C = SCALE * 1.4426950408889634f; const float mnC = -mn * C;
;   for (int r = 0; r < 16; ++r) p0[r] = fmaf(p0[r], C, mnC); for (int r = 0; r < 16; ++r) p1[r] = fmaf(p1[r], C, mnC);
; }
; template <int MODE, int QMODE> ...
;     ...
;     SBAR(); qkt(pA0, pA1, K_lds, qr, r32, hi);
;     finishSM(pB0, pB1, alB, l_reg, pa0, pa1, pa2, pa3); SBAR();
;     if (SDEPTH == 1 || j + 3 < NT) SLOAD(SE, (j + 1 + SDEPTH) * KVBLK); SBAR();
;     PVSM(vb0 + (int)SHM_V, pA0, pA1, (j + 1) * KVBLK, mnA, alA);
;     __syncthreads(); SWAIT(); SWRITE(1, SO);
.LBB0_177:
	ds_read_b64_tr_b16 v[82:83], v216 offset:0
	ds_read_b64_tr_b16 v[84:85], v216 offset:0x800
	ds_read_b64_tr_b16 v[86:87], v216 offset:0x1000
	ds_read_b64_tr_b16 v[88:89], v216 offset:0x1800
	ds_read_b64_tr_b16 v[90:91], v216 offset:0x2000
	ds_read_b64_tr_b16 v[92:93], v216 offset:0x2800
	ds_read_b64_tr_b16 v[94:95], v216 offset:0x3000
	ds_read_b64_tr_b16 v[96:97], v216 offset:0x3800
	s_waitcnt lgkmcnt(0)
	s_nop 0
	v_mfma_f32_32x32x16_bf16 v[50:65], v[206:209], v[82:85], v[50:65]
	v_max_f32_e32 v82, v114, v115
	v_max3_f32 v82, v82, v116, v117
	v_max3_f32 v82, v82, v118, v119
	v_max3_f32 v82, v82, v120, v121
	v_max3_f32 v82, v82, v122, v123
	v_mfma_f32_32x32x16_bf16 v[50:65], v[198:201], v[86:89], v[50:65]
	v_max3_f32 v82, v82, v124, v125
	v_max3_f32 v84, v82, v126, v127
	ds_read_b64_tr_b16 v[82:83], v216 offset:0x200
	v_max3_f32 v102, v84, v128, v129
	ds_read_b64_tr_b16 v[84:85], v216 offset:0xa00
	ds_read_b64_tr_b16 v[86:87], v216 offset:0x1200
	ds_read_b64_tr_b16 v[88:89], v216 offset:0x1a00
	v_mfma_f32_32x32x16_bf16 v[50:65], v[202:205], v[90:93], v[50:65]
	ds_read_b64_tr_b16 v[90:91], v216 offset:0x2200
	ds_read_b64_tr_b16 v[92:93], v216 offset:0x2a00
	ds_read_b64_tr_b16 v[98:99], v216 offset:0x3200
	ds_read_b64_tr_b16 v[100:101], v216 offset:0x3a00
	s_waitcnt lgkmcnt(0)
	v_mfma_f32_32x32x16_bf16 v[50:65], v[194:197], v[94:97], v[50:65]
	v_max3_f32 v94, v102, v66, v67
	v_mfma_f32_32x32x16_bf16 v[34:49], v[206:209], v[82:85], v[34:49]
	v_max3_f32 v94, v94, v68, v69
	v_max3_f32 v94, v94, v70, v71
	v_max3_f32 v94, v94, v72, v73
	v_max3_f32 v94, v94, v74, v75
	v_max3_f32 v94, v94, v76, v77
	v_max3_f32 v82, v94, v78, v79
	v_max3_f32 v82, v82, v80, v81
	v_mov_b32_e32 v83, v82
	v_mfma_f32_32x32x16_bf16 v[34:49], v[198:201], v[86:89], v[34:49]
	s_nop 0
	v_permlane32_swap_b32_e32 v82, v83
	v_max_f32_e32 v82, v82, v83
	v_sub_f32_e32 v83, v82, v236
	v_cmp_ge_f32_e32 vcc, s62, v83
	v_max_f32_e32 v82, v236, v82
	v_sub_f32_e32 v83, v236, v82
	v_mul_f32_e32 v83, 0x3e0293ee, v83
	v_mfma_f32_32x32x16_bf16 v[34:49], v[202:205], v[90:93], v[34:49]
	v_exp_f32_e32 v83, v83
	s_cmp_eq_u64 vcc, exec
	s_cselect_b64 vcc, -1, 0
	v_cndmask_b32_e32 v237, v82, v236, vcc
	v_cndmask_b32_e64 v236, v83, 1.0, vcc
	ds_read_b64_tr_b16 v[82:83], v216 offset:0x400
	ds_read_b64_tr_b16 v[84:85], v216 offset:0xc00
	ds_read_b64_tr_b16 v[86:87], v216 offset:0x1400
	v_mfma_f32_32x32x16_bf16 v[34:49], v[194:197], v[98:101], v[34:49]
	ds_read_b64_tr_b16 v[88:89], v216 offset:0x1c00
	ds_read_b64_tr_b16 v[242:243], v216 offset:0x2400
	ds_read_b64_tr_b16 v[244:245], v216 offset:0x2c00
	ds_read_b64_tr_b16 v[246:247], v216 offset:0x3400
	ds_read_b64_tr_b16 v[248:249], v216 offset:0x3c00
	s_waitcnt lgkmcnt(0)
	v_mfma_f32_32x32x16_bf16 v[18:33], v[206:209], v[82:85], v[18:33]
	v_mul_f32_e32 v250, 0xbe0293ee, v237
	v_fma_f32 v112, v128, s12, v250
	v_fma_f32 v113, v129, s12, v250
	v_fma_f32 v110, v126, s12, v250
	v_fma_f32 v111, v127, s12, v250
	v_pk_fma_f32 v[108:109], v[124:125], s[12:13], v[250:251] op_sel_hi:[1,0,0]
	v_pk_fma_f32 v[106:107], v[122:123], s[12:13], v[250:251] op_sel_hi:[1,0,0]
	v_pk_fma_f32 v[104:105], v[120:121], s[12:13], v[250:251] op_sel_hi:[1,0,0]
	v_pk_fma_f32 v[102:103], v[118:119], s[12:13], v[250:251] op_sel_hi:[1,0,0]
	v_mfma_f32_32x32x16_bf16 v[18:33], v[198:201], v[86:89], v[18:33]
	v_fma_f32 v100, v116, s12, v250
	v_fma_f32 v101, v117, s12, v250
	v_fma_f32 v98, v114, s12, v250
	v_fma_f32 v99, v115, s12, v250
	v_fma_f32 v96, v80, s12, v250
	v_fma_f32 v97, v81, s12, v250
	v_pk_fma_f32 v[94:95], v[78:79], s[12:13], v[250:251] op_sel_hi:[1,0,0]
	v_pk_fma_f32 v[92:93], v[76:77], s[12:13], v[250:251] op_sel_hi:[1,0,0]
	v_pk_fma_f32 v[90:91], v[74:75], s[12:13], v[250:251] op_sel_hi:[1,0,0]
	v_pk_fma_f32 v[88:89], v[72:73], s[12:13], v[250:251] op_sel_hi:[1,0,0]
	v_mfma_f32_32x32x16_bf16 v[18:33], v[202:205], v[242:245], v[18:33]
	v_fma_f32 v86, v70, s12, v250
	v_fma_f32 v87, v71, s12, v250
	v_fma_f32 v84, v68, s12, v250
	v_fma_f32 v85, v69, s12, v250
	v_fma_f32 v82, v66, s12, v250
	v_fma_f32 v83, v67, s12, v250
	ds_read_b64_tr_b16 v[66:67], v216 offset:0x600
	ds_read_b64_tr_b16 v[68:69], v216 offset:0xe00
	ds_read_b64_tr_b16 v[70:71], v216 offset:0x1600
	ds_read_b64_tr_b16 v[72:73], v216 offset:0x1e00
	v_mfma_f32_32x32x16_bf16 v[18:33], v[194:197], v[246:249], v[18:33]
	ds_read_b64_tr_b16 v[76:77], v216 offset:0x2600
	ds_read_b64_tr_b16 v[78:79], v216 offset:0x2e00
	ds_read_b64_tr_b16 v[114:115], v216 offset:0x3600
	ds_read_b64_tr_b16 v[116:117], v216 offset:0x3e00
	s_waitcnt lgkmcnt(0)
	v_mfma_f32_32x32x16_bf16 v[2:17], v[206:209], v[66:69], v[2:17]
	v_exp_f32_e32 v66, v98
	v_exp_f32_e32 v67, v99
	v_exp_f32_e32 v68, v100
	v_exp_f32_e32 v69, v101
	v_exp_f32_e32 v74, v106
	v_exp_f32_e32 v75, v107
	v_exp_f32_e32 v80, v112
	v_mfma_f32_32x32x16_bf16 v[2:17], v[198:201], v[70:73], v[2:17]
	v_exp_f32_e32 v70, v102
	v_exp_f32_e32 v71, v103
	v_exp_f32_e32 v72, v104
	v_exp_f32_e32 v73, v105
	v_exp_f32_e32 v81, v113
	v_mfma_f32_32x32x16_bf16 v[2:17], v[202:205], v[76:79], v[2:17]
	v_exp_f32_e32 v76, v108
	v_exp_f32_e32 v77, v109
	v_exp_f32_e32 v78, v110
	v_exp_f32_e32 v79, v111
	v_mfma_f32_32x32x16_bf16 v[2:17], v[194:197], v[114:117], v[2:17]
	s_waitcnt vmcnt(4)
	s_cmp_ge_u32 s96, s94
	s_cbranch_scc0 .Lb_nodrain
	s_waitcnt vmcnt(0)

; #define PG8_STAGE(bufoff, gbase, voff) do { _Pragma("unroll") for (int _i = 0; _i < 2; ++_i) \
;         __builtin_amdgcn_global_load_lds((const unsigned*)((const char*)(gbase) + (voff)[_i]), (PG8_LAS unsigned*)(lds + (bufoff) + ldsw + _i * 8192), 16, 0, 0); } while (0)
; #define PG8_LDA(dst, b, h) do { _Pragma("unroll") for (int m = 0; m < 4; ++m) _Pragma("unroll") for (int k = 0; k < 2; ++k) dst[m][k] = *(const PG8_LAS bf16x8*)(lds + PG8_SA(b, h) + aoff + m * 2048 + k * 1024); } while (0)
; #define PG8_LDB(dst, b, h) do { _Pragma("unroll") for (int n = 0; n < 2; ++n) _Pragma("unroll") for (int k = 0; k < 2; ++k) dst[n][k] = *(const PG8_LAS bf16x8*)(lds + PG8_SB(b, h) + boff + n * 2048 + k * 1024); } while (0)
; #define PG8_MMA(ai, bj, At, Bt) do { __builtin_amdgcn_s_setprio(1); _Pragma("unroll") for (int m = 0; m < 4; ++m) _Pragma("unroll") for (int n = 0; n < 2; ++n) _Pragma("unroll") for (int k = 0; k < 2; ++k) \
;         acc[ai][bj][m][n] = __builtin_amdgcn_mfma_f32_16x16x32_bf16(Bt[n][k], At[m][k], acc[ai][bj][m][n], 0, 0, 0); __builtin_amdgcn_s_setprio(0); } while (0)
; #define PG8_WAIT_V(n) asm volatile("s_waitcnt vmcnt(" #n ")" ::: "memory")
; #define PG8_WAIT_L(n) asm volatile("s_waitcnt lgkmcnt(" #n ")" ::: "memory")
; #define PG8_BAR __builtin_amdgcn_s_barrier()
; #define PG8_SCHED __builtin_amdgcn_sched_barrier(0)
; template <class Epi, class Sched, bool ALIGN_EPI = false, bool SP2 = false, bool KSEG = false>
; __device__ __forceinline__ void gemm_phase(PG8_LAS unsigned char* lds, const Gemm g, const Sched& S, const Epi& E) {
;     ...
;             PG8_LDB(B0, 0, 0); PG8_LDB(B1, 0, 1); PG8_SCHED; PG8_LDA(At, 0, 0); PG8_STAGE(PG8_SA(1, 1), a1 + hstep, voffA);
;             PG8_WAIT_V(8); PG8_WAIT_L(0); PG8_BAR; PG8_MMA(0, 0, At, B0); PG8_MMA(0, 1, At, B1); PG8_BAR; PG8_SCHED;
;             PG8_LDA(At, 0, 1); PG8_STAGE(PG8_SB(0, 0), b2, voffB); PG8_STAGE(PG8_SB(0, 1), b2 + hstep, voffB); PG8_STAGE(PG8_SA(0, 0), a2, voffA);
;             PG8_WAIT_V(8); PG8_WAIT_L(0); PG8_BAR; PG8_MMA(1, 0, At, B0); PG8_MMA(1, 1, At, B1); PG8_BAR; PG8_SCHED;
;             PG8_LDB(B0, 1, 0); PG8_LDB(B1, 1, 1); PG8_SCHED; PG8_LDA(At, 1, 0); PG8_STAGE(PG8_SA(0, 1), a2 + hstep, voffA);
;             PG8_WAIT_V(8); PG8_WAIT_L(0); PG8_BAR; PG8_MMA(0, 0, At, B0); PG8_MMA(0, 1, At, B1); PG8_BAR; PG8_SCHED;
.LBB0_413:
	ds_read_b128 v[170:173], v160
	ds_read_b128 v[174:177], v160 offset:1024
	ds_read_b128 v[178:181], v160 offset:2048
	ds_read_b128 v[182:185], v160 offset:3072
	ds_read_b128 v[186:189], v161
	ds_read_b128 v[190:193], v161 offset:1024
	ds_read_b128 v[194:197], v161 offset:2048
	ds_read_b128 v[198:201], v161 offset:3072
	s_add_u32 s33, s40, s42
	s_addc_u32 s44, s41, s43
	s_add_u32 s33, s33, 0x100
	s_addc_u32 s44, s44, 0
	s_add_u32 s88, s85, s42
	s_addc_u32 s45, s86, s43
	s_cmpk_eq_i32 s42, 0xf00
	s_cselect_b32 s47, s23, s44
	s_cselect_b32 s46, s29, s33
	s_cselect_b32 s45, s21, s45
	s_cselect_b32 s44, s31, s88
	v_lshl_add_u64 v[4:5], v[150:151], 0, s[42:43]
	s_add_i32 m0, s51, 0xc000
	ds_read_b128 v[202:205], v162
	ds_read_b128 v[206:209], v162 offset:1024
	ds_read_b128 v[210:213], v162 offset:2048
	ds_read_b128 v[214:217], v162 offset:3072
	ds_read_b128 v[218:221], v162 offset:4096
	ds_read_b128 v[222:225], v162 offset:5120
	ds_read_b128 v[226:229], v162 offset:6144
	ds_read_b128 v[230:233], v162 offset:7168
	global_load_lds_dwordx4 v[4:5], off
	s_add_i32 m0, s51, 0xe000
	v_lshl_add_u64 v[4:5], v[152:153], 0, s[42:43]
	global_load_lds_dwordx4 v[4:5], off
	s_waitcnt vmcnt(8) lgkmcnt(0)
	s_barrier
	s_setprio 1
	v_mfma_f32_16x16x32_bf16 v[130:133], v[170:173], v[202:205], v[130:133]
	v_mfma_f32_16x16x32_bf16 v[126:129], v[178:181], v[202:205], v[126:129]
	v_mfma_f32_16x16x32_bf16 v[114:117], v[170:173], v[210:213], v[114:117]
	v_mfma_f32_16x16x32_bf16 v[110:113], v[178:181], v[210:213], v[110:113]
	v_mfma_f32_16x16x32_bf16 v[98:101], v[170:173], v[218:221], v[98:101]
	v_mfma_f32_16x16x32_bf16 v[94:97], v[178:181], v[218:221], v[94:97]
	v_mfma_f32_16x16x32_bf16 v[82:85], v[170:173], v[226:229], v[82:85]
	v_mfma_f32_16x16x32_bf16 v[78:81], v[178:181], v[226:229], v[78:81]
	v_mfma_f32_16x16x32_bf16 v[130:133], v[174:177], v[206:209], v[130:133]
	v_mfma_f32_16x16x32_bf16 v[126:129], v[182:185], v[206:209], v[126:129]
	v_mfma_f32_16x16x32_bf16 v[114:117], v[174:177], v[214:217], v[114:117]
	v_mfma_f32_16x16x32_bf16 v[110:113], v[182:185], v[214:217], v[110:113]
	v_mfma_f32_16x16x32_bf16 v[98:101], v[174:177], v[222:225], v[98:101]
	v_mfma_f32_16x16x32_bf16 v[94:97], v[182:185], v[222:225], v[94:97]
	v_mfma_f32_16x16x32_bf16 v[82:85], v[174:177], v[230:233], v[82:85]
	v_mfma_f32_16x16x32_bf16 v[78:81], v[182:185], v[230:233], v[78:81]
	s_setprio 0
	s_setprio 1
	v_mfma_f32_16x16x32_bf16 v[122:125], v[186:189], v[202:205], v[122:125]
	v_mfma_f32_16x16x32_bf16 v[118:121], v[194:197], v[202:205], v[118:121]
	v_mfma_f32_16x16x32_bf16 v[106:109], v[186:189], v[210:213], v[106:109]
	v_mfma_f32_16x16x32_bf16 v[102:105], v[194:197], v[210:213], v[102:105]
	v_mfma_f32_16x16x32_bf16 v[90:93], v[186:189], v[218:221], v[90:93]
	v_mfma_f32_16x16x32_bf16 v[86:89], v[194:197], v[218:221], v[86:89]
	v_mfma_f32_16x16x32_bf16 v[74:77], v[186:189], v[226:229], v[74:77]
	v_mfma_f32_16x16x32_bf16 v[70:73], v[194:197], v[226:229], v[70:73]
	v_mfma_f32_16x16x32_bf16 v[122:125], v[190:193], v[206:209], v[122:125]
	v_mfma_f32_16x16x32_bf16 v[118:121], v[198:201], v[206:209], v[118:121]
	v_mfma_f32_16x16x32_bf16 v[106:109], v[190:193], v[214:217], v[106:109]
	v_mfma_f32_16x16x32_bf16 v[102:105], v[198:201], v[214:217], v[102:105]
	v_mfma_f32_16x16x32_bf16 v[90:93], v[190:193], v[222:225], v[90:93]
	v_mfma_f32_16x16x32_bf16 v[86:89], v[198:201], v[222:225], v[86:89]
	v_mfma_f32_16x16x32_bf16 v[74:77], v[190:193], v[230:233], v[74:77]
	v_mfma_f32_16x16x32_bf16 v[70:73], v[198:201], v[230:233], v[70:73]
	s_setprio 0
	s_barrier
	s_add_i32 s33, s65, s50
	v_lshl_add_u64 v[234:235], s[44:45], 0, v[136:137]
	s_mov_b32 m0, s33
	ds_read_b128 v[202:205], v162 offset:16384
	ds_read_b128 v[206:209], v162 offset:17408
	ds_read_b128 v[210:213], v162 offset:18432
	ds_read_b128 v[214:217], v162 offset:19456
	ds_read_b128 v[218:221], v162 offset:20480
	ds_read_b128 v[222:225], v162 offset:21504
	ds_read_b128 v[226:229], v162 offset:22528
	ds_read_b128 v[230:233], v162 offset:23552
	global_load_lds_dwordx4 v[234:235], off
	s_add_i32 m0, s33, 0x2000
	s_add_u32 s88, s44, 0x80000
	v_lshl_add_u64 v[236:237], s[44:45], 0, v[140:141]
	s_addc_u32 s89, s45, 0
	s_add_i32 s33, s66, s50
	global_load_lds_dwordx4 v[236:237], off
	v_lshl_add_u64 v[4:5], s[88:89], 0, v[136:137]
	s_mov_b32 m0, s33
	v_lshl_add_u64 v[238:239], s[46:47], 0, v[134:135]
	global_load_lds_dwordx4 v[4:5], off
	v_lshl_add_u64 v[4:5], s[88:89], 0, v[140:141]
	s_add_i32 m0, s33, 0x2000
	v_lshl_add_u64 v[240:241], s[46:47], 0, v[138:139]
	global_load_lds_dwordx4 v[4:5], off
	s_mov_b32 m0, s51
	s_nop 0
	global_load_lds_dwordx4 v[238:239], off
	s_mov_b32 m0, s52
	s_nop 0
	global_load_lds_dwordx4 v[240:241], off
	s_waitcnt vmcnt(8) lgkmcnt(0)
	s_barrier
; #define PG8_STAGE(bufoff, gbase, voff) do { _Pragma("unroll") for (int _i = 0; _i < 2; ++_i) \
;         __builtin_amdgcn_global_load_lds((const unsigned*)((const char*)(gbase) + (voff)[_i]), (PG8_LAS unsigned*)(lds + (bufoff) + ldsw + _i * 8192), 16, 0, 0); } while (0)
; #define PG8_LDA(dst, b, h) do { _Pragma("unroll") for (int m = 0; m < 4; ++m) _Pragma("unroll") for (int k = 0; k < 2; ++k) dst[m][k] = *(const PG8_LAS bf16x8*)(lds + PG8_SA(b, h) + aoff + m * 2048 + k * 1024); } while (0)
; #define PG8_LDB(dst, b, h) do { _Pragma("unroll") for (int n = 0; n < 2; ++n) _Pragma("unroll") for (int k = 0; k < 2; ++k) dst[n][k] = *(const PG8_LAS bf16x8*)(lds + PG8_SB(b, h) + boff + n * 2048 + k * 1024); } while (0)
; #define PG8_MMA(ai, bj, At, Bt) do { __builtin_amdgcn_s_setprio(1); _Pragma("unroll") for (int m = 0; m < 4; ++m) _Pragma("unroll") for (int n = 0; n < 2; ++n) _Pragma("unroll") for (int k = 0; k < 2; ++k) \
;         acc[ai][bj][m][n] = __builtin_amdgcn_mfma_f32_16x16x32_bf16(Bt[n][k], At[m][k], acc[ai][bj][m][n], 0, 0, 0); __builtin_amdgcn_s_setprio(0); } while (0)
; #define PG8_WAIT_V(n) asm volatile("s_waitcnt vmcnt(" #n ")" ::: "memory")
; #define PG8_WAIT_L(n) asm volatile("s_waitcnt lgkmcnt(" #n ")" ::: "memory")
; #define PG8_BAR __builtin_amdgcn_s_barrier()
; #define PG8_SCHED __builtin_amdgcn_sched_barrier(0)
; template <class Epi, class Sched, bool ALIGN_EPI = false, bool SP2 = false, bool KSEG = false>
; __device__ __forceinline__ void gemm_phase(PG8_LAS unsigned char* lds, const Gemm g, const Sched& S, const Epi& E) {
;     ...
;             PG8_WAIT_V(8); PG8_WAIT_L(0); PG8_BAR; PG8_MMA(1, 0, At, B0); PG8_MMA(1, 1, At, B1); PG8_BAR; PG8_SCHED;
;             PG8_LDB(B0, 1, 0); PG8_LDB(B1, 1, 1); PG8_SCHED; PG8_LDA(At, 1, 0); PG8_STAGE(PG8_SA(0, 1), a2 + hstep, voffA);
;             PG8_WAIT_V(8); PG8_WAIT_L(0); PG8_BAR; PG8_MMA(0, 0, At, B0); PG8_MMA(0, 1, At, B1); PG8_BAR; PG8_SCHED;
;             PG8_LDA(At, 1, 1); PG8_STAGE(PG8_SB(1, 0), b3, voffB); PG8_STAGE(PG8_SB(1, 1), b3 + hstep, voffB); PG8_STAGE(PG8_SA(1, 0), a3, voffA);
;             PG8_WAIT_V(8); PG8_WAIT_L(0); PG8_BAR; PG8_MMA(1, 0, At, B0); PG8_MMA(1, 1, At, B1); PG8_BAR; PG8_SCHED;
	s_setprio 1
	v_mfma_f32_16x16x32_bf16 v[66:69], v[170:173], v[202:205], v[66:69]
	v_mfma_f32_16x16x32_bf16 v[62:65], v[178:181], v[202:205], v[62:65]
	v_mfma_f32_16x16x32_bf16 v[50:53], v[170:173], v[210:213], v[50:53]
	v_mfma_f32_16x16x32_bf16 v[46:49], v[178:181], v[210:213], v[46:49]
	v_mfma_f32_16x16x32_bf16 v[34:37], v[170:173], v[218:221], v[34:37]
	v_mfma_f32_16x16x32_bf16 v[30:33], v[178:181], v[218:221], v[30:33]
	v_mfma_f32_16x16x32_bf16 v[18:21], v[170:173], v[226:229], v[18:21]
	v_mfma_f32_16x16x32_bf16 v[14:17], v[178:181], v[226:229], v[14:17]
	v_mfma_f32_16x16x32_bf16 v[66:69], v[174:177], v[206:209], v[66:69]
	v_mfma_f32_16x16x32_bf16 v[62:65], v[182:185], v[206:209], v[62:65]
	v_mfma_f32_16x16x32_bf16 v[50:53], v[174:177], v[214:217], v[50:53]
	v_mfma_f32_16x16x32_bf16 v[46:49], v[182:185], v[214:217], v[46:49]
	v_mfma_f32_16x16x32_bf16 v[34:37], v[174:177], v[222:225], v[34:37]
	v_mfma_f32_16x16x32_bf16 v[30:33], v[182:185], v[222:225], v[30:33]
	v_mfma_f32_16x16x32_bf16 v[18:21], v[174:177], v[230:233], v[18:21]
	v_mfma_f32_16x16x32_bf16 v[14:17], v[182:185], v[230:233], v[14:17]
	s_setprio 0
	s_setprio 1
	v_mfma_f32_16x16x32_bf16 v[58:61], v[186:189], v[202:205], v[58:61]
	v_mfma_f32_16x16x32_bf16 v[54:57], v[194:197], v[202:205], v[54:57]
	v_mfma_f32_16x16x32_bf16 v[42:45], v[186:189], v[210:213], v[42:45]
	v_mfma_f32_16x16x32_bf16 v[38:41], v[194:197], v[210:213], v[38:41]
	v_mfma_f32_16x16x32_bf16 v[26:29], v[186:189], v[218:221], v[26:29]
	v_mfma_f32_16x16x32_bf16 v[22:25], v[194:197], v[218:221], v[22:25]
	v_mfma_f32_16x16x32_bf16 v[10:13], v[186:189], v[226:229], v[10:13]
	v_mfma_f32_16x16x32_bf16 v[4:7], v[194:197], v[226:229], v[6:9]
	v_mfma_f32_16x16x32_bf16 v[58:61], v[190:193], v[206:209], v[58:61]
	v_mfma_f32_16x16x32_bf16 v[54:57], v[198:201], v[206:209], v[54:57]
	v_mfma_f32_16x16x32_bf16 v[42:45], v[190:193], v[214:217], v[42:45]
	v_mfma_f32_16x16x32_bf16 v[38:41], v[198:201], v[214:217], v[38:41]
	v_mfma_f32_16x16x32_bf16 v[26:29], v[190:193], v[222:225], v[26:29]
	v_mfma_f32_16x16x32_bf16 v[22:25], v[198:201], v[222:225], v[22:25]
	v_mfma_f32_16x16x32_bf16 v[10:13], v[190:193], v[230:233], v[10:13]
	v_mfma_f32_16x16x32_bf16 v[4:7], v[198:201], v[230:233], v[4:7]
	s_setprio 0
	s_barrier
	s_add_i32 s33, 0, 0x18000
	v_add_u32_e32 v3, s33, v157
	s_add_i32 s88, 0, 0x1c000
	ds_read_b128 v[170:173], v3
	ds_read_b128 v[174:177], v3 offset:1024
	ds_read_b128 v[178:181], v3 offset:2048
	ds_read_b128 v[182:185], v3 offset:3072
	v_add_u32_e32 v3, s88, v157
	ds_read_b128 v[186:189], v3
	ds_read_b128 v[190:193], v3 offset:1024
	ds_read_b128 v[194:197], v3 offset:2048
	ds_read_b128 v[198:201], v3 offset:3072
	s_add_u32 s46, s46, 0x80000
	s_addc_u32 s47, s47, 0
	s_mov_b32 m0, s53
	v_lshl_add_u64 v[8:9], s[46:47], 0, v[134:135]
	ds_read_b128 v[202:205], v162 offset:32768
	ds_read_b128 v[206:209], v162 offset:33792
	ds_read_b128 v[210:213], v162 offset:34816
	ds_read_b128 v[214:217], v162 offset:35840
	ds_read_b128 v[218:221], v162 offset:36864
	ds_read_b128 v[222:225], v162 offset:37888
	ds_read_b128 v[226:229], v162 offset:38912
	ds_read_b128 v[230:233], v162 offset:39936
	global_load_lds_dwordx4 v[8:9], off
	s_mov_b32 m0, s54
	v_lshl_add_u64 v[8:9], s[46:47], 0, v[138:139]
	global_load_lds_dwordx4 v[8:9], off
	s_waitcnt vmcnt(8) lgkmcnt(0)
	s_barrier
	s_setprio 1
	v_mfma_f32_16x16x32_bf16 v[130:133], v[170:173], v[202:205], v[130:133]
	v_mfma_f32_16x16x32_bf16 v[126:129], v[178:181], v[202:205], v[126:129]
	v_mfma_f32_16x16x32_bf16 v[114:117], v[170:173], v[210:213], v[114:117]
	v_mfma_f32_16x16x32_bf16 v[110:113], v[178:181], v[210:213], v[110:113]
	v_mfma_f32_16x16x32_bf16 v[98:101], v[170:173], v[218:221], v[98:101]
	v_mfma_f32_16x16x32_bf16 v[94:97], v[178:181], v[218:221], v[94:97]
	v_mfma_f32_16x16x32_bf16 v[82:85], v[170:173], v[226:229], v[82:85]
	v_mfma_f32_16x16x32_bf16 v[78:81], v[178:181], v[226:229], v[78:81]
	v_mfma_f32_16x16x32_bf16 v[130:133], v[174:177], v[206:209], v[130:133]
	v_mfma_f32_16x16x32_bf16 v[126:129], v[182:185], v[206:209], v[126:129]
	v_mfma_f32_16x16x32_bf16 v[114:117], v[174:177], v[214:217], v[114:117]
	v_mfma_f32_16x16x32_bf16 v[110:113], v[182:185], v[214:217], v[110:113]
	v_mfma_f32_16x16x32_bf16 v[98:101], v[174:177], v[222:225], v[98:101]
	v_mfma_f32_16x16x32_bf16 v[94:97], v[182:185], v[222:225], v[94:97]
	v_mfma_f32_16x16x32_bf16 v[82:85], v[174:177], v[230:233], v[82:85]
	v_mfma_f32_16x16x32_bf16 v[78:81], v[182:185], v[230:233], v[78:81]
	s_setprio 0
	s_setprio 1
	v_mfma_f32_16x16x32_bf16 v[122:125], v[186:189], v[202:205], v[122:125]
	v_mfma_f32_16x16x32_bf16 v[118:121], v[194:197], v[202:205], v[118:121]
	v_mfma_f32_16x16x32_bf16 v[106:109], v[186:189], v[210:213], v[106:109]
	v_mfma_f32_16x16x32_bf16 v[102:105], v[194:197], v[210:213], v[102:105]
	v_mfma_f32_16x16x32_bf16 v[90:93], v[186:189], v[218:221], v[90:93]
	v_mfma_f32_16x16x32_bf16 v[86:89], v[194:197], v[218:221], v[86:89]
	v_mfma_f32_16x16x32_bf16 v[74:77], v[186:189], v[226:229], v[74:77]
	v_mfma_f32_16x16x32_bf16 v[70:73], v[194:197], v[226:229], v[70:73]
	v_mfma_f32_16x16x32_bf16 v[122:125], v[190:193], v[206:209], v[122:125]
	v_mfma_f32_16x16x32_bf16 v[118:121], v[198:201], v[206:209], v[118:121]
	v_mfma_f32_16x16x32_bf16 v[106:109], v[190:193], v[214:217], v[106:109]
	v_mfma_f32_16x16x32_bf16 v[102:105], v[198:201], v[214:217], v[102:105]
	v_mfma_f32_16x16x32_bf16 v[90:93], v[190:193], v[222:225], v[90:93]
	v_mfma_f32_16x16x32_bf16 v[86:89], v[198:201], v[222:225], v[86:89]
	v_mfma_f32_16x16x32_bf16 v[74:77], v[190:193], v[230:233], v[74:77]
	v_mfma_f32_16x16x32_bf16 v[70:73], v[198:201], v[230:233], v[70:73]
	s_setprio 0
	s_barrier
; #define PG8_STAGE(bufoff, gbase, voff) do { _Pragma("unroll") for (int _i = 0; _i < 2; ++_i) \
;         __builtin_amdgcn_global_load_lds((const unsigned*)((const char*)(gbase) + (voff)[_i]), (PG8_LAS unsigned*)(lds + (bufoff) + ldsw + _i * 8192), 16, 0, 0); } while (0)
; #define PG8_LDA(dst, b, h) do { _Pragma("unroll") for (int m = 0; m < 4; ++m) _Pragma("unroll") for (int k = 0; k < 2; ++k) dst[m][k] = *(const PG8_LAS bf16x8*)(lds + PG8_SA(b, h) + aoff + m * 2048 + k * 1024); } while (0)
; #define PG8_MMA(ai, bj, At, Bt) do { __builtin_amdgcn_s_setprio(1); _Pragma("unroll") for (int m = 0; m < 4; ++m) _Pragma("unroll") for (int n = 0; n < 2; ++n) _Pragma("unroll") for (int k = 0; k < 2; ++k) \
;         acc[ai][bj][m][n] = __builtin_amdgcn_mfma_f32_16x16x32_bf16(Bt[n][k], At[m][k], acc[ai][bj][m][n], 0, 0, 0); __builtin_amdgcn_s_setprio(0); } while (0)
; #define PG8_WAIT_V(n) asm volatile("s_waitcnt vmcnt(" #n ")" ::: "memory")
; #define PG8_WAIT_L(n) asm volatile("s_waitcnt lgkmcnt(" #n ")" ::: "memory")
; #define PG8_BAR __builtin_amdgcn_s_barrier()
; #define PG8_SCHED __builtin_amdgcn_sched_barrier(0)
; template <class Epi, class Sched, bool ALIGN_EPI = false, bool SP2 = false, bool KSEG = false>
; __device__ __forceinline__ void gemm_phase(PG8_LAS unsigned char* lds, const Gemm g, const Sched& S, const Epi& E) {
;     ...
;             PG8_LDA(At, 1, 1); PG8_STAGE(PG8_SB(1, 0), b3, voffB); PG8_STAGE(PG8_SB(1, 1), b3 + hstep, voffB); PG8_STAGE(PG8_SA(1, 0), a3, voffA);
;             PG8_WAIT_V(8); PG8_WAIT_L(0); PG8_BAR; PG8_MMA(1, 0, At, B0); PG8_MMA(1, 1, At, B1); PG8_BAR; PG8_SCHED;
;     ...
;             if constexpr (KSEG) { if (t == 14 || t == 22) E.kscale(acc, ui, t == 14 ? 0 : 1, wr, fr); }
	s_add_i32 s33, s33, s50
	v_lshl_add_u64 v[8:9], v[234:235], 0, s[8:9]
	s_mov_b32 m0, s33
	ds_read_b128 v[202:205], v162 offset:49152
	ds_read_b128 v[206:209], v162 offset:50176
	ds_read_b128 v[210:213], v162 offset:51200
	ds_read_b128 v[214:217], v162 offset:52224
	ds_read_b128 v[218:221], v162 offset:53248
	ds_read_b128 v[222:225], v162 offset:54272
	ds_read_b128 v[226:229], v162 offset:55296
	ds_read_b128 v[230:233], v162 offset:56320
	global_load_lds_dwordx4 v[8:9], off
	s_add_i32 m0, s33, 0x2000
	s_add_u32 s44, s44, 0x80080
	v_lshl_add_u64 v[8:9], v[236:237], 0, s[8:9]
	s_addc_u32 s45, s45, 0
	s_add_i32 s33, s88, s50
	global_load_lds_dwordx4 v[8:9], off
	s_mov_b32 m0, s33
	v_lshl_add_u64 v[8:9], s[44:45], 0, v[136:137]
	global_load_lds_dwordx4 v[8:9], off
	s_add_i32 m0, s33, 0x2000
	v_lshl_add_u64 v[8:9], s[44:45], 0, v[140:141]
	global_load_lds_dwordx4 v[8:9], off
	s_mov_b32 m0, s55
	v_lshl_add_u64 v[8:9], v[238:239], 0, s[8:9]
	global_load_lds_dwordx4 v[8:9], off
	s_mov_b32 m0, s56
	v_lshl_add_u64 v[8:9], v[240:241], 0, s[8:9]
	global_load_lds_dwordx4 v[8:9], off
	s_waitcnt vmcnt(8) lgkmcnt(0)
	s_barrier
	s_setprio 1
	v_mfma_f32_16x16x32_bf16 v[66:69], v[170:173], v[202:205], v[66:69]
	v_mfma_f32_16x16x32_bf16 v[62:65], v[178:181], v[202:205], v[62:65]
	v_mfma_f32_16x16x32_bf16 v[50:53], v[170:173], v[210:213], v[50:53]
	v_mfma_f32_16x16x32_bf16 v[46:49], v[178:181], v[210:213], v[46:49]
	v_mfma_f32_16x16x32_bf16 v[34:37], v[170:173], v[218:221], v[34:37]
	v_mfma_f32_16x16x32_bf16 v[30:33], v[178:181], v[218:221], v[30:33]
	v_mfma_f32_16x16x32_bf16 v[18:21], v[170:173], v[226:229], v[18:21]
	v_mfma_f32_16x16x32_bf16 v[14:17], v[178:181], v[226:229], v[14:17]
	v_mfma_f32_16x16x32_bf16 v[66:69], v[174:177], v[206:209], v[66:69]
	v_mfma_f32_16x16x32_bf16 v[62:65], v[182:185], v[206:209], v[62:65]
	v_mfma_f32_16x16x32_bf16 v[50:53], v[174:177], v[214:217], v[50:53]
	v_mfma_f32_16x16x32_bf16 v[46:49], v[182:185], v[214:217], v[46:49]
	v_mfma_f32_16x16x32_bf16 v[34:37], v[174:177], v[222:225], v[34:37]
	v_mfma_f32_16x16x32_bf16 v[30:33], v[182:185], v[222:225], v[30:33]
	v_mfma_f32_16x16x32_bf16 v[18:21], v[174:177], v[230:233], v[18:21]
	v_mfma_f32_16x16x32_bf16 v[14:17], v[182:185], v[230:233], v[14:17]
	s_setprio 0
	s_setprio 1
	v_mfma_f32_16x16x32_bf16 v[58:61], v[186:189], v[202:205], v[58:61]
	v_mfma_f32_16x16x32_bf16 v[54:57], v[194:197], v[202:205], v[54:57]
	v_mfma_f32_16x16x32_bf16 v[42:45], v[186:189], v[210:213], v[42:45]
	v_mfma_f32_16x16x32_bf16 v[38:41], v[194:197], v[210:213], v[38:41]
	v_mfma_f32_16x16x32_bf16 v[26:29], v[186:189], v[218:221], v[26:29]
	v_mfma_f32_16x16x32_bf16 v[22:25], v[194:197], v[218:221], v[22:25]
	v_mfma_f32_16x16x32_bf16 v[8:11], v[186:189], v[226:229], v[10:13]
	v_mfma_f32_16x16x32_bf16 v[4:7], v[194:197], v[226:229], v[4:7]
	v_mfma_f32_16x16x32_bf16 v[58:61], v[190:193], v[206:209], v[58:61]
	v_mfma_f32_16x16x32_bf16 v[54:57], v[198:201], v[206:209], v[54:57]
	v_mfma_f32_16x16x32_bf16 v[42:45], v[190:193], v[214:217], v[42:45]
	v_mfma_f32_16x16x32_bf16 v[38:41], v[198:201], v[214:217], v[38:41]
	v_mfma_f32_16x16x32_bf16 v[26:29], v[190:193], v[222:225], v[26:29]
	v_mfma_f32_16x16x32_bf16 v[22:25], v[198:201], v[222:225], v[22:25]
	v_mfma_f32_16x16x32_bf16 v[10:13], v[190:193], v[230:233], v[8:11]
	v_mfma_f32_16x16x32_bf16 v[6:9], v[198:201], v[230:233], v[4:7]
	s_setprio 0
	s_barrier
	s_cmp_lt_i32 s87, 22
	s_cbranch_scc1 .LBB0_415
	s_cmp_eq_u32 s87, 22
	s_cselect_b64 s[44:45], -1, 0
	s_cbranch_execz .LBB0_416
	s_branch .LBB0_417

; #define PG8_STAGE(bufoff, gbase, voff) do { _Pragma("unroll") for (int _i = 0; _i < 2; ++_i) \
;         __builtin_amdgcn_global_load_lds((const unsigned*)((const char*)(gbase) + (voff)[_i]), (PG8_LAS unsigned*)(lds + (bufoff) + ldsw + _i * 8192), 16, 0, 0); } while (0)
; #define PG8_LDA(dst, b, h) do { _Pragma("unroll") for (int m = 0; m < 4; ++m) _Pragma("unroll") for (int k = 0; k < 2; ++k) dst[m][k] = *(const PG8_LAS bf16x8*)(lds + PG8_SA(b, h) + aoff + m * 2048 + k * 1024); } while (0)
; #define PG8_LDB(dst, b, h) do { _Pragma("unroll") for (int n = 0; n < 2; ++n) _Pragma("unroll") for (int k = 0; k < 2; ++k) dst[n][k] = *(const PG8_LAS bf16x8*)(lds + PG8_SB(b, h) + boff + n * 2048 + k * 1024); } while (0)
; #define PG8_MMA(ai, bj, At, Bt) do { __builtin_amdgcn_s_setprio(1); _Pragma("unroll") for (int m = 0; m < 4; ++m) _Pragma("unroll") for (int n = 0; n < 2; ++n) _Pragma("unroll") for (int k = 0; k < 2; ++k) \
;         acc[ai][bj][m][n] = __builtin_amdgcn_mfma_f32_16x16x32_bf16(Bt[n][k], At[m][k], acc[ai][bj][m][n], 0, 0, 0); __builtin_amdgcn_s_setprio(0); } while (0)
; #define PG8_WAIT_V(n) asm volatile("s_waitcnt vmcnt(" #n ")" ::: "memory")
; #define PG8_WAIT_L(n) asm volatile("s_waitcnt lgkmcnt(" #n ")" ::: "memory")
; #define PG8_BAR __builtin_amdgcn_s_barrier()
; #define PG8_SCHED __builtin_amdgcn_sched_barrier(0)
; template <class Epi, class Sched, bool ALIGN_EPI = false, bool SP2 = false, bool KSEG = false>
; __device__ __forceinline__ void gemm_phase(PG8_LAS unsigned char* lds, const Gemm g, const Sched& S, const Epi& E) {
;     ...
;             PG8_LDB(B0, 0, 0); PG8_LDB(B1, 0, 1); PG8_SCHED; PG8_LDA(At, 0, 0); PG8_STAGE(PG8_SA(1, 1), a1 + hstep, voffA);
;             PG8_WAIT_V(8); PG8_WAIT_L(0); PG8_BAR; PG8_MMA(0, 0, At, B0); PG8_MMA(0, 1, At, B1); PG8_BAR; PG8_SCHED;
;             PG8_LDA(At, 0, 1); PG8_STAGE(PG8_SB(0, 0), b2, voffB); PG8_STAGE(PG8_SB(0, 1), b2 + hstep, voffB); PG8_STAGE(PG8_SA(0, 0), a2, voffA);
;             PG8_WAIT_V(8); PG8_WAIT_L(0); PG8_BAR; PG8_MMA(1, 0, At, B0); PG8_MMA(1, 1, At, B1); PG8_BAR; PG8_SCHED;
;             PG8_LDB(B0, 1, 0); PG8_LDB(B1, 1, 1); PG8_SCHED; PG8_LDA(At, 1, 0); PG8_STAGE(PG8_SA(0, 1), a2 + hstep, voffA);
;             PG8_WAIT_V(8); PG8_WAIT_L(0); PG8_BAR; PG8_MMA(0, 0, At, B0); PG8_MMA(0, 1, At, B1); PG8_BAR; PG8_SCHED;
.LBB0_497:
	ds_read_b128 v[148:151], v168
	ds_read_b128 v[172:175], v168 offset:1024
	ds_read_b128 v[176:179], v168 offset:2048
	ds_read_b128 v[180:183], v168 offset:3072
	ds_read_b128 v[184:187], v169
	ds_read_b128 v[188:191], v169 offset:1024
	ds_read_b128 v[192:195], v169 offset:2048
	ds_read_b128 v[196:199], v169 offset:3072
	s_add_u32 s33, s36, 0xfff80080
	s_addc_u32 s38, s37, -1
	s_cmp_eq_u32 s62, 28
	s_cselect_b32 s41, s25, s38
	s_cselect_b32 s40, s58, s33
	s_cselect_b32 s39, s23, s61
	s_cselect_b32 s38, s59, s60
	s_add_u32 s98, s36, 0xfff80000
	s_addc_u32 s99, s37, -1
	s_mov_b32 m0, s52
	v_lshl_add_u64 v[232:233], s[98:99], 0, v[132:133]
	global_load_lds_dwordx4 v[232:233], off
	s_mov_b32 m0, s53
	v_lshl_add_u64 v[232:233], s[98:99], 0, v[136:137]
	global_load_lds_dwordx4 v[232:233], off
	v_lshl_add_u64 v[232:233], s[36:37], 0, v[140:141]
	s_add_i32 m0, s31, 0xc000
	ds_read_b128 v[200:203], v170
	ds_read_b128 v[204:207], v170 offset:1024
	ds_read_b128 v[208:211], v170 offset:2048
	ds_read_b128 v[212:215], v170 offset:3072
	ds_read_b128 v[216:219], v170 offset:4096
	ds_read_b128 v[220:223], v170 offset:5120
	ds_read_b128 v[224:227], v170 offset:6144
	ds_read_b128 v[228:231], v170 offset:7168
	global_load_lds_dwordx4 v[232:233], off
	s_add_i32 m0, s31, 0xe000
	v_lshl_add_u64 v[232:233], s[36:37], 0, v[142:143]
	global_load_lds_dwordx4 v[232:233], off
	s_waitcnt vmcnt(8) lgkmcnt(0)
	s_barrier
	s_setprio 1
	v_mfma_f32_16x16x32_bf16 v[126:129], v[148:151], v[200:203], v[126:129]
	v_mfma_f32_16x16x32_bf16 v[122:125], v[176:179], v[200:203], v[122:125]
	v_mfma_f32_16x16x32_bf16 v[110:113], v[148:151], v[208:211], v[110:113]
	v_mfma_f32_16x16x32_bf16 v[106:109], v[176:179], v[208:211], v[106:109]
	v_mfma_f32_16x16x32_bf16 v[94:97], v[148:151], v[216:219], v[94:97]
	v_mfma_f32_16x16x32_bf16 v[90:93], v[176:179], v[216:219], v[90:93]
	v_mfma_f32_16x16x32_bf16 v[78:81], v[148:151], v[224:227], v[78:81]
	v_mfma_f32_16x16x32_bf16 v[74:77], v[176:179], v[224:227], v[74:77]
	v_mfma_f32_16x16x32_bf16 v[126:129], v[172:175], v[204:207], v[126:129]
	v_mfma_f32_16x16x32_bf16 v[122:125], v[180:183], v[204:207], v[122:125]
	v_mfma_f32_16x16x32_bf16 v[110:113], v[172:175], v[212:215], v[110:113]
	v_mfma_f32_16x16x32_bf16 v[106:109], v[180:183], v[212:215], v[106:109]
	v_mfma_f32_16x16x32_bf16 v[94:97], v[172:175], v[220:223], v[94:97]
	v_mfma_f32_16x16x32_bf16 v[90:93], v[180:183], v[220:223], v[90:93]
	v_mfma_f32_16x16x32_bf16 v[78:81], v[172:175], v[228:231], v[78:81]
	v_mfma_f32_16x16x32_bf16 v[74:77], v[180:183], v[228:231], v[74:77]
	s_setprio 0
	s_setprio 1
	v_mfma_f32_16x16x32_bf16 v[118:121], v[184:187], v[200:203], v[118:121]
	v_mfma_f32_16x16x32_bf16 v[114:117], v[192:195], v[200:203], v[114:117]
	v_mfma_f32_16x16x32_bf16 v[102:105], v[184:187], v[208:211], v[102:105]
	v_mfma_f32_16x16x32_bf16 v[98:101], v[192:195], v[208:211], v[98:101]
	v_mfma_f32_16x16x32_bf16 v[86:89], v[184:187], v[216:219], v[86:89]
	v_mfma_f32_16x16x32_bf16 v[82:85], v[192:195], v[216:219], v[82:85]
	v_mfma_f32_16x16x32_bf16 v[70:73], v[184:187], v[224:227], v[70:73]
	v_mfma_f32_16x16x32_bf16 v[66:69], v[192:195], v[224:227], v[66:69]
	v_mfma_f32_16x16x32_bf16 v[118:121], v[188:191], v[204:207], v[118:121]
	v_mfma_f32_16x16x32_bf16 v[114:117], v[196:199], v[204:207], v[114:117]
	v_mfma_f32_16x16x32_bf16 v[102:105], v[188:191], v[212:215], v[102:105]
	v_mfma_f32_16x16x32_bf16 v[98:101], v[196:199], v[212:215], v[98:101]
	v_mfma_f32_16x16x32_bf16 v[86:89], v[188:191], v[220:223], v[86:89]
	v_mfma_f32_16x16x32_bf16 v[82:85], v[196:199], v[220:223], v[82:85]
	v_mfma_f32_16x16x32_bf16 v[70:73], v[188:191], v[228:231], v[70:73]
	v_mfma_f32_16x16x32_bf16 v[66:69], v[196:199], v[228:231], v[66:69]
	s_setprio 0
	s_barrier
	s_add_i32 s33, s54, s43
	v_lshl_add_u64 v[232:233], s[38:39], 0, v[134:135]
	s_mov_b32 m0, s33
	ds_read_b128 v[200:203], v170 offset:16384
	ds_read_b128 v[204:207], v170 offset:17408
	ds_read_b128 v[208:211], v170 offset:18432
	ds_read_b128 v[212:215], v170 offset:19456
	ds_read_b128 v[216:219], v170 offset:20480
	ds_read_b128 v[220:223], v170 offset:21504
	ds_read_b128 v[224:227], v170 offset:22528
	ds_read_b128 v[228:231], v170 offset:23552
	global_load_lds_dwordx4 v[232:233], off
	s_add_i32 m0, s33, 0x2000
	s_add_u32 s64, s38, 0x80000
	v_lshl_add_u64 v[234:235], s[38:39], 0, v[138:139]
	s_addc_u32 s65, s39, 0
	s_add_i32 s33, s55, s43
	global_load_lds_dwordx4 v[234:235], off
	s_mov_b32 m0, s33
	v_lshl_add_u64 v[236:237], s[64:65], 0, v[134:135]
	global_load_lds_dwordx4 v[236:237], off
	s_add_i32 m0, s33, 0x2000
	v_lshl_add_u64 v[236:237], s[64:65], 0, v[138:139]
	global_load_lds_dwordx4 v[236:237], off
	s_waitcnt vmcnt(6) lgkmcnt(0)
	s_barrier
; #define PG8_STAGE(bufoff, gbase, voff) do { _Pragma("unroll") for (int _i = 0; _i < 2; ++_i) \
;         __builtin_amdgcn_global_load_lds((const unsigned*)((const char*)(gbase) + (voff)[_i]), (PG8_LAS unsigned*)(lds + (bufoff) + ldsw + _i * 8192), 16, 0, 0); } while (0)
; #define PG8_LDA(dst, b, h) do { _Pragma("unroll") for (int m = 0; m < 4; ++m) _Pragma("unroll") for (int k = 0; k < 2; ++k) dst[m][k] = *(const PG8_LAS bf16x8*)(lds + PG8_SA(b, h) + aoff + m * 2048 + k * 1024); } while (0)
; #define PG8_LDB(dst, b, h) do { _Pragma("unroll") for (int n = 0; n < 2; ++n) _Pragma("unroll") for (int k = 0; k < 2; ++k) dst[n][k] = *(const PG8_LAS bf16x8*)(lds + PG8_SB(b, h) + boff + n * 2048 + k * 1024); } while (0)
; #define PG8_MMA(ai, bj, At, Bt) do { __builtin_amdgcn_s_setprio(1); _Pragma("unroll") for (int m = 0; m < 4; ++m) _Pragma("unroll") for (int n = 0; n < 2; ++n) _Pragma("unroll") for (int k = 0; k < 2; ++k) \
;         acc[ai][bj][m][n] = __builtin_amdgcn_mfma_f32_16x16x32_bf16(Bt[n][k], At[m][k], acc[ai][bj][m][n], 0, 0, 0); __builtin_amdgcn_s_setprio(0); } while (0)
; #define PG8_WAIT_V(n) asm volatile("s_waitcnt vmcnt(" #n ")" ::: "memory")
; #define PG8_WAIT_L(n) asm volatile("s_waitcnt lgkmcnt(" #n ")" ::: "memory")
; #define PG8_BAR __builtin_amdgcn_s_barrier()
; #define PG8_SCHED __builtin_amdgcn_sched_barrier(0)
; template <class Epi, class Sched, bool ALIGN_EPI = false, bool SP2 = false, bool KSEG = false>
; __device__ __forceinline__ void gemm_phase(PG8_LAS unsigned char* lds, const Gemm g, const Sched& S, const Epi& E) {
;     ...
;             PG8_WAIT_V(8); PG8_WAIT_L(0); PG8_BAR; PG8_MMA(1, 0, At, B0); PG8_MMA(1, 1, At, B1); PG8_BAR; PG8_SCHED;
;             PG8_LDB(B0, 1, 0); PG8_LDB(B1, 1, 1); PG8_SCHED; PG8_LDA(At, 1, 0); PG8_STAGE(PG8_SA(0, 1), a2 + hstep, voffA);
;             PG8_WAIT_V(8); PG8_WAIT_L(0); PG8_BAR; PG8_MMA(0, 0, At, B0); PG8_MMA(0, 1, At, B1); PG8_BAR; PG8_SCHED;
	s_setprio 1
	v_mfma_f32_16x16x32_bf16 v[62:65], v[148:151], v[200:203], v[62:65]
	v_mfma_f32_16x16x32_bf16 v[58:61], v[176:179], v[200:203], v[58:61]
	v_mfma_f32_16x16x32_bf16 v[46:49], v[148:151], v[208:211], v[46:49]
	v_mfma_f32_16x16x32_bf16 v[42:45], v[176:179], v[208:211], v[42:45]
	v_mfma_f32_16x16x32_bf16 v[30:33], v[148:151], v[216:219], v[30:33]
	v_mfma_f32_16x16x32_bf16 v[26:29], v[176:179], v[216:219], v[26:29]
	v_mfma_f32_16x16x32_bf16 v[14:17], v[148:151], v[224:227], v[14:17]
	v_mfma_f32_16x16x32_bf16 v[10:13], v[176:179], v[224:227], v[10:13]
	v_mfma_f32_16x16x32_bf16 v[62:65], v[172:175], v[204:207], v[62:65]
	v_mfma_f32_16x16x32_bf16 v[58:61], v[180:183], v[204:207], v[58:61]
	v_mfma_f32_16x16x32_bf16 v[46:49], v[172:175], v[212:215], v[46:49]
	v_mfma_f32_16x16x32_bf16 v[42:45], v[180:183], v[212:215], v[42:45]
	v_mfma_f32_16x16x32_bf16 v[30:33], v[172:175], v[220:223], v[30:33]
	v_mfma_f32_16x16x32_bf16 v[26:29], v[180:183], v[220:223], v[26:29]
	v_mfma_f32_16x16x32_bf16 v[14:17], v[172:175], v[228:231], v[14:17]
	v_mfma_f32_16x16x32_bf16 v[10:13], v[180:183], v[228:231], v[10:13]
	s_setprio 0
	s_setprio 1
	v_mfma_f32_16x16x32_bf16 v[54:57], v[184:187], v[200:203], v[54:57]
	v_mfma_f32_16x16x32_bf16 v[50:53], v[192:195], v[200:203], v[50:53]
	v_mfma_f32_16x16x32_bf16 v[38:41], v[184:187], v[208:211], v[38:41]
	v_mfma_f32_16x16x32_bf16 v[34:37], v[192:195], v[208:211], v[34:37]
	v_mfma_f32_16x16x32_bf16 v[22:25], v[184:187], v[216:219], v[22:25]
	v_mfma_f32_16x16x32_bf16 v[18:21], v[192:195], v[216:219], v[18:21]
	v_mfma_f32_16x16x32_bf16 v[6:9], v[184:187], v[224:227], v[6:9]
	v_mfma_f32_16x16x32_bf16 v[2:5], v[192:195], v[224:227], v[2:5]
	v_mfma_f32_16x16x32_bf16 v[54:57], v[188:191], v[204:207], v[54:57]
	v_mfma_f32_16x16x32_bf16 v[50:53], v[196:199], v[204:207], v[50:53]
	v_mfma_f32_16x16x32_bf16 v[38:41], v[188:191], v[212:215], v[38:41]
	v_mfma_f32_16x16x32_bf16 v[34:37], v[196:199], v[212:215], v[34:37]
	v_mfma_f32_16x16x32_bf16 v[22:25], v[188:191], v[220:223], v[22:25]
	v_mfma_f32_16x16x32_bf16 v[18:21], v[196:199], v[220:223], v[18:21]
	v_mfma_f32_16x16x32_bf16 v[6:9], v[188:191], v[228:231], v[6:9]
	v_mfma_f32_16x16x32_bf16 v[2:5], v[196:199], v[228:231], v[2:5]
	s_setprio 0
	s_barrier
	s_add_i32 s33, 0, 0x18000
	s_add_i32 s63, 0, 0x1c000
	v_add_u32_e32 v180, s33, v166
	v_add_u32_e32 v196, s63, v166
	ds_read_b128 v[148:151], v180
	ds_read_b128 v[172:175], v180 offset:1024
	ds_read_b128 v[176:179], v180 offset:2048
	ds_read_b128 v[180:183], v180 offset:3072
	ds_read_b128 v[184:187], v196
	ds_read_b128 v[188:191], v196 offset:1024
	ds_read_b128 v[192:195], v196 offset:2048
	ds_read_b128 v[196:199], v196 offset:3072
	s_mov_b32 m0, s31
	v_lshl_add_u64 v[240:241], s[40:41], 0, v[132:133]
	global_load_lds_dwordx4 v[240:241], off
	s_mov_b32 m0, s45
	v_lshl_add_u64 v[240:241], s[40:41], 0, v[136:137]
	global_load_lds_dwordx4 v[240:241], off
	s_add_u32 s40, s40, 0x80000
	s_addc_u32 s41, s41, 0
	s_mov_b32 m0, s49
	v_lshl_add_u64 v[240:241], s[40:41], 0, v[132:133]
	ds_read_b128 v[200:203], v170 offset:32768
	ds_read_b128 v[204:207], v170 offset:33792
	ds_read_b128 v[208:211], v170 offset:34816
	ds_read_b128 v[212:215], v170 offset:35840
	ds_read_b128 v[216:219], v170 offset:36864
	ds_read_b128 v[220:223], v170 offset:37888
	ds_read_b128 v[224:227], v170 offset:38912
	ds_read_b128 v[228:231], v170 offset:39936
	global_load_lds_dwordx4 v[240:241], off
	s_mov_b32 m0, s50
	v_lshl_add_u64 v[240:241], s[40:41], 0, v[136:137]
	global_load_lds_dwordx4 v[240:241], off
	s_waitcnt vmcnt(8) lgkmcnt(0)
	s_barrier
	s_setprio 1
	v_mfma_f32_16x16x32_bf16 v[126:129], v[148:151], v[200:203], v[126:129]
	v_mfma_f32_16x16x32_bf16 v[122:125], v[176:179], v[200:203], v[122:125]
	v_mfma_f32_16x16x32_bf16 v[110:113], v[148:151], v[208:211], v[110:113]
	v_mfma_f32_16x16x32_bf16 v[106:109], v[176:179], v[208:211], v[106:109]
	v_mfma_f32_16x16x32_bf16 v[94:97], v[148:151], v[216:219], v[94:97]
	v_mfma_f32_16x16x32_bf16 v[90:93], v[176:179], v[216:219], v[90:93]
	v_mfma_f32_16x16x32_bf16 v[78:81], v[148:151], v[224:227], v[78:81]
	v_mfma_f32_16x16x32_bf16 v[74:77], v[176:179], v[224:227], v[74:77]
	v_mfma_f32_16x16x32_bf16 v[126:129], v[172:175], v[204:207], v[126:129]
	v_mfma_f32_16x16x32_bf16 v[122:125], v[180:183], v[204:207], v[122:125]
	v_mfma_f32_16x16x32_bf16 v[110:113], v[172:175], v[212:215], v[110:113]
	v_mfma_f32_16x16x32_bf16 v[106:109], v[180:183], v[212:215], v[106:109]
	v_mfma_f32_16x16x32_bf16 v[94:97], v[172:175], v[220:223], v[94:97]
	v_mfma_f32_16x16x32_bf16 v[90:93], v[180:183], v[220:223], v[90:93]
	v_mfma_f32_16x16x32_bf16 v[78:81], v[172:175], v[228:231], v[78:81]
	v_mfma_f32_16x16x32_bf16 v[74:77], v[180:183], v[228:231], v[74:77]
	s_setprio 0
	s_setprio 1
	v_mfma_f32_16x16x32_bf16 v[118:121], v[184:187], v[200:203], v[118:121]
	v_mfma_f32_16x16x32_bf16 v[114:117], v[192:195], v[200:203], v[114:117]
	v_mfma_f32_16x16x32_bf16 v[102:105], v[184:187], v[208:211], v[102:105]
	v_mfma_f32_16x16x32_bf16 v[98:101], v[192:195], v[208:211], v[98:101]
	v_mfma_f32_16x16x32_bf16 v[86:89], v[184:187], v[216:219], v[86:89]
	v_mfma_f32_16x16x32_bf16 v[82:85], v[192:195], v[216:219], v[82:85]
	v_mfma_f32_16x16x32_bf16 v[70:73], v[184:187], v[224:227], v[70:73]
	v_mfma_f32_16x16x32_bf16 v[66:69], v[192:195], v[224:227], v[66:69]
	v_mfma_f32_16x16x32_bf16 v[118:121], v[188:191], v[204:207], v[118:121]
	v_mfma_f32_16x16x32_bf16 v[114:117], v[196:199], v[204:207], v[114:117]
	v_mfma_f32_16x16x32_bf16 v[102:105], v[188:191], v[212:215], v[102:105]
	v_mfma_f32_16x16x32_bf16 v[98:101], v[196:199], v[212:215], v[98:101]
	v_mfma_f32_16x16x32_bf16 v[86:89], v[188:191], v[220:223], v[86:89]
	v_mfma_f32_16x16x32_bf16 v[82:85], v[196:199], v[220:223], v[82:85]
	v_mfma_f32_16x16x32_bf16 v[70:73], v[188:191], v[228:231], v[70:73]
	v_mfma_f32_16x16x32_bf16 v[66:69], v[196:199], v[228:231], v[66:69]
	s_setprio 0
	s_barrier
; #define PG8_STAGE(bufoff, gbase, voff) do { _Pragma("unroll") for (int _i = 0; _i < 2; ++_i) \
;         __builtin_amdgcn_global_load_lds((const unsigned*)((const char*)(gbase) + (voff)[_i]), (PG8_LAS unsigned*)(lds + (bufoff) + ldsw + _i * 8192), 16, 0, 0); } while (0)
; #define PG8_LDA(dst, b, h) do { _Pragma("unroll") for (int m = 0; m < 4; ++m) _Pragma("unroll") for (int k = 0; k < 2; ++k) dst[m][k] = *(const PG8_LAS bf16x8*)(lds + PG8_SA(b, h) + aoff + m * 2048 + k * 1024); } while (0)
; #define PG8_MMA(ai, bj, At, Bt) do { __builtin_amdgcn_s_setprio(1); _Pragma("unroll") for (int m = 0; m < 4; ++m) _Pragma("unroll") for (int n = 0; n < 2; ++n) _Pragma("unroll") for (int k = 0; k < 2; ++k) \
;         acc[ai][bj][m][n] = __builtin_amdgcn_mfma_f32_16x16x32_bf16(Bt[n][k], At[m][k], acc[ai][bj][m][n], 0, 0, 0); __builtin_amdgcn_s_setprio(0); } while (0)
; #define PG8_WAIT_V(n) asm volatile("s_waitcnt vmcnt(" #n ")" ::: "memory")
; #define PG8_WAIT_L(n) asm volatile("s_waitcnt lgkmcnt(" #n ")" ::: "memory")
; #define PG8_BAR __builtin_amdgcn_s_barrier()
; #define PG8_SCHED __builtin_amdgcn_sched_barrier(0)
; template <class Epi, class Sched, bool ALIGN_EPI = false, bool SP2 = false, bool KSEG = false>
; __device__ __forceinline__ void gemm_phase(PG8_LAS unsigned char* lds, const Gemm g, const Sched& S, const Epi& E) {
;     ...
;             PG8_LDA(At, 1, 1); PG8_STAGE(PG8_SB(1, 0), b3, voffB); PG8_STAGE(PG8_SB(1, 1), b3 + hstep, voffB); PG8_STAGE(PG8_SA(1, 0), a3, voffA);
;             PG8_WAIT_V(8); PG8_WAIT_L(0); PG8_BAR; PG8_MMA(1, 0, At, B0); PG8_MMA(1, 1, At, B1); PG8_BAR; PG8_SCHED;
;     __device__ __forceinline__ void operator()(const f32x4 (&acc)[2][2][4][2], const Unit& u, int wr, int wc, int fr, int fq) const {
;         const int row0 = u.pm * BM + wr * 64 + fr, col0 = u.pn * HALF + wc * 32 + 8 * fq;
; #pragma unroll
;         for (int ai = 0; ai < 2; ++ai)
; #pragma unroll
;             for (int m = 0; m < 4; ++m) { const int row = row0 + ai * HALF + m * 16; const float rs = __builtin_amdgcn_rsqf(ss[row_base + row] * (1.0f / 2048.0f) + 1e-6f);
;                 float a[8];
	s_add_i32 s33, s33, s43
	v_lshl_add_u64 v[232:233], v[232:233], 0, s[10:11]
	s_mov_b32 m0, s33
	ds_read_b128 v[200:203], v170 offset:49152
	ds_read_b128 v[204:207], v170 offset:50176
	ds_read_b128 v[208:211], v170 offset:51200
	ds_read_b128 v[212:215], v170 offset:52224
	ds_read_b128 v[216:219], v170 offset:53248
	ds_read_b128 v[220:223], v170 offset:54272
	ds_read_b128 v[224:227], v170 offset:55296
	ds_read_b128 v[228:231], v170 offset:56320
	global_load_lds_dwordx4 v[232:233], off
	s_add_i32 m0, s33, 0x2000
	s_add_u32 s38, s38, 0x80080
	v_lshl_add_u64 v[232:233], v[234:235], 0, s[10:11]
	s_addc_u32 s39, s39, 0
	s_add_i32 s33, s63, s43
	global_load_lds_dwordx4 v[232:233], off
	s_mov_b32 m0, s33
	v_lshl_add_u64 v[232:233], s[38:39], 0, v[134:135]
	global_load_lds_dwordx4 v[232:233], off
	s_add_i32 m0, s33, 0x2000
	v_lshl_add_u64 v[232:233], s[38:39], 0, v[138:139]
	global_load_lds_dwordx4 v[232:233], off
	s_waitcnt vmcnt(6) lgkmcnt(0)
	s_barrier
	s_setprio 1
	v_mfma_f32_16x16x32_bf16 v[62:65], v[148:151], v[200:203], v[62:65]
	v_mfma_f32_16x16x32_bf16 v[58:61], v[176:179], v[200:203], v[58:61]
	v_mfma_f32_16x16x32_bf16 v[46:49], v[148:151], v[208:211], v[46:49]
	v_mfma_f32_16x16x32_bf16 v[42:45], v[176:179], v[208:211], v[42:45]
	v_mfma_f32_16x16x32_bf16 v[30:33], v[148:151], v[216:219], v[30:33]
	v_mfma_f32_16x16x32_bf16 v[26:29], v[176:179], v[216:219], v[26:29]
	v_mfma_f32_16x16x32_bf16 v[14:17], v[148:151], v[224:227], v[14:17]
	v_mfma_f32_16x16x32_bf16 v[10:13], v[176:179], v[224:227], v[10:13]
	v_mfma_f32_16x16x32_bf16 v[62:65], v[172:175], v[204:207], v[62:65]
	v_mfma_f32_16x16x32_bf16 v[58:61], v[180:183], v[204:207], v[58:61]
	v_mfma_f32_16x16x32_bf16 v[46:49], v[172:175], v[212:215], v[46:49]
	v_mfma_f32_16x16x32_bf16 v[42:45], v[180:183], v[212:215], v[42:45]
	v_mfma_f32_16x16x32_bf16 v[30:33], v[172:175], v[220:223], v[30:33]
	v_mfma_f32_16x16x32_bf16 v[26:29], v[180:183], v[220:223], v[26:29]
	v_mfma_f32_16x16x32_bf16 v[14:17], v[172:175], v[228:231], v[14:17]
	v_mfma_f32_16x16x32_bf16 v[10:13], v[180:183], v[228:231], v[10:13]
	s_setprio 0
	s_setprio 1
	v_mfma_f32_16x16x32_bf16 v[54:57], v[184:187], v[200:203], v[54:57]
	v_mfma_f32_16x16x32_bf16 v[50:53], v[192:195], v[200:203], v[50:53]
	v_mfma_f32_16x16x32_bf16 v[38:41], v[184:187], v[208:211], v[38:41]
	v_mfma_f32_16x16x32_bf16 v[34:37], v[192:195], v[208:211], v[34:37]
	v_mfma_f32_16x16x32_bf16 v[22:25], v[184:187], v[216:219], v[22:25]
	v_mfma_f32_16x16x32_bf16 v[18:21], v[192:195], v[216:219], v[18:21]
	v_mfma_f32_16x16x32_bf16 v[6:9], v[184:187], v[224:227], v[6:9]
	v_mfma_f32_16x16x32_bf16 v[2:5], v[192:195], v[224:227], v[2:5]
	v_mfma_f32_16x16x32_bf16 v[54:57], v[188:191], v[204:207], v[54:57]
	v_mfma_f32_16x16x32_bf16 v[50:53], v[196:199], v[204:207], v[50:53]
	v_mfma_f32_16x16x32_bf16 v[38:41], v[188:191], v[212:215], v[38:41]
	v_mfma_f32_16x16x32_bf16 v[34:37], v[196:199], v[212:215], v[34:37]
	v_mfma_f32_16x16x32_bf16 v[22:25], v[188:191], v[220:223], v[22:25]
	v_mfma_f32_16x16x32_bf16 v[18:21], v[196:199], v[220:223], v[18:21]
	v_mfma_f32_16x16x32_bf16 v[6:9], v[188:191], v[228:231], v[6:9]
	v_mfma_f32_16x16x32_bf16 v[2:5], v[196:199], v[228:231], v[2:5]
	s_setprio 0
	s_barrier
	s_add_i32 s62, s62, 2
	s_add_u32 s36, s36, 0x100
	s_addc_u32 s37, s37, 0
	s_add_u32 s60, s60, 0x100
	s_addc_u32 s61, s61, 0
	s_cmp_gt_u32 s62, 29
	s_cbranch_scc0 .LBB0_497
	s_and_b64 vcc, exec, s[12:13]
	s_cbranch_vccz .LBB0_500
	s_barrier
.LBB0_500:
	v_lshl_add_u32 v148, s30, 8, v165
	v_ashrrev_i32_e32 v149, 31, v148
	v_lshl_add_u64 v[150:151], v[148:149], 2, s[18:19]
	global_load_dword v149, v[150:151], off
	global_load_dword v243, v[150:151], off offset:64
	global_load_dword v244, v[150:151], off offset:128
	global_load_dword v245, v[150:151], off offset:192
	global_load_dword v246, v[150:151], off offset:512
	global_load_dword v247, v[150:151], off offset:576
	global_load_dword v248, v[150:151], off offset:640
	global_load_dword v249, v[150:151], off offset:704
	v_lshl_or_b32 v172, s57, 7, v167
	v_ashrrev_i32_e32 v173, 31, v172
	v_mov_b32_e32 v176, v124
	v_mov_b32_e32 v177, v116
	v_mov_b32_e32 v116, v125
	v_lshlrev_b64 v[124:125], 1, v[172:173]
	v_mov_b32_e32 v174, v126
	v_mov_b32_e32 v175, v118
	v_mov_b32_e32 v118, v127
	v_mov_b32_e32 v126, v128
	v_mov_b32_e32 v127, v120
	v_mov_b32_e32 v120, v129
	v_mov_b32_e32 v128, v122
	v_mov_b32_e32 v129, v114
	v_mov_b32_e32 v114, v123
	v_mov_b64_e32 v[122:123], s[74:75]
	v_mad_i64_i32 v[178:179], s[36:37], v148, s56, v[122:123]
	v_or_b32_e32 v180, 16, v148
	v_ashrrev_i32_e32 v181, 31, v180
	v_lshl_add_u64 v[178:179], v[178:179], 0, v[124:125]
	v_lshl_add_u64 v[182:183], v[180:181], 2, s[18:19]
	s_andn2_b64 vcc, exec, s[4:5]
	s_mov_b64 s[4:5], -1
	s_waitcnt vmcnt(0)
; __device__ __forceinline__ unsigned cvt_pk_bf16(float lo, float hi) { unsigned r; asm volatile("v_cvt_pk_bf16_f32 %0, %1, %2" : "=v"(r) : "v"(lo), "v"(hi)); return r; }
;     __device__ __forceinline__ void operator()(const f32x4 (&acc)[2][2][4][2], const Unit& u, int wr, int wc, int fr, int fq) const {
;     ...
;             for (int m = 0; m < 4; ++m) { const int row = row0 + ai * HALF + m * 16; const float rs = __builtin_amdgcn_rsqf(ss[row_base + row] * (1.0f / 2048.0f) + 1e-6f);
;                 float a[8];
; #pragma unroll
;                 for (int n = 0; n < 2; ++n)
; #pragma unroll
;                     for (int j = 0; j < 4; ++j) { const float g = acc[ai][0][m][n][j] * rs, uu = acc[ai][1][m][n][j] * rs;
;                         a[n * 4 + j] = g * uu * __builtin_amdgcn_rcpf(1.0f + __builtin_amdgcn_exp2f(-1.4426950408889634f * g)); }
;                 u32x4 w; w.x = cvt_pk_bf16(a[0], a[1]); w.y = cvt_pk_bf16(a[2], a[3]); w.z = cvt_pk_bf16(a[4], a[5]); w.w = cvt_pk_bf16(a[6], a[7]);
;                 *(u32x4*)(act + (size_t)row * 5632 + col0) = w; }
	v_fmamk_f32 v149, v149, 0x3a000000, v171
	v_rsq_f32_e32 v172, v149
	s_nop 0
	v_pk_mul_f32 v[116:117], v[116:117], v[172:173] op_sel_hi:[1,0]
	v_pk_mul_f32 v[174:175], v[174:175], v[172:173] op_sel_hi:[1,0]
	v_pk_mul_f32 v[118:119], v[118:119], v[172:173] op_sel_hi:[1,0]
	v_pk_mul_f32 v[126:127], v[126:127], v[172:173] op_sel_hi:[1,0]
	v_pk_mul_f32 v[120:121], v[120:121], v[172:173] op_sel_hi:[1,0]
	v_pk_mul_f32 v[128:129], v[128:129], v[172:173] op_sel_hi:[1,0]
	v_pk_mul_f32 v[114:115], v[114:115], v[172:173] op_sel_hi:[1,0]
	v_pk_mul_f32 v[176:177], v[176:177], v[172:173] op_sel_hi:[1,0]
	v_mul_f32_e32 v117, v116, v117
	v_mul_f32_e32 v116, 0xbfb8aa3b, v116
	v_mul_f32_e32 v149, v174, v175
	v_mul_f32_e32 v172, 0xbfb8aa3b, v174
	v_mul_f32_e32 v119, v118, v119
	v_mul_f32_e32 v118, 0xbfb8aa3b, v118
	v_mul_f32_e32 v127, v126, v127
	v_mul_f32_e32 v126, 0xbfb8aa3b, v126
	v_mul_f32_e32 v121, v120, v121
	v_mul_f32_e32 v120, 0xbfb8aa3b, v120
	v_mul_f32_e32 v129, v128, v129
	v_mul_f32_e32 v128, 0xbfb8aa3b, v128
	v_mul_f32_e32 v115, v114, v115
	v_mul_f32_e32 v114, 0xbfb8aa3b, v114
	v_mul_f32_e32 v174, 0xbfb8aa3b, v176
	v_exp_f32_e32 v116, v116
	v_exp_f32_e32 v172, v172
	v_exp_f32_e32 v118, v118
	v_exp_f32_e32 v126, v126
	v_exp_f32_e32 v120, v120
	v_exp_f32_e32 v128, v128
	v_exp_f32_e32 v114, v114
	v_exp_f32_e32 v174, v174
	v_add_f32_e32 v116, 1.0, v116
	v_add_f32_e32 v172, 1.0, v172
	v_add_f32_e32 v118, 1.0, v118
	v_add_f32_e32 v126, 1.0, v126
	v_add_f32_e32 v120, 1.0, v120
	v_add_f32_e32 v128, 1.0, v128
	v_add_f32_e32 v114, 1.0, v114
	v_add_f32_e32 v174, 1.0, v174
	v_rcp_f32_e32 v116, v116
	v_rcp_f32_e32 v172, v172
	v_rcp_f32_e32 v118, v118
	v_rcp_f32_e32 v126, v126
	v_rcp_f32_e32 v120, v120
	v_rcp_f32_e32 v128, v128
	v_rcp_f32_e32 v114, v114
	v_rcp_f32_e32 v174, v174
	v_mul_f32_e32 v173, v176, v177
	v_mul_f32_e32 v117, v117, v116
	v_mul_f32_e32 v149, v149, v172
	v_mul_f32_e32 v118, v119, v118
	v_mul_f32_e32 v119, v127, v126
	v_mul_f32_e32 v120, v121, v120
	v_mul_f32_e32 v121, v129, v128
	v_mul_f32_e32 v126, v115, v114
	v_mul_f32_e32 v127, v173, v174
	v_cvt_pk_bf16_f32 v114, v149, v118
	v_cvt_pk_bf16_f32 v115, v119, v120
	v_cvt_pk_bf16_f32 v116, v121, v126
	v_cvt_pk_bf16_f32 v117, v127, v117
	global_store_dwordx4 v[178:179], v[114:117], off
	s_nop 0
	s_nop 0
	v_mov_b32_e32 v115, v102
	v_mov_b32_e32 v102, v111
	v_mov_b32_e32 v111, v104
	v_mov_b32_e32 v104, v113
	v_mov_b32_e32 v113, v98
	v_mov_b32_e32 v98, v107
	v_mov_b32_e32 v107, v100
	v_mov_b32_e32 v100, v109
	v_mov_b32_e32 v114, v110
	v_mov_b32_e32 v110, v112
	v_mov_b32_e32 v112, v106
	v_mov_b32_e32 v106, v108
	v_or_b32_e32 v108, 32, v148
	v_mad_i64_i32 v[116:117], s[36:37], v180, s56, v[122:123]
	v_lshl_add_u64 v[116:117], v[116:117], 0, v[124:125]
	v_fmamk_f32 v109, v243, 0x3a000000, v171
	v_rsq_f32_e32 v118, v109
	v_ashrrev_i32_e32 v109, 31, v108
	v_lshl_add_u64 v[120:121], v[108:109], 2, s[18:19]
	v_pk_mul_f32 v[100:101], v[100:101], v[118:119] op_sel_hi:[1,0]
	v_pk_mul_f32 v[114:115], v[114:115], v[118:119] op_sel_hi:[1,0]
	v_pk_mul_f32 v[102:103], v[102:103], v[118:119] op_sel_hi:[1,0]
	v_pk_mul_f32 v[110:111], v[110:111], v[118:119] op_sel_hi:[1,0]
	v_pk_mul_f32 v[104:105], v[104:105], v[118:119] op_sel_hi:[1,0]
	v_pk_mul_f32 v[112:113], v[112:113], v[118:119] op_sel_hi:[1,0]
	v_pk_mul_f32 v[98:99], v[98:99], v[118:119] op_sel_hi:[1,0]
	v_pk_mul_f32 v[106:107], v[106:107], v[118:119] op_sel_hi:[1,0]
	v_mul_f32_e32 v101, v100, v101
	v_mul_f32_e32 v100, 0xbfb8aa3b, v100
	v_mul_f32_e32 v109, v114, v115
	v_mul_f32_e32 v114, 0xbfb8aa3b, v114
	v_mul_f32_e32 v103, v102, v103
	v_mul_f32_e32 v102, 0xbfb8aa3b, v102
	v_mul_f32_e32 v111, v110, v111
	v_mul_f32_e32 v110, 0xbfb8aa3b, v110
	v_mul_f32_e32 v105, v104, v105
	v_mul_f32_e32 v104, 0xbfb8aa3b, v104
	v_mul_f32_e32 v113, v112, v113
	v_mul_f32_e32 v112, 0xbfb8aa3b, v112
	v_mul_f32_e32 v99, v98, v99
	v_mul_f32_e32 v98, 0xbfb8aa3b, v98
	v_mul_f32_e32 v107, v106, v107
	v_mul_f32_e32 v106, 0xbfb8aa3b, v106
	v_exp_f32_e32 v100, v100
	v_exp_f32_e32 v114, v114
	v_exp_f32_e32 v102, v102
	v_exp_f32_e32 v110, v110
	v_exp_f32_e32 v104, v104
	v_exp_f32_e32 v112, v112
	v_exp_f32_e32 v98, v98
	v_exp_f32_e32 v106, v106
	v_add_f32_e32 v100, 1.0, v100
	v_add_f32_e32 v114, 1.0, v114
	v_add_f32_e32 v102, 1.0, v102
	v_add_f32_e32 v110, 1.0, v110
	v_add_f32_e32 v104, 1.0, v104
	v_add_f32_e32 v112, 1.0, v112
	v_add_f32_e32 v98, 1.0, v98
	v_add_f32_e32 v106, 1.0, v106
	v_rcp_f32_e32 v100, v100
	v_rcp_f32_e32 v114, v114
	v_rcp_f32_e32 v102, v102
	v_rcp_f32_e32 v110, v110
	v_rcp_f32_e32 v104, v104
	v_rcp_f32_e32 v112, v112
	v_rcp_f32_e32 v98, v98
	v_rcp_f32_e32 v106, v106
	v_mul_f32_e32 v101, v101, v100
	v_mul_f32_e32 v109, v109, v114
	v_mul_f32_e32 v102, v103, v102
	v_mul_f32_e32 v103, v111, v110
	v_mul_f32_e32 v104, v105, v104
	v_mul_f32_e32 v105, v113, v112
	v_mul_f32_e32 v110, v99, v98
	v_mul_f32_e32 v106, v107, v106
	v_cvt_pk_bf16_f32 v98, v109, v102
	v_cvt_pk_bf16_f32 v99, v103, v104
	v_cvt_pk_bf16_f32 v100, v105, v110
	v_cvt_pk_bf16_f32 v101, v106, v101
	global_store_dwordx4 v[116:117], v[98:101], off
	s_nop 0
	s_nop 0
	v_mov_b32_e32 v99, v86
	v_mov_b32_e32 v86, v95
	v_mov_b32_e32 v95, v88
	v_mov_b32_e32 v88, v97
	v_mov_b32_e32 v97, v82
	v_mov_b32_e32 v82, v91
	v_mov_b32_e32 v91, v84
	v_mov_b32_e32 v84, v93
	v_mov_b32_e32 v98, v94
	v_mov_b32_e32 v94, v96
	v_mov_b32_e32 v96, v90
	v_mov_b32_e32 v90, v92
	v_or_b32_e32 v92, 48, v148
	v_mad_i64_i32 v[100:101], s[36:37], v108, s56, v[122:123]
	v_lshl_add_u64 v[100:101], v[100:101], 0, v[124:125]
	v_fmamk_f32 v93, v244, 0x3a000000, v171
	v_rsq_f32_e32 v102, v93
	v_ashrrev_i32_e32 v93, 31, v92
	v_lshl_add_u64 v[104:105], v[92:93], 2, s[18:19]
; __device__ __forceinline__ unsigned cvt_pk_bf16(float lo, float hi) { unsigned r; asm volatile("v_cvt_pk_bf16_f32 %0, %1, %2" : "=v"(r) : "v"(lo), "v"(hi)); return r; }
;     __device__ __forceinline__ void operator()(const f32x4 (&acc)[2][2][4][2], const Unit& u, int wr, int wc, int fr, int fq) const {
;     ...
;             for (int m = 0; m < 4; ++m) { const int row = row0 + ai * HALF + m * 16; const float rs = __builtin_amdgcn_rsqf(ss[row_base + row] * (1.0f / 2048.0f) + 1e-6f);
;                 float a[8];
; #pragma unroll
;                 for (int n = 0; n < 2; ++n)
; #pragma unroll
;                     for (int j = 0; j < 4; ++j) { const float g = acc[ai][0][m][n][j] * rs, uu = acc[ai][1][m][n][j] * rs;
;                         a[n * 4 + j] = g * uu * __builtin_amdgcn_rcpf(1.0f + __builtin_amdgcn_exp2f(-1.4426950408889634f * g)); }
;                 u32x4 w; w.x = cvt_pk_bf16(a[0], a[1]); w.y = cvt_pk_bf16(a[2], a[3]); w.z = cvt_pk_bf16(a[4], a[5]); w.w = cvt_pk_bf16(a[6], a[7]);
;                 *(u32x4*)(act + (size_t)row * 5632 + col0) = w; }
	v_pk_mul_f32 v[84:85], v[84:85], v[102:103] op_sel_hi:[1,0]
	v_pk_mul_f32 v[98:99], v[98:99], v[102:103] op_sel_hi:[1,0]
	v_pk_mul_f32 v[86:87], v[86:87], v[102:103] op_sel_hi:[1,0]
	v_pk_mul_f32 v[94:95], v[94:95], v[102:103] op_sel_hi:[1,0]
	v_pk_mul_f32 v[88:89], v[88:89], v[102:103] op_sel_hi:[1,0]
	v_pk_mul_f32 v[96:97], v[96:97], v[102:103] op_sel_hi:[1,0]
	v_pk_mul_f32 v[82:83], v[82:83], v[102:103] op_sel_hi:[1,0]
	v_pk_mul_f32 v[90:91], v[90:91], v[102:103] op_sel_hi:[1,0]
	v_mul_f32_e32 v85, v84, v85
	v_mul_f32_e32 v84, 0xbfb8aa3b, v84
	v_mul_f32_e32 v93, v98, v99
	v_mul_f32_e32 v98, 0xbfb8aa3b, v98
	v_mul_f32_e32 v87, v86, v87
	v_mul_f32_e32 v86, 0xbfb8aa3b, v86
	v_mul_f32_e32 v95, v94, v95
	v_mul_f32_e32 v94, 0xbfb8aa3b, v94
	v_mul_f32_e32 v89, v88, v89
	v_mul_f32_e32 v88, 0xbfb8aa3b, v88
	v_mul_f32_e32 v97, v96, v97
	v_mul_f32_e32 v96, 0xbfb8aa3b, v96
	v_mul_f32_e32 v83, v82, v83
	v_mul_f32_e32 v82, 0xbfb8aa3b, v82
	v_mul_f32_e32 v91, v90, v91
	v_mul_f32_e32 v90, 0xbfb8aa3b, v90
	v_exp_f32_e32 v84, v84
	v_exp_f32_e32 v98, v98
	v_exp_f32_e32 v86, v86
	v_exp_f32_e32 v94, v94
	v_exp_f32_e32 v88, v88
	v_exp_f32_e32 v96, v96
	v_exp_f32_e32 v82, v82
	v_exp_f32_e32 v90, v90
	v_add_f32_e32 v84, 1.0, v84
	v_add_f32_e32 v98, 1.0, v98
	v_add_f32_e32 v86, 1.0, v86
	v_add_f32_e32 v94, 1.0, v94
	v_add_f32_e32 v88, 1.0, v88
	v_add_f32_e32 v96, 1.0, v96
	v_add_f32_e32 v82, 1.0, v82
	v_add_f32_e32 v90, 1.0, v90
	v_rcp_f32_e32 v84, v84
	v_rcp_f32_e32 v98, v98
	v_rcp_f32_e32 v86, v86
	v_rcp_f32_e32 v94, v94
	v_rcp_f32_e32 v88, v88
	v_rcp_f32_e32 v96, v96
	v_rcp_f32_e32 v82, v82
	v_rcp_f32_e32 v90, v90
	v_mul_f32_e32 v85, v85, v84
	v_mul_f32_e32 v93, v93, v98
	v_mul_f32_e32 v86, v87, v86
	v_mul_f32_e32 v87, v95, v94
	v_mul_f32_e32 v88, v89, v88
	v_mul_f32_e32 v89, v97, v96
	v_mul_f32_e32 v94, v83, v82
	v_mul_f32_e32 v90, v91, v90
	v_cvt_pk_bf16_f32 v82, v93, v86
	v_cvt_pk_bf16_f32 v83, v87, v88
	v_cvt_pk_bf16_f32 v84, v89, v94
	v_cvt_pk_bf16_f32 v85, v90, v85
	global_store_dwordx4 v[100:101], v[82:85], off
	s_nop 0
	s_nop 0
	v_mov_b32_e32 v82, v78
	v_mov_b32_e32 v78, v80
	v_mov_b32_e32 v80, v74
	v_mov_b32_e32 v74, v76
	v_mov_b32_e32 v83, v70
	v_mov_b32_e32 v70, v79
	v_mov_b32_e32 v79, v72
	v_mov_b32_e32 v72, v81
	v_mov_b32_e32 v81, v66
	v_mov_b32_e32 v66, v75
	v_mov_b32_e32 v75, v68
	v_mov_b32_e32 v68, v77
	v_fmamk_f32 v76, v245, 0x3a000000, v171
	v_rsq_f32_e32 v76, v76
	v_mad_i64_i32 v[84:85], s[36:37], v92, s56, v[122:123]
	v_lshl_add_u64 v[84:85], v[84:85], 0, v[124:125]
	v_pk_mul_f32 v[68:69], v[68:69], v[76:77] op_sel_hi:[1,0]
	v_pk_mul_f32 v[82:83], v[82:83], v[76:77] op_sel_hi:[1,0]
	v_pk_mul_f32 v[70:71], v[70:71], v[76:77] op_sel_hi:[1,0]
	v_pk_mul_f32 v[78:79], v[78:79], v[76:77] op_sel_hi:[1,0]
	v_pk_mul_f32 v[72:73], v[72:73], v[76:77] op_sel_hi:[1,0]
	v_pk_mul_f32 v[80:81], v[80:81], v[76:77] op_sel_hi:[1,0]
	v_pk_mul_f32 v[66:67], v[66:67], v[76:77] op_sel_hi:[1,0]
	v_pk_mul_f32 v[74:75], v[74:75], v[76:77] op_sel_hi:[1,0]
	v_mul_f32_e32 v69, v68, v69
	v_mul_f32_e32 v68, 0xbfb8aa3b, v68
	v_mul_f32_e32 v77, 0xbfb8aa3b, v82
	v_mul_f32_e32 v71, v70, v71
	v_mul_f32_e32 v70, 0xbfb8aa3b, v70
	v_mul_f32_e32 v79, v78, v79
	v_mul_f32_e32 v78, 0xbfb8aa3b, v78
	v_mul_f32_e32 v73, v72, v73
	v_mul_f32_e32 v72, 0xbfb8aa3b, v72
	v_mul_f32_e32 v81, v80, v81
	v_mul_f32_e32 v80, 0xbfb8aa3b, v80
	v_mul_f32_e32 v67, v66, v67
	v_mul_f32_e32 v66, 0xbfb8aa3b, v66
	v_mul_f32_e32 v75, v74, v75
	v_mul_f32_e32 v74, 0xbfb8aa3b, v74
	v_exp_f32_e32 v68, v68
	v_exp_f32_e32 v77, v77
	v_exp_f32_e32 v70, v70
	v_exp_f32_e32 v78, v78
	v_exp_f32_e32 v72, v72
	v_exp_f32_e32 v80, v80
	v_exp_f32_e32 v66, v66
	v_exp_f32_e32 v74, v74
	v_add_f32_e32 v68, 1.0, v68
	v_add_f32_e32 v77, 1.0, v77
	v_add_f32_e32 v70, 1.0, v70
	v_add_f32_e32 v78, 1.0, v78
	v_add_f32_e32 v72, 1.0, v72
	v_add_f32_e32 v80, 1.0, v80
	v_add_f32_e32 v66, 1.0, v66
	v_add_f32_e32 v74, 1.0, v74
	v_rcp_f32_e32 v68, v68
	v_rcp_f32_e32 v77, v77
	v_rcp_f32_e32 v70, v70
	v_rcp_f32_e32 v78, v78
	v_rcp_f32_e32 v72, v72
	v_rcp_f32_e32 v80, v80
	v_rcp_f32_e32 v66, v66
	v_rcp_f32_e32 v74, v74
	v_mul_f32_e32 v76, v82, v83
	v_mul_f32_e32 v69, v69, v68
	v_mul_f32_e32 v76, v76, v77
	v_mul_f32_e32 v70, v71, v70
	v_mul_f32_e32 v71, v79, v78
	v_mul_f32_e32 v72, v73, v72
	v_mul_f32_e32 v73, v81, v80
	v_mul_f32_e32 v77, v67, v66
	v_mul_f32_e32 v74, v75, v74
	v_cvt_pk_bf16_f32 v66, v76, v70
	v_cvt_pk_bf16_f32 v67, v71, v72
	v_cvt_pk_bf16_f32 v68, v73, v77
	v_cvt_pk_bf16_f32 v69, v74, v69
	global_store_dwordx4 v[84:85], v[66:69], off
	s_nop 0
	s_nop 0
	v_mov_b32_e32 v66, v62
	v_mov_b32_e32 v62, v64
	v_mov_b32_e32 v64, v58
	v_mov_b32_e32 v58, v60
	v_mov_b32_e32 v67, v54
	v_mov_b32_e32 v54, v63
	v_mov_b32_e32 v63, v56
	v_mov_b32_e32 v56, v65
	v_mov_b32_e32 v65, v50
	v_mov_b32_e32 v50, v59
	v_mov_b32_e32 v59, v52
	v_mov_b32_e32 v52, v61
	v_add_u32_e32 v61, 0x80, v148
	v_fmamk_f32 v60, v246, 0x3a000000, v171
	v_rsq_f32_e32 v60, v60
	v_mad_i64_i32 v[68:69], s[36:37], v61, s56, v[122:123]
	v_lshl_add_u64 v[68:69], v[68:69], 0, v[124:125]
	v_pk_mul_f32 v[52:53], v[52:53], v[60:61] op_sel_hi:[1,0]
	v_pk_mul_f32 v[66:67], v[66:67], v[60:61] op_sel_hi:[1,0]
	v_pk_mul_f32 v[54:55], v[54:55], v[60:61] op_sel_hi:[1,0]
	v_pk_mul_f32 v[62:63], v[62:63], v[60:61] op_sel_hi:[1,0]
	v_pk_mul_f32 v[56:57], v[56:57], v[60:61] op_sel_hi:[1,0]
	v_pk_mul_f32 v[64:65], v[64:65], v[60:61] op_sel_hi:[1,0]
	v_pk_mul_f32 v[50:51], v[50:51], v[60:61] op_sel_hi:[1,0]
	v_pk_mul_f32 v[58:59], v[58:59], v[60:61] op_sel_hi:[1,0]
	v_mul_f32_e32 v53, v52, v53
	v_mul_f32_e32 v52, 0xbfb8aa3b, v52
	v_mul_f32_e32 v61, 0xbfb8aa3b, v66
	v_mul_f32_e32 v55, v54, v55
; __device__ __forceinline__ unsigned cvt_pk_bf16(float lo, float hi) { unsigned r; asm volatile("v_cvt_pk_bf16_f32 %0, %1, %2" : "=v"(r) : "v"(lo), "v"(hi)); return r; }
;     __device__ __forceinline__ void operator()(const f32x4 (&acc)[2][2][4][2], const Unit& u, int wr, int wc, int fr, int fq) const {
;     ...
;             for (int m = 0; m < 4; ++m) { const int row = row0 + ai * HALF + m * 16; const float rs = __builtin_amdgcn_rsqf(ss[row_base + row] * (1.0f / 2048.0f) + 1e-6f);
;                 float a[8];
; #pragma unroll
;                 for (int n = 0; n < 2; ++n)
; #pragma unroll
;                     for (int j = 0; j < 4; ++j) { const float g = acc[ai][0][m][n][j] * rs, uu = acc[ai][1][m][n][j] * rs;
;                         a[n * 4 + j] = g * uu * __builtin_amdgcn_rcpf(1.0f + __builtin_amdgcn_exp2f(-1.4426950408889634f * g)); }
;                 u32x4 w; w.x = cvt_pk_bf16(a[0], a[1]); w.y = cvt_pk_bf16(a[2], a[3]); w.z = cvt_pk_bf16(a[4], a[5]); w.w = cvt_pk_bf16(a[6], a[7]);
;                 *(u32x4*)(act + (size_t)row * 5632 + col0) = w; }
	v_mul_f32_e32 v54, 0xbfb8aa3b, v54
	v_mul_f32_e32 v63, v62, v63
	v_mul_f32_e32 v62, 0xbfb8aa3b, v62
	v_mul_f32_e32 v57, v56, v57
	v_mul_f32_e32 v56, 0xbfb8aa3b, v56
	v_mul_f32_e32 v65, v64, v65
	v_mul_f32_e32 v64, 0xbfb8aa3b, v64
	v_mul_f32_e32 v51, v50, v51
	v_mul_f32_e32 v50, 0xbfb8aa3b, v50
	v_mul_f32_e32 v59, v58, v59
	v_mul_f32_e32 v58, 0xbfb8aa3b, v58
	v_exp_f32_e32 v52, v52
	v_exp_f32_e32 v61, v61
	v_exp_f32_e32 v54, v54
	v_exp_f32_e32 v62, v62
	v_exp_f32_e32 v56, v56
	v_exp_f32_e32 v64, v64
	v_exp_f32_e32 v50, v50
	v_exp_f32_e32 v58, v58
	v_add_f32_e32 v52, 1.0, v52
	v_add_f32_e32 v61, 1.0, v61
	v_add_f32_e32 v54, 1.0, v54
	v_add_f32_e32 v62, 1.0, v62
	v_add_f32_e32 v56, 1.0, v56
	v_add_f32_e32 v64, 1.0, v64
	v_add_f32_e32 v50, 1.0, v50
	v_add_f32_e32 v58, 1.0, v58
	v_rcp_f32_e32 v52, v52
	v_rcp_f32_e32 v61, v61
	v_rcp_f32_e32 v54, v54
	v_rcp_f32_e32 v62, v62
	v_rcp_f32_e32 v56, v56
	v_rcp_f32_e32 v64, v64
	v_rcp_f32_e32 v50, v50
	v_rcp_f32_e32 v58, v58
	v_mul_f32_e32 v60, v66, v67
	v_mul_f32_e32 v53, v53, v52
	v_mul_f32_e32 v60, v60, v61
	v_mul_f32_e32 v54, v55, v54
	v_mul_f32_e32 v55, v63, v62
	v_mul_f32_e32 v56, v57, v56
	v_mul_f32_e32 v57, v65, v64
	v_mul_f32_e32 v61, v51, v50
	v_mul_f32_e32 v58, v59, v58
	v_cvt_pk_bf16_f32 v50, v60, v54
	v_cvt_pk_bf16_f32 v51, v55, v56
	v_cvt_pk_bf16_f32 v52, v57, v61
	v_cvt_pk_bf16_f32 v53, v58, v53
	global_store_dwordx4 v[68:69], v[50:53], off
	s_nop 0
	s_nop 0
	v_mov_b32_e32 v50, v46
	v_mov_b32_e32 v46, v48
	v_mov_b32_e32 v48, v42
	v_mov_b32_e32 v42, v44
	v_mov_b32_e32 v51, v38
	v_mov_b32_e32 v38, v47
	v_mov_b32_e32 v47, v40
	v_mov_b32_e32 v40, v49
	v_mov_b32_e32 v49, v34
	v_mov_b32_e32 v34, v43
	v_mov_b32_e32 v43, v36
	v_mov_b32_e32 v36, v45
	v_add_u32_e32 v45, 0x90, v148
	v_fmamk_f32 v44, v247, 0x3a000000, v171
	v_rsq_f32_e32 v44, v44
	v_mad_i64_i32 v[52:53], s[36:37], v45, s56, v[122:123]
	v_lshl_add_u64 v[52:53], v[52:53], 0, v[124:125]
	v_pk_mul_f32 v[36:37], v[36:37], v[44:45] op_sel_hi:[1,0]
	v_pk_mul_f32 v[50:51], v[50:51], v[44:45] op_sel_hi:[1,0]
	v_pk_mul_f32 v[38:39], v[38:39], v[44:45] op_sel_hi:[1,0]
	v_pk_mul_f32 v[46:47], v[46:47], v[44:45] op_sel_hi:[1,0]
	v_pk_mul_f32 v[40:41], v[40:41], v[44:45] op_sel_hi:[1,0]
	v_pk_mul_f32 v[48:49], v[48:49], v[44:45] op_sel_hi:[1,0]
	v_pk_mul_f32 v[34:35], v[34:35], v[44:45] op_sel_hi:[1,0]
	v_pk_mul_f32 v[42:43], v[42:43], v[44:45] op_sel_hi:[1,0]
	v_mul_f32_e32 v37, v36, v37
	v_mul_f32_e32 v36, 0xbfb8aa3b, v36
	v_mul_f32_e32 v45, 0xbfb8aa3b, v50
	v_mul_f32_e32 v39, v38, v39
	v_mul_f32_e32 v38, 0xbfb8aa3b, v38
	v_mul_f32_e32 v47, v46, v47
	v_mul_f32_e32 v46, 0xbfb8aa3b, v46
	v_mul_f32_e32 v41, v40, v41
	v_mul_f32_e32 v40, 0xbfb8aa3b, v40
	v_mul_f32_e32 v49, v48, v49
	v_mul_f32_e32 v48, 0xbfb8aa3b, v48
	v_mul_f32_e32 v35, v34, v35
	v_mul_f32_e32 v34, 0xbfb8aa3b, v34
	v_mul_f32_e32 v43, v42, v43
	v_mul_f32_e32 v42, 0xbfb8aa3b, v42
	v_exp_f32_e32 v36, v36
	v_exp_f32_e32 v45, v45
	v_exp_f32_e32 v38, v38
	v_exp_f32_e32 v46, v46
	v_exp_f32_e32 v40, v40
	v_exp_f32_e32 v48, v48
	v_exp_f32_e32 v34, v34
	v_exp_f32_e32 v42, v42
	v_add_f32_e32 v36, 1.0, v36
	v_add_f32_e32 v45, 1.0, v45
	v_add_f32_e32 v38, 1.0, v38
	v_add_f32_e32 v46, 1.0, v46
	v_add_f32_e32 v40, 1.0, v40
	v_add_f32_e32 v48, 1.0, v48
	v_add_f32_e32 v34, 1.0, v34
	v_add_f32_e32 v42, 1.0, v42
	v_rcp_f32_e32 v36, v36
	v_rcp_f32_e32 v45, v45
	v_rcp_f32_e32 v38, v38
	v_rcp_f32_e32 v46, v46
	v_rcp_f32_e32 v40, v40
	v_rcp_f32_e32 v48, v48
	v_rcp_f32_e32 v34, v34
	v_rcp_f32_e32 v42, v42
	v_mul_f32_e32 v44, v50, v51
	v_mul_f32_e32 v37, v37, v36
	v_mul_f32_e32 v44, v44, v45
	v_mul_f32_e32 v38, v39, v38
	v_mul_f32_e32 v39, v47, v46
	v_mul_f32_e32 v40, v41, v40
	v_mul_f32_e32 v41, v49, v48
	v_mul_f32_e32 v45, v35, v34
	v_mul_f32_e32 v42, v43, v42
	v_cvt_pk_bf16_f32 v34, v44, v38
	v_cvt_pk_bf16_f32 v35, v39, v40
	v_cvt_pk_bf16_f32 v36, v41, v45
	v_cvt_pk_bf16_f32 v37, v42, v37
	global_store_dwordx4 v[52:53], v[34:37], off
	s_nop 0
	s_nop 0
	v_mov_b32_e32 v34, v30
	v_mov_b32_e32 v30, v32
	v_mov_b32_e32 v32, v26
	v_mov_b32_e32 v26, v28
	v_mov_b32_e32 v35, v22
	v_mov_b32_e32 v22, v31
	v_mov_b32_e32 v31, v24
	v_mov_b32_e32 v24, v33
	v_mov_b32_e32 v33, v18
	v_mov_b32_e32 v18, v27
	v_mov_b32_e32 v27, v20
	v_mov_b32_e32 v20, v29
	v_add_u32_e32 v29, 0xa0, v148
	v_fmamk_f32 v28, v248, 0x3a000000, v171
	v_rsq_f32_e32 v28, v28
	v_mad_i64_i32 v[36:37], s[36:37], v29, s56, v[122:123]
	v_lshl_add_u64 v[36:37], v[36:37], 0, v[124:125]
	v_pk_mul_f32 v[20:21], v[20:21], v[28:29] op_sel_hi:[1,0]
; __device__ __forceinline__ unsigned cvt_pk_bf16(float lo, float hi) { unsigned r; asm volatile("v_cvt_pk_bf16_f32 %0, %1, %2" : "=v"(r) : "v"(lo), "v"(hi)); return r; }
;     __device__ __forceinline__ void operator()(const f32x4 (&acc)[2][2][4][2], const Unit& u, int wr, int wc, int fr, int fq) const {
;     ...
;             for (int m = 0; m < 4; ++m) { const int row = row0 + ai * HALF + m * 16; const float rs = __builtin_amdgcn_rsqf(ss[row_base + row] * (1.0f / 2048.0f) + 1e-6f);
;                 float a[8];
; #pragma unroll
;                 for (int n = 0; n < 2; ++n)
; #pragma unroll
;                     for (int j = 0; j < 4; ++j) { const float g = acc[ai][0][m][n][j] * rs, uu = acc[ai][1][m][n][j] * rs;
;                         a[n * 4 + j] = g * uu * __builtin_amdgcn_rcpf(1.0f + __builtin_amdgcn_exp2f(-1.4426950408889634f * g)); }
;                 u32x4 w; w.x = cvt_pk_bf16(a[0], a[1]); w.y = cvt_pk_bf16(a[2], a[3]); w.z = cvt_pk_bf16(a[4], a[5]); w.w = cvt_pk_bf16(a[6], a[7]);
;                 *(u32x4*)(act + (size_t)row * 5632 + col0) = w; }
	v_pk_mul_f32 v[34:35], v[34:35], v[28:29] op_sel_hi:[1,0]
	v_pk_mul_f32 v[22:23], v[22:23], v[28:29] op_sel_hi:[1,0]
	v_pk_mul_f32 v[30:31], v[30:31], v[28:29] op_sel_hi:[1,0]
	v_pk_mul_f32 v[24:25], v[24:25], v[28:29] op_sel_hi:[1,0]
	v_pk_mul_f32 v[32:33], v[32:33], v[28:29] op_sel_hi:[1,0]
	v_pk_mul_f32 v[18:19], v[18:19], v[28:29] op_sel_hi:[1,0]
	v_pk_mul_f32 v[26:27], v[26:27], v[28:29] op_sel_hi:[1,0]
	v_mul_f32_e32 v21, v20, v21
	v_mul_f32_e32 v20, 0xbfb8aa3b, v20
	v_mul_f32_e32 v29, 0xbfb8aa3b, v34
	v_mul_f32_e32 v23, v22, v23
	v_mul_f32_e32 v22, 0xbfb8aa3b, v22
	v_mul_f32_e32 v31, v30, v31
	v_mul_f32_e32 v30, 0xbfb8aa3b, v30
	v_mul_f32_e32 v25, v24, v25
	v_mul_f32_e32 v24, 0xbfb8aa3b, v24
	v_mul_f32_e32 v33, v32, v33
	v_mul_f32_e32 v32, 0xbfb8aa3b, v32
	v_mul_f32_e32 v19, v18, v19
	v_mul_f32_e32 v18, 0xbfb8aa3b, v18
	v_mul_f32_e32 v27, v26, v27
	v_mul_f32_e32 v26, 0xbfb8aa3b, v26
	v_exp_f32_e32 v20, v20
	v_exp_f32_e32 v29, v29
	v_exp_f32_e32 v22, v22
	v_exp_f32_e32 v30, v30
	v_exp_f32_e32 v24, v24
	v_exp_f32_e32 v32, v32
	v_exp_f32_e32 v18, v18
	v_exp_f32_e32 v26, v26
	v_add_f32_e32 v20, 1.0, v20
	v_add_f32_e32 v29, 1.0, v29
	v_add_f32_e32 v22, 1.0, v22
	v_add_f32_e32 v30, 1.0, v30
	v_add_f32_e32 v24, 1.0, v24
	v_add_f32_e32 v32, 1.0, v32
	v_add_f32_e32 v18, 1.0, v18
	v_add_f32_e32 v26, 1.0, v26
	v_rcp_f32_e32 v20, v20
	v_rcp_f32_e32 v29, v29
	v_rcp_f32_e32 v22, v22
	v_rcp_f32_e32 v30, v30
	v_rcp_f32_e32 v24, v24
	v_rcp_f32_e32 v32, v32
	v_rcp_f32_e32 v18, v18
	v_rcp_f32_e32 v26, v26
	v_mul_f32_e32 v28, v34, v35
	v_mul_f32_e32 v21, v21, v20
	v_mul_f32_e32 v28, v28, v29
	v_mul_f32_e32 v22, v23, v22
	v_mul_f32_e32 v23, v31, v30
	v_mul_f32_e32 v24, v25, v24
	v_mul_f32_e32 v25, v33, v32
	v_mul_f32_e32 v29, v19, v18
	v_mul_f32_e32 v26, v27, v26
	v_cvt_pk_bf16_f32 v18, v28, v22
	v_cvt_pk_bf16_f32 v19, v23, v24
	v_cvt_pk_bf16_f32 v20, v25, v29
	v_cvt_pk_bf16_f32 v21, v26, v21
	global_store_dwordx4 v[36:37], v[18:21], off
	s_nop 0
	s_nop 0
	v_mov_b32_e32 v18, v14
	v_mov_b32_e32 v14, v16
	v_mov_b32_e32 v16, v10
	v_mov_b32_e32 v10, v12
	v_mov_b32_e32 v19, v6
	v_mov_b32_e32 v6, v15
	v_mov_b32_e32 v15, v8
	v_mov_b32_e32 v8, v17
	v_mov_b32_e32 v17, v2
	v_mov_b32_e32 v2, v11
	v_mov_b32_e32 v11, v4
	v_mov_b32_e32 v4, v13
	v_add_u32_e32 v13, 0xb0, v148
	v_fmamk_f32 v12, v249, 0x3a000000, v171
	v_rsq_f32_e32 v12, v12
	v_mad_i64_i32 v[20:21], s[36:37], v13, s56, v[122:123]
	v_lshl_add_u64 v[20:21], v[20:21], 0, v[124:125]
	v_pk_mul_f32 v[4:5], v[4:5], v[12:13] op_sel_hi:[1,0]
	v_pk_mul_f32 v[18:19], v[18:19], v[12:13] op_sel_hi:[1,0]
	v_pk_mul_f32 v[6:7], v[6:7], v[12:13] op_sel_hi:[1,0]
	v_pk_mul_f32 v[14:15], v[14:15], v[12:13] op_sel_hi:[1,0]
	v_pk_mul_f32 v[8:9], v[8:9], v[12:13] op_sel_hi:[1,0]
	v_pk_mul_f32 v[16:17], v[16:17], v[12:13] op_sel_hi:[1,0]
	v_pk_mul_f32 v[2:3], v[2:3], v[12:13] op_sel_hi:[1,0]
	v_pk_mul_f32 v[10:11], v[10:11], v[12:13] op_sel_hi:[1,0]
	v_mul_f32_e32 v5, v4, v5
	v_mul_f32_e32 v4, 0xbfb8aa3b, v4
	v_mul_f32_e32 v13, 0xbfb8aa3b, v18
	v_mul_f32_e32 v7, v6, v7
	v_mul_f32_e32 v6, 0xbfb8aa3b, v6
	v_mul_f32_e32 v15, v14, v15
	v_mul_f32_e32 v14, 0xbfb8aa3b, v14
	v_mul_f32_e32 v9, v8, v9
	v_mul_f32_e32 v8, 0xbfb8aa3b, v8
	v_mul_f32_e32 v17, v16, v17
	v_mul_f32_e32 v16, 0xbfb8aa3b, v16
	v_mul_f32_e32 v3, v2, v3
	v_mul_f32_e32 v2, 0xbfb8aa3b, v2
	v_mul_f32_e32 v11, v10, v11
	v_mul_f32_e32 v10, 0xbfb8aa3b, v10
	v_exp_f32_e32 v4, v4
	v_exp_f32_e32 v13, v13
	v_exp_f32_e32 v6, v6
	v_exp_f32_e32 v14, v14
	v_exp_f32_e32 v8, v8
	v_exp_f32_e32 v16, v16
	v_exp_f32_e32 v2, v2
	v_exp_f32_e32 v10, v10
	v_add_f32_e32 v4, 1.0, v4
	v_add_f32_e32 v13, 1.0, v13
	v_add_f32_e32 v6, 1.0, v6
	v_add_f32_e32 v14, 1.0, v14
	v_add_f32_e32 v8, 1.0, v8
	v_add_f32_e32 v16, 1.0, v16
	v_add_f32_e32 v2, 1.0, v2
	v_add_f32_e32 v10, 1.0, v10
	v_rcp_f32_e32 v4, v4
	v_rcp_f32_e32 v13, v13
	v_rcp_f32_e32 v6, v6
	v_rcp_f32_e32 v14, v14
	v_rcp_f32_e32 v8, v8
	v_rcp_f32_e32 v16, v16
	v_rcp_f32_e32 v2, v2
	v_rcp_f32_e32 v10, v10
	v_mul_f32_e32 v12, v18, v19
	v_mul_f32_e32 v5, v5, v4
	v_mul_f32_e32 v12, v12, v13
	v_mul_f32_e32 v6, v7, v6
	v_mul_f32_e32 v7, v15, v14
	v_mul_f32_e32 v8, v9, v8
	v_mul_f32_e32 v9, v17, v16
	v_mul_f32_e32 v13, v3, v2
	v_mul_f32_e32 v10, v11, v10
	v_cvt_pk_bf16_f32 v2, v12, v6
	v_cvt_pk_bf16_f32 v3, v7, v8
	v_cvt_pk_bf16_f32 v4, v9, v13
	v_cvt_pk_bf16_f32 v5, v10, v5
	global_store_dwordx4 v[20:21], v[2:5], off
	s_cbranch_vccnz .LBB0_493
	s_andn2_b64 vcc, exec, s[8:9]
	s_cbranch_vccnz .LBB0_492
	s_barrier
	s_branch .LBB0_492

; #define PG8_STAGE(bufoff, gbase, voff) do { _Pragma("unroll") for (int _i = 0; _i < 2; ++_i) \
;         __builtin_amdgcn_global_load_lds((const unsigned*)((const char*)(gbase) + (voff)[_i]), (PG8_LAS unsigned*)(lds + (bufoff) + ldsw + _i * 8192), 16, 0, 0); } while (0)
; #define PG8_LDA(dst, b, h) do { _Pragma("unroll") for (int m = 0; m < 4; ++m) _Pragma("unroll") for (int k = 0; k < 2; ++k) dst[m][k] = *(const PG8_LAS bf16x8*)(lds + PG8_SA(b, h) + aoff + m * 2048 + k * 1024); } while (0)
; #define PG8_LDB(dst, b, h) do { _Pragma("unroll") for (int n = 0; n < 2; ++n) _Pragma("unroll") for (int k = 0; k < 2; ++k) dst[n][k] = *(const PG8_LAS bf16x8*)(lds + PG8_SB(b, h) + boff + n * 2048 + k * 1024); } while (0)
; #define PG8_MMA(ai, bj, At, Bt) do { __builtin_amdgcn_s_setprio(1); _Pragma("unroll") for (int m = 0; m < 4; ++m) _Pragma("unroll") for (int n = 0; n < 2; ++n) _Pragma("unroll") for (int k = 0; k < 2; ++k) \
;         acc[ai][bj][m][n] = __builtin_amdgcn_mfma_f32_16x16x32_bf16(Bt[n][k], At[m][k], acc[ai][bj][m][n], 0, 0, 0); __builtin_amdgcn_s_setprio(0); } while (0)
; #define PG8_WAIT_V(n) asm volatile("s_waitcnt vmcnt(" #n ")" ::: "memory")
; #define PG8_WAIT_L(n) asm volatile("s_waitcnt lgkmcnt(" #n ")" ::: "memory")
; #define PG8_BAR __builtin_amdgcn_s_barrier()
; #define PG8_SCHED __builtin_amdgcn_sched_barrier(0)
; template <class Epi, class Sched, bool ALIGN_EPI = false, bool SP2 = false, bool KSEG = false>
; __device__ __forceinline__ void gemm_phase(PG8_LAS unsigned char* lds, const Gemm g, const Sched& S, const Epi& E) {
;     ...
;             PG8_LDB(B0, 0, 0); PG8_LDB(B1, 0, 1); PG8_SCHED; PG8_LDA(At, 0, 0); PG8_STAGE(PG8_SA(1, 1), a1 + hstep, voffA);
;             PG8_WAIT_V(8); PG8_WAIT_L(0); PG8_BAR; PG8_MMA(0, 0, At, B0); PG8_MMA(0, 1, At, B1); PG8_BAR; PG8_SCHED;
;             PG8_LDA(At, 0, 1); PG8_STAGE(PG8_SB(0, 0), b2, voffB); PG8_STAGE(PG8_SB(0, 1), b2 + hstep, voffB); PG8_STAGE(PG8_SA(0, 0), a2, voffA);
;             PG8_WAIT_V(8); PG8_WAIT_L(0); PG8_BAR; PG8_MMA(1, 0, At, B0); PG8_MMA(1, 1, At, B1); PG8_BAR; PG8_SCHED;
;             PG8_LDB(B0, 1, 0); PG8_LDB(B1, 1, 1); PG8_SCHED; PG8_LDA(At, 1, 0); PG8_STAGE(PG8_SA(0, 1), a2 + hstep, voffA);
;             PG8_WAIT_V(8); PG8_WAIT_L(0); PG8_BAR; PG8_MMA(0, 0, At, B0); PG8_MMA(0, 1, At, B1); PG8_BAR; PG8_SCHED;
.LBB0_537:
	ds_read_b128 v[154:157], v173
	ds_read_b128 v[176:179], v173 offset:1024
	ds_read_b128 v[180:183], v173 offset:2048
	ds_read_b128 v[184:187], v173 offset:3072
	ds_read_b128 v[188:191], v174
	ds_read_b128 v[192:195], v174 offset:1024
	ds_read_b128 v[196:199], v174 offset:2048
	ds_read_b128 v[200:203], v174 offset:3072
	s_add_u32 s33, s36, 0xffea0080
	s_addc_u32 s38, s37, -1
	s_cmpk_eq_i32 s64, 0x54
	s_cselect_b32 s41, s13, s38
	s_cselect_b32 s40, s12, s33
	s_cselect_b32 s39, s31, s63
	s_cselect_b32 s38, s30, s62
	s_add_u32 s98, s36, 0xffea0000
	s_addc_u32 s99, s37, -1
	s_mov_b32 m0, s54
	v_lshl_add_u64 v[236:237], s[98:99], 0, v[140:141]
	global_load_lds_dwordx4 v[236:237], off
	s_mov_b32 m0, s55
	v_lshl_add_u64 v[236:237], s[98:99], 0, v[142:143]
	global_load_lds_dwordx4 v[236:237], off
	v_lshl_add_u64 v[236:237], s[36:37], 0, v[146:147]
	s_add_i32 m0, s44, 0xc000
	ds_read_b128 v[204:207], v175
	ds_read_b128 v[208:211], v175 offset:1024
	ds_read_b128 v[212:215], v175 offset:2048
	ds_read_b128 v[216:219], v175 offset:3072
	ds_read_b128 v[220:223], v175 offset:4096
	ds_read_b128 v[224:227], v175 offset:5120
	ds_read_b128 v[228:231], v175 offset:6144
	ds_read_b128 v[232:235], v175 offset:7168
	global_load_lds_dwordx4 v[236:237], off
	s_add_i32 m0, s44, 0xe000
	v_lshl_add_u64 v[236:237], s[36:37], 0, v[148:149]
	global_load_lds_dwordx4 v[236:237], off
	s_waitcnt vmcnt(8) lgkmcnt(0)
	s_barrier
	s_setprio 1
	v_mfma_f32_16x16x32_bf16 v[126:129], v[154:157], v[204:207], v[126:129]
	v_mfma_f32_16x16x32_bf16 v[122:125], v[180:183], v[204:207], v[122:125]
	v_mfma_f32_16x16x32_bf16 v[110:113], v[154:157], v[212:215], v[110:113]
	v_mfma_f32_16x16x32_bf16 v[106:109], v[180:183], v[212:215], v[106:109]
	v_mfma_f32_16x16x32_bf16 v[94:97], v[154:157], v[220:223], v[94:97]
	v_mfma_f32_16x16x32_bf16 v[90:93], v[180:183], v[220:223], v[90:93]
	v_mfma_f32_16x16x32_bf16 v[78:81], v[154:157], v[228:231], v[78:81]
	v_mfma_f32_16x16x32_bf16 v[74:77], v[180:183], v[228:231], v[74:77]
	v_mfma_f32_16x16x32_bf16 v[126:129], v[176:179], v[208:211], v[126:129]
	v_mfma_f32_16x16x32_bf16 v[122:125], v[184:187], v[208:211], v[122:125]
	v_mfma_f32_16x16x32_bf16 v[110:113], v[176:179], v[216:219], v[110:113]
	v_mfma_f32_16x16x32_bf16 v[106:109], v[184:187], v[216:219], v[106:109]
	v_mfma_f32_16x16x32_bf16 v[94:97], v[176:179], v[224:227], v[94:97]
	v_mfma_f32_16x16x32_bf16 v[90:93], v[184:187], v[224:227], v[90:93]
	v_mfma_f32_16x16x32_bf16 v[78:81], v[176:179], v[232:235], v[78:81]
	v_mfma_f32_16x16x32_bf16 v[74:77], v[184:187], v[232:235], v[74:77]
	s_setprio 0
	s_setprio 1
	v_mfma_f32_16x16x32_bf16 v[118:121], v[188:191], v[204:207], v[118:121]
	v_mfma_f32_16x16x32_bf16 v[114:117], v[196:199], v[204:207], v[114:117]
	v_mfma_f32_16x16x32_bf16 v[102:105], v[188:191], v[212:215], v[102:105]
	v_mfma_f32_16x16x32_bf16 v[98:101], v[196:199], v[212:215], v[98:101]
	v_mfma_f32_16x16x32_bf16 v[86:89], v[188:191], v[220:223], v[86:89]
	v_mfma_f32_16x16x32_bf16 v[82:85], v[196:199], v[220:223], v[82:85]
	v_mfma_f32_16x16x32_bf16 v[70:73], v[188:191], v[228:231], v[70:73]
	v_mfma_f32_16x16x32_bf16 v[66:69], v[196:199], v[228:231], v[66:69]
	v_mfma_f32_16x16x32_bf16 v[118:121], v[192:195], v[208:211], v[118:121]
	v_mfma_f32_16x16x32_bf16 v[114:117], v[200:203], v[208:211], v[114:117]
	v_mfma_f32_16x16x32_bf16 v[102:105], v[192:195], v[216:219], v[102:105]
	v_mfma_f32_16x16x32_bf16 v[98:101], v[200:203], v[216:219], v[98:101]
	v_mfma_f32_16x16x32_bf16 v[86:89], v[192:195], v[224:227], v[86:89]
	v_mfma_f32_16x16x32_bf16 v[82:85], v[200:203], v[224:227], v[82:85]
	v_mfma_f32_16x16x32_bf16 v[70:73], v[192:195], v[232:235], v[70:73]
	v_mfma_f32_16x16x32_bf16 v[66:69], v[200:203], v[232:235], v[66:69]
	s_setprio 0
	s_barrier
	s_add_i32 s33, s56, s43
	v_lshl_add_u64 v[236:237], s[38:39], 0, v[130:131]
	s_mov_b32 m0, s33
	ds_read_b128 v[204:207], v175 offset:16384
	ds_read_b128 v[208:211], v175 offset:17408
	ds_read_b128 v[212:215], v175 offset:18432
	ds_read_b128 v[216:219], v175 offset:19456
	ds_read_b128 v[220:223], v175 offset:20480
	ds_read_b128 v[224:227], v175 offset:21504
	ds_read_b128 v[228:231], v175 offset:22528
	ds_read_b128 v[232:235], v175 offset:23552
	global_load_lds_dwordx4 v[236:237], off
	s_add_i32 m0, s33, 0x2000
	s_add_u32 s66, s38, 0x160000
	v_lshl_add_u64 v[238:239], s[38:39], 0, v[144:145]
	s_addc_u32 s67, s39, 0
	s_add_i32 s33, s57, s43
	global_load_lds_dwordx4 v[238:239], off
	s_mov_b32 m0, s33
	v_lshl_add_u64 v[240:241], s[66:67], 0, v[130:131]
	global_load_lds_dwordx4 v[240:241], off
	s_add_i32 m0, s33, 0x2000
	v_lshl_add_u64 v[240:241], s[66:67], 0, v[144:145]
	global_load_lds_dwordx4 v[240:241], off
	s_waitcnt vmcnt(6) lgkmcnt(0)
	s_barrier
; #define PG8_STAGE(bufoff, gbase, voff) do { _Pragma("unroll") for (int _i = 0; _i < 2; ++_i) \
;         __builtin_amdgcn_global_load_lds((const unsigned*)((const char*)(gbase) + (voff)[_i]), (PG8_LAS unsigned*)(lds + (bufoff) + ldsw + _i * 8192), 16, 0, 0); } while (0)
; #define PG8_LDA(dst, b, h) do { _Pragma("unroll") for (int m = 0; m < 4; ++m) _Pragma("unroll") for (int k = 0; k < 2; ++k) dst[m][k] = *(const PG8_LAS bf16x8*)(lds + PG8_SA(b, h) + aoff + m * 2048 + k * 1024); } while (0)
; #define PG8_LDB(dst, b, h) do { _Pragma("unroll") for (int n = 0; n < 2; ++n) _Pragma("unroll") for (int k = 0; k < 2; ++k) dst[n][k] = *(const PG8_LAS bf16x8*)(lds + PG8_SB(b, h) + boff + n * 2048 + k * 1024); } while (0)
; #define PG8_MMA(ai, bj, At, Bt) do { __builtin_amdgcn_s_setprio(1); _Pragma("unroll") for (int m = 0; m < 4; ++m) _Pragma("unroll") for (int n = 0; n < 2; ++n) _Pragma("unroll") for (int k = 0; k < 2; ++k) \
;         acc[ai][bj][m][n] = __builtin_amdgcn_mfma_f32_16x16x32_bf16(Bt[n][k], At[m][k], acc[ai][bj][m][n], 0, 0, 0); __builtin_amdgcn_s_setprio(0); } while (0)
; #define PG8_WAIT_V(n) asm volatile("s_waitcnt vmcnt(" #n ")" ::: "memory")
; #define PG8_WAIT_L(n) asm volatile("s_waitcnt lgkmcnt(" #n ")" ::: "memory")
; #define PG8_BAR __builtin_amdgcn_s_barrier()
; #define PG8_SCHED __builtin_amdgcn_sched_barrier(0)
; template <class Epi, class Sched, bool ALIGN_EPI = false, bool SP2 = false, bool KSEG = false>
; __device__ __forceinline__ void gemm_phase(PG8_LAS unsigned char* lds, const Gemm g, const Sched& S, const Epi& E) {
;     ...
;             PG8_WAIT_V(8); PG8_WAIT_L(0); PG8_BAR; PG8_MMA(1, 0, At, B0); PG8_MMA(1, 1, At, B1); PG8_BAR; PG8_SCHED;
;             PG8_LDB(B0, 1, 0); PG8_LDB(B1, 1, 1); PG8_SCHED; PG8_LDA(At, 1, 0); PG8_STAGE(PG8_SA(0, 1), a2 + hstep, voffA);
;             PG8_WAIT_V(8); PG8_WAIT_L(0); PG8_BAR; PG8_MMA(0, 0, At, B0); PG8_MMA(0, 1, At, B1); PG8_BAR; PG8_SCHED;
	s_setprio 1
	v_mfma_f32_16x16x32_bf16 v[62:65], v[154:157], v[204:207], v[62:65]
	v_mfma_f32_16x16x32_bf16 v[58:61], v[180:183], v[204:207], v[58:61]
	v_mfma_f32_16x16x32_bf16 v[46:49], v[154:157], v[212:215], v[46:49]
	v_mfma_f32_16x16x32_bf16 v[42:45], v[180:183], v[212:215], v[42:45]
	v_mfma_f32_16x16x32_bf16 v[30:33], v[154:157], v[220:223], v[30:33]
	v_mfma_f32_16x16x32_bf16 v[26:29], v[180:183], v[220:223], v[26:29]
	v_mfma_f32_16x16x32_bf16 v[14:17], v[154:157], v[228:231], v[14:17]
	v_mfma_f32_16x16x32_bf16 v[10:13], v[180:183], v[228:231], v[10:13]
	v_mfma_f32_16x16x32_bf16 v[62:65], v[176:179], v[208:211], v[62:65]
	v_mfma_f32_16x16x32_bf16 v[58:61], v[184:187], v[208:211], v[58:61]
	v_mfma_f32_16x16x32_bf16 v[46:49], v[176:179], v[216:219], v[46:49]
	v_mfma_f32_16x16x32_bf16 v[42:45], v[184:187], v[216:219], v[42:45]
	v_mfma_f32_16x16x32_bf16 v[30:33], v[176:179], v[224:227], v[30:33]
	v_mfma_f32_16x16x32_bf16 v[26:29], v[184:187], v[224:227], v[26:29]
	v_mfma_f32_16x16x32_bf16 v[14:17], v[176:179], v[232:235], v[14:17]
	v_mfma_f32_16x16x32_bf16 v[10:13], v[184:187], v[232:235], v[10:13]
	s_setprio 0
	s_setprio 1
	v_mfma_f32_16x16x32_bf16 v[54:57], v[188:191], v[204:207], v[54:57]
	v_mfma_f32_16x16x32_bf16 v[50:53], v[196:199], v[204:207], v[50:53]
	v_mfma_f32_16x16x32_bf16 v[38:41], v[188:191], v[212:215], v[38:41]
	v_mfma_f32_16x16x32_bf16 v[34:37], v[196:199], v[212:215], v[34:37]
	v_mfma_f32_16x16x32_bf16 v[22:25], v[188:191], v[220:223], v[22:25]
	v_mfma_f32_16x16x32_bf16 v[18:21], v[196:199], v[220:223], v[18:21]
	v_mfma_f32_16x16x32_bf16 v[6:9], v[188:191], v[228:231], v[6:9]
	v_mfma_f32_16x16x32_bf16 v[2:5], v[196:199], v[228:231], v[2:5]
	v_mfma_f32_16x16x32_bf16 v[54:57], v[192:195], v[208:211], v[54:57]
	v_mfma_f32_16x16x32_bf16 v[50:53], v[200:203], v[208:211], v[50:53]
	v_mfma_f32_16x16x32_bf16 v[38:41], v[192:195], v[216:219], v[38:41]
	v_mfma_f32_16x16x32_bf16 v[34:37], v[200:203], v[216:219], v[34:37]
	v_mfma_f32_16x16x32_bf16 v[22:25], v[192:195], v[224:227], v[22:25]
	v_mfma_f32_16x16x32_bf16 v[18:21], v[200:203], v[224:227], v[18:21]
	v_mfma_f32_16x16x32_bf16 v[6:9], v[192:195], v[232:235], v[6:9]
	v_mfma_f32_16x16x32_bf16 v[2:5], v[200:203], v[232:235], v[2:5]
	s_setprio 0
	s_barrier
	s_add_i32 s33, 0, 0x18000
	s_add_i32 s65, 0, 0x1c000
	v_add_u32_e32 v184, s33, v171
	v_add_u32_e32 v200, s65, v171
	ds_read_b128 v[154:157], v184
	ds_read_b128 v[176:179], v184 offset:1024
	ds_read_b128 v[180:183], v184 offset:2048
	ds_read_b128 v[184:187], v184 offset:3072
	ds_read_b128 v[188:191], v200
	ds_read_b128 v[192:195], v200 offset:1024
	ds_read_b128 v[196:199], v200 offset:2048
	ds_read_b128 v[200:203], v200 offset:3072
	s_mov_b32 m0, s44
	v_lshl_add_u64 v[244:245], s[40:41], 0, v[140:141]
	global_load_lds_dwordx4 v[244:245], off
	s_mov_b32 m0, s45
	v_lshl_add_u64 v[244:245], s[40:41], 0, v[142:143]
	global_load_lds_dwordx4 v[244:245], off
	s_add_u32 s40, s40, 0x160000
	s_addc_u32 s41, s41, 0
	s_mov_b32 m0, s51
	v_lshl_add_u64 v[244:245], s[40:41], 0, v[140:141]
	ds_read_b128 v[204:207], v175 offset:32768
	ds_read_b128 v[208:211], v175 offset:33792
	ds_read_b128 v[212:215], v175 offset:34816
	ds_read_b128 v[216:219], v175 offset:35840
	ds_read_b128 v[220:223], v175 offset:36864
	ds_read_b128 v[224:227], v175 offset:37888
	ds_read_b128 v[228:231], v175 offset:38912
	ds_read_b128 v[232:235], v175 offset:39936
	global_load_lds_dwordx4 v[244:245], off
	s_mov_b32 m0, s52
	v_lshl_add_u64 v[244:245], s[40:41], 0, v[142:143]
	global_load_lds_dwordx4 v[244:245], off
	s_waitcnt vmcnt(8) lgkmcnt(0)
	s_barrier
; #define PG8_STAGE(bufoff, gbase, voff) do { _Pragma("unroll") for (int _i = 0; _i < 2; ++_i) \
;         __builtin_amdgcn_global_load_lds((const unsigned*)((const char*)(gbase) + (voff)[_i]), (PG8_LAS unsigned*)(lds + (bufoff) + ldsw + _i * 8192), 16, 0, 0); } while (0)
; #define PG8_LDA(dst, b, h) do { _Pragma("unroll") for (int m = 0; m < 4; ++m) _Pragma("unroll") for (int k = 0; k < 2; ++k) dst[m][k] = *(const PG8_LAS bf16x8*)(lds + PG8_SA(b, h) + aoff + m * 2048 + k * 1024); } while (0)
; #define PG8_MMA(ai, bj, At, Bt) do { __builtin_amdgcn_s_setprio(1); _Pragma("unroll") for (int m = 0; m < 4; ++m) _Pragma("unroll") for (int n = 0; n < 2; ++n) _Pragma("unroll") for (int k = 0; k < 2; ++k) \
;         acc[ai][bj][m][n] = __builtin_amdgcn_mfma_f32_16x16x32_bf16(Bt[n][k], At[m][k], acc[ai][bj][m][n], 0, 0, 0); __builtin_amdgcn_s_setprio(0); } while (0)
; #define PG8_WAIT_V(n) asm volatile("s_waitcnt vmcnt(" #n ")" ::: "memory")
; #define PG8_WAIT_L(n) asm volatile("s_waitcnt lgkmcnt(" #n ")" ::: "memory")
; #define PG8_BAR __builtin_amdgcn_s_barrier()
; #define PG8_SCHED __builtin_amdgcn_sched_barrier(0)
; template <class Epi, class Sched, bool ALIGN_EPI = false, bool SP2 = false, bool KSEG = false>
; __device__ __forceinline__ void gemm_phase(PG8_LAS unsigned char* lds, const Gemm g, const Sched& S, const Epi& E) {
;     ...
;             PG8_WAIT_V(8); PG8_WAIT_L(0); PG8_BAR; PG8_MMA(0, 0, At, B0); PG8_MMA(0, 1, At, B1); PG8_BAR; PG8_SCHED;
;             PG8_LDA(At, 1, 1); PG8_STAGE(PG8_SB(1, 0), b3, voffB); PG8_STAGE(PG8_SB(1, 1), b3 + hstep, voffB); PG8_STAGE(PG8_SA(1, 0), a3, voffA);
;             PG8_WAIT_V(8); PG8_WAIT_L(0); PG8_BAR; PG8_MMA(1, 0, At, B0); PG8_MMA(1, 1, At, B1); PG8_BAR; PG8_SCHED;
	s_setprio 1
	v_mfma_f32_16x16x32_bf16 v[126:129], v[154:157], v[204:207], v[126:129]
	v_mfma_f32_16x16x32_bf16 v[122:125], v[180:183], v[204:207], v[122:125]
	v_mfma_f32_16x16x32_bf16 v[110:113], v[154:157], v[212:215], v[110:113]
	v_mfma_f32_16x16x32_bf16 v[106:109], v[180:183], v[212:215], v[106:109]
	v_mfma_f32_16x16x32_bf16 v[94:97], v[154:157], v[220:223], v[94:97]
	v_mfma_f32_16x16x32_bf16 v[90:93], v[180:183], v[220:223], v[90:93]
	v_mfma_f32_16x16x32_bf16 v[78:81], v[154:157], v[228:231], v[78:81]
	v_mfma_f32_16x16x32_bf16 v[74:77], v[180:183], v[228:231], v[74:77]
	v_mfma_f32_16x16x32_bf16 v[126:129], v[176:179], v[208:211], v[126:129]
	v_mfma_f32_16x16x32_bf16 v[122:125], v[184:187], v[208:211], v[122:125]
	v_mfma_f32_16x16x32_bf16 v[110:113], v[176:179], v[216:219], v[110:113]
	v_mfma_f32_16x16x32_bf16 v[106:109], v[184:187], v[216:219], v[106:109]
	v_mfma_f32_16x16x32_bf16 v[94:97], v[176:179], v[224:227], v[94:97]
	v_mfma_f32_16x16x32_bf16 v[90:93], v[184:187], v[224:227], v[90:93]
	v_mfma_f32_16x16x32_bf16 v[78:81], v[176:179], v[232:235], v[78:81]
	v_mfma_f32_16x16x32_bf16 v[74:77], v[184:187], v[232:235], v[74:77]
	s_setprio 0
	s_setprio 1
	v_mfma_f32_16x16x32_bf16 v[118:121], v[188:191], v[204:207], v[118:121]
	v_mfma_f32_16x16x32_bf16 v[114:117], v[196:199], v[204:207], v[114:117]
	v_mfma_f32_16x16x32_bf16 v[102:105], v[188:191], v[212:215], v[102:105]
	v_mfma_f32_16x16x32_bf16 v[98:101], v[196:199], v[212:215], v[98:101]
	v_mfma_f32_16x16x32_bf16 v[86:89], v[188:191], v[220:223], v[86:89]
	v_mfma_f32_16x16x32_bf16 v[82:85], v[196:199], v[220:223], v[82:85]
	v_mfma_f32_16x16x32_bf16 v[70:73], v[188:191], v[228:231], v[70:73]
	v_mfma_f32_16x16x32_bf16 v[66:69], v[196:199], v[228:231], v[66:69]
	v_mfma_f32_16x16x32_bf16 v[118:121], v[192:195], v[208:211], v[118:121]
	v_mfma_f32_16x16x32_bf16 v[114:117], v[200:203], v[208:211], v[114:117]
	v_mfma_f32_16x16x32_bf16 v[102:105], v[192:195], v[216:219], v[102:105]
	v_mfma_f32_16x16x32_bf16 v[98:101], v[200:203], v[216:219], v[98:101]
	v_mfma_f32_16x16x32_bf16 v[86:89], v[192:195], v[224:227], v[86:89]
	v_mfma_f32_16x16x32_bf16 v[82:85], v[200:203], v[224:227], v[82:85]
	v_mfma_f32_16x16x32_bf16 v[70:73], v[192:195], v[232:235], v[70:73]
	v_mfma_f32_16x16x32_bf16 v[66:69], v[200:203], v[232:235], v[66:69]
	s_setprio 0
	s_barrier
	s_add_i32 s33, s33, s43
	v_lshl_add_u64 v[236:237], v[236:237], 0, s[26:27]
	s_mov_b32 m0, s33
	ds_read_b128 v[204:207], v175 offset:49152
	ds_read_b128 v[208:211], v175 offset:50176
	ds_read_b128 v[212:215], v175 offset:51200
	ds_read_b128 v[216:219], v175 offset:52224
	ds_read_b128 v[220:223], v175 offset:53248
	ds_read_b128 v[224:227], v175 offset:54272
	ds_read_b128 v[228:231], v175 offset:55296
	ds_read_b128 v[232:235], v175 offset:56320
	global_load_lds_dwordx4 v[236:237], off
	s_add_i32 m0, s33, 0x2000
	s_add_u32 s38, s38, 0x160080
	v_lshl_add_u64 v[236:237], v[238:239], 0, s[26:27]
	s_addc_u32 s39, s39, 0
	s_add_i32 s33, s65, s43
	global_load_lds_dwordx4 v[236:237], off
	s_mov_b32 m0, s33
	v_lshl_add_u64 v[236:237], s[38:39], 0, v[130:131]
	global_load_lds_dwordx4 v[236:237], off
	s_add_i32 m0, s33, 0x2000
	v_lshl_add_u64 v[236:237], s[38:39], 0, v[144:145]
	global_load_lds_dwordx4 v[236:237], off
	s_waitcnt vmcnt(6) lgkmcnt(0)
	s_barrier
	s_setprio 1
	v_mfma_f32_16x16x32_bf16 v[62:65], v[154:157], v[204:207], v[62:65]
	v_mfma_f32_16x16x32_bf16 v[58:61], v[180:183], v[204:207], v[58:61]
	v_mfma_f32_16x16x32_bf16 v[46:49], v[154:157], v[212:215], v[46:49]
	v_mfma_f32_16x16x32_bf16 v[42:45], v[180:183], v[212:215], v[42:45]
	v_mfma_f32_16x16x32_bf16 v[30:33], v[154:157], v[220:223], v[30:33]
	v_mfma_f32_16x16x32_bf16 v[26:29], v[180:183], v[220:223], v[26:29]
	v_mfma_f32_16x16x32_bf16 v[14:17], v[154:157], v[228:231], v[14:17]
	v_mfma_f32_16x16x32_bf16 v[10:13], v[180:183], v[228:231], v[10:13]
	v_mfma_f32_16x16x32_bf16 v[62:65], v[176:179], v[208:211], v[62:65]
	v_mfma_f32_16x16x32_bf16 v[58:61], v[184:187], v[208:211], v[58:61]
	v_mfma_f32_16x16x32_bf16 v[46:49], v[176:179], v[216:219], v[46:49]
	v_mfma_f32_16x16x32_bf16 v[42:45], v[184:187], v[216:219], v[42:45]
	v_mfma_f32_16x16x32_bf16 v[30:33], v[176:179], v[224:227], v[30:33]
	v_mfma_f32_16x16x32_bf16 v[26:29], v[184:187], v[224:227], v[26:29]
	v_mfma_f32_16x16x32_bf16 v[14:17], v[176:179], v[232:235], v[14:17]
	v_mfma_f32_16x16x32_bf16 v[10:13], v[184:187], v[232:235], v[10:13]
	s_setprio 0
	s_setprio 1
	v_mfma_f32_16x16x32_bf16 v[54:57], v[188:191], v[204:207], v[54:57]
	v_mfma_f32_16x16x32_bf16 v[50:53], v[196:199], v[204:207], v[50:53]
	v_mfma_f32_16x16x32_bf16 v[38:41], v[188:191], v[212:215], v[38:41]
	v_mfma_f32_16x16x32_bf16 v[34:37], v[196:199], v[212:215], v[34:37]
	v_mfma_f32_16x16x32_bf16 v[22:25], v[188:191], v[220:223], v[22:25]
	v_mfma_f32_16x16x32_bf16 v[18:21], v[196:199], v[220:223], v[18:21]
	v_mfma_f32_16x16x32_bf16 v[6:9], v[188:191], v[228:231], v[6:9]
	v_mfma_f32_16x16x32_bf16 v[2:5], v[196:199], v[228:231], v[2:5]
	v_mfma_f32_16x16x32_bf16 v[54:57], v[192:195], v[208:211], v[54:57]
	v_mfma_f32_16x16x32_bf16 v[50:53], v[200:203], v[208:211], v[50:53]
	v_mfma_f32_16x16x32_bf16 v[38:41], v[192:195], v[216:219], v[38:41]
	v_mfma_f32_16x16x32_bf16 v[34:37], v[200:203], v[216:219], v[34:37]
	v_mfma_f32_16x16x32_bf16 v[22:25], v[192:195], v[224:227], v[22:25]
	v_mfma_f32_16x16x32_bf16 v[18:21], v[200:203], v[224:227], v[18:21]
	v_mfma_f32_16x16x32_bf16 v[6:9], v[192:195], v[232:235], v[6:9]
	v_mfma_f32_16x16x32_bf16 v[2:5], v[200:203], v[232:235], v[2:5]
	s_setprio 0
	s_barrier
	s_add_i32 s64, s64, 2
	s_add_u32 s36, s36, 0x100
	s_addc_u32 s37, s37, 0
	s_add_u32 s62, s62, 0x100
	s_addc_u32 s63, s63, 0
	s_cmpk_gt_u32 s64, 0x55
	s_cbranch_scc0 .LBB0_537
	s_and_b64 vcc, exec, s[28:29]
	s_cbranch_vccz .LBB0_540
	s_barrier

; #define PG8_STAGE(bufoff, gbase, voff) do { _Pragma("unroll") for (int _i = 0; _i < 2; ++_i) \
;         __builtin_amdgcn_global_load_lds((const unsigned*)((const char*)(gbase) + (voff)[_i]), (PG8_LAS unsigned*)(lds + (bufoff) + ldsw + _i * 8192), 16, 0, 0); } while (0)
; #define PG8_LDA(dst, b, h) do { _Pragma("unroll") for (int m = 0; m < 4; ++m) _Pragma("unroll") for (int k = 0; k < 2; ++k) dst[m][k] = *(const PG8_LAS bf16x8*)(lds + PG8_SA(b, h) + aoff + m * 2048 + k * 1024); } while (0)
; #define PG8_LDB(dst, b, h) do { _Pragma("unroll") for (int n = 0; n < 2; ++n) _Pragma("unroll") for (int k = 0; k < 2; ++k) dst[n][k] = *(const PG8_LAS bf16x8*)(lds + PG8_SB(b, h) + boff + n * 2048 + k * 1024); } while (0)
; #define PG8_MMA(ai, bj, At, Bt) do { __builtin_amdgcn_s_setprio(1); _Pragma("unroll") for (int m = 0; m < 4; ++m) _Pragma("unroll") for (int n = 0; n < 2; ++n) _Pragma("unroll") for (int k = 0; k < 2; ++k) \
;         acc[ai][bj][m][n] = __builtin_amdgcn_mfma_f32_16x16x32_bf16(Bt[n][k], At[m][k], acc[ai][bj][m][n], 0, 0, 0); __builtin_amdgcn_s_setprio(0); } while (0)
; #define PG8_WAIT_V(n) asm volatile("s_waitcnt vmcnt(" #n ")" ::: "memory")
; #define PG8_WAIT_L(n) asm volatile("s_waitcnt lgkmcnt(" #n ")" ::: "memory")
; #define PG8_BAR __builtin_amdgcn_s_barrier()
; #define PG8_SCHED __builtin_amdgcn_sched_barrier(0)
; template <class Epi, class Sched, bool ALIGN_EPI = false, bool SP2 = false, bool KSEG = false>
; __device__ __forceinline__ void gemm_phase(PG8_LAS unsigned char* lds, const Gemm g, const Sched& S, const Epi& E) {
;     ...
;             PG8_LDB(B0, 0, 0); PG8_LDB(B1, 0, 1); PG8_SCHED; PG8_LDA(At, 0, 0); PG8_STAGE(PG8_SA(1, 1), a1 + hstep, voffA);
;             PG8_WAIT_V(8); PG8_WAIT_L(0); PG8_BAR; PG8_MMA(0, 0, At, B0); PG8_MMA(0, 1, At, B1); PG8_BAR; PG8_SCHED;
;             PG8_LDA(At, 0, 1); PG8_STAGE(PG8_SB(0, 0), b2, voffB); PG8_STAGE(PG8_SB(0, 1), b2 + hstep, voffB); PG8_STAGE(PG8_SA(0, 0), a2, voffA);
;             PG8_WAIT_V(8); PG8_WAIT_L(0); PG8_BAR; PG8_MMA(1, 0, At, B0); PG8_MMA(1, 1, At, B1); PG8_BAR; PG8_SCHED;
;             PG8_LDB(B0, 1, 0); PG8_LDB(B1, 1, 1); PG8_SCHED; PG8_LDA(At, 1, 0); PG8_STAGE(PG8_SA(0, 1), a2 + hstep, voffA);
;             PG8_WAIT_V(8); PG8_WAIT_L(0); PG8_BAR; PG8_MMA(0, 0, At, B0); PG8_MMA(0, 1, At, B1); PG8_BAR; PG8_SCHED;
.LBB0_581:
	ds_read_b128 v[154:157], v160
	ds_read_b128 v[172:175], v160 offset:1024
	ds_read_b128 v[176:179], v160 offset:2048
	ds_read_b128 v[180:183], v160 offset:3072
	ds_read_b128 v[184:187], v161
	ds_read_b128 v[188:191], v161 offset:1024
	ds_read_b128 v[192:195], v161 offset:2048
	ds_read_b128 v[196:199], v161 offset:3072
	s_add_u32 s33, s40, 0xfff80080
	s_addc_u32 s42, s41, -1
	s_cmp_eq_u32 s79, 28
	s_cselect_b32 s45, s29, s42
	s_cselect_b32 s44, s65, s33
	s_cselect_b32 s43, s27, s78
	s_cselect_b32 s42, s66, s67
	s_add_u32 s98, s40, 0xfff80000
	s_addc_u32 s99, s41, -1
	s_mov_b32 m0, s60
	v_lshl_add_u64 v[232:233], s[98:99], 0, v[132:133]
	global_load_lds_dwordx4 v[232:233], off
	s_mov_b32 m0, s61
	v_lshl_add_u64 v[232:233], s[98:99], 0, v[136:137]
	global_load_lds_dwordx4 v[232:233], off
	v_lshl_add_u64 v[232:233], s[40:41], 0, v[146:147]
	s_add_i32 m0, s55, 0xc000
	ds_read_b128 v[200:203], v164
	ds_read_b128 v[204:207], v164 offset:1024
	ds_read_b128 v[208:211], v164 offset:2048
	ds_read_b128 v[212:215], v164 offset:3072
	ds_read_b128 v[216:219], v164 offset:4096
	ds_read_b128 v[220:223], v164 offset:5120
	ds_read_b128 v[224:227], v164 offset:6144
	ds_read_b128 v[228:231], v164 offset:7168
	global_load_lds_dwordx4 v[232:233], off
	s_add_i32 m0, s55, 0xe000
	v_lshl_add_u64 v[232:233], s[40:41], 0, v[148:149]
	global_load_lds_dwordx4 v[232:233], off
	s_waitcnt vmcnt(8) lgkmcnt(0)
	s_barrier
	s_setprio 1
	v_mfma_f32_16x16x32_bf16 v[126:129], v[154:157], v[200:203], v[126:129]
	v_mfma_f32_16x16x32_bf16 v[122:125], v[176:179], v[200:203], v[122:125]
	v_mfma_f32_16x16x32_bf16 v[110:113], v[154:157], v[208:211], v[110:113]
	v_mfma_f32_16x16x32_bf16 v[106:109], v[176:179], v[208:211], v[106:109]
	v_mfma_f32_16x16x32_bf16 v[94:97], v[154:157], v[216:219], v[94:97]
	v_mfma_f32_16x16x32_bf16 v[90:93], v[176:179], v[216:219], v[90:93]
	v_mfma_f32_16x16x32_bf16 v[78:81], v[154:157], v[224:227], v[78:81]
	v_mfma_f32_16x16x32_bf16 v[74:77], v[176:179], v[224:227], v[74:77]
	v_mfma_f32_16x16x32_bf16 v[126:129], v[172:175], v[204:207], v[126:129]
	v_mfma_f32_16x16x32_bf16 v[122:125], v[180:183], v[204:207], v[122:125]
	v_mfma_f32_16x16x32_bf16 v[110:113], v[172:175], v[212:215], v[110:113]
	v_mfma_f32_16x16x32_bf16 v[106:109], v[180:183], v[212:215], v[106:109]
	v_mfma_f32_16x16x32_bf16 v[94:97], v[172:175], v[220:223], v[94:97]
	v_mfma_f32_16x16x32_bf16 v[90:93], v[180:183], v[220:223], v[90:93]
	v_mfma_f32_16x16x32_bf16 v[78:81], v[172:175], v[228:231], v[78:81]
	v_mfma_f32_16x16x32_bf16 v[74:77], v[180:183], v[228:231], v[74:77]
	s_setprio 0
	s_setprio 1
	v_mfma_f32_16x16x32_bf16 v[118:121], v[184:187], v[200:203], v[118:121]
	v_mfma_f32_16x16x32_bf16 v[114:117], v[192:195], v[200:203], v[114:117]
	v_mfma_f32_16x16x32_bf16 v[102:105], v[184:187], v[208:211], v[102:105]
	v_mfma_f32_16x16x32_bf16 v[98:101], v[192:195], v[208:211], v[98:101]
	v_mfma_f32_16x16x32_bf16 v[86:89], v[184:187], v[216:219], v[86:89]
	v_mfma_f32_16x16x32_bf16 v[82:85], v[192:195], v[216:219], v[82:85]
	v_mfma_f32_16x16x32_bf16 v[70:73], v[184:187], v[224:227], v[70:73]
	v_mfma_f32_16x16x32_bf16 v[66:69], v[192:195], v[224:227], v[66:69]
	v_mfma_f32_16x16x32_bf16 v[118:121], v[188:191], v[204:207], v[118:121]
	v_mfma_f32_16x16x32_bf16 v[114:117], v[196:199], v[204:207], v[114:117]
	v_mfma_f32_16x16x32_bf16 v[102:105], v[188:191], v[212:215], v[102:105]
	v_mfma_f32_16x16x32_bf16 v[98:101], v[196:199], v[212:215], v[98:101]
	v_mfma_f32_16x16x32_bf16 v[86:89], v[188:191], v[220:223], v[86:89]
	v_mfma_f32_16x16x32_bf16 v[82:85], v[196:199], v[220:223], v[82:85]
	v_mfma_f32_16x16x32_bf16 v[70:73], v[188:191], v[228:231], v[70:73]
	v_mfma_f32_16x16x32_bf16 v[66:69], v[196:199], v[228:231], v[66:69]
	s_setprio 0
	s_barrier
	s_add_i32 s33, s62, s53
	v_lshl_add_u64 v[232:233], s[42:43], 0, v[134:135]
	s_mov_b32 m0, s33
	ds_read_b128 v[200:203], v164 offset:16384
	ds_read_b128 v[204:207], v164 offset:17408
	ds_read_b128 v[208:211], v164 offset:18432
	ds_read_b128 v[212:215], v164 offset:19456
	ds_read_b128 v[216:219], v164 offset:20480
	ds_read_b128 v[220:223], v164 offset:21504
	ds_read_b128 v[224:227], v164 offset:22528
	ds_read_b128 v[228:231], v164 offset:23552
	global_load_lds_dwordx4 v[232:233], off
	s_add_i32 m0, s33, 0x2000
	s_add_u32 s80, s42, 0x80000
	v_lshl_add_u64 v[234:235], s[42:43], 0, v[138:139]
	s_addc_u32 s81, s43, 0
	s_add_i32 s33, s63, s53
	global_load_lds_dwordx4 v[234:235], off
	s_mov_b32 m0, s33
	v_lshl_add_u64 v[236:237], s[80:81], 0, v[134:135]
	global_load_lds_dwordx4 v[236:237], off
	s_add_i32 m0, s33, 0x2000
	v_lshl_add_u64 v[236:237], s[80:81], 0, v[138:139]
	global_load_lds_dwordx4 v[236:237], off
	s_waitcnt vmcnt(6) lgkmcnt(0)
	s_barrier
; #define PG8_STAGE(bufoff, gbase, voff) do { _Pragma("unroll") for (int _i = 0; _i < 2; ++_i) \
;         __builtin_amdgcn_global_load_lds((const unsigned*)((const char*)(gbase) + (voff)[_i]), (PG8_LAS unsigned*)(lds + (bufoff) + ldsw + _i * 8192), 16, 0, 0); } while (0)
; #define PG8_LDA(dst, b, h) do { _Pragma("unroll") for (int m = 0; m < 4; ++m) _Pragma("unroll") for (int k = 0; k < 2; ++k) dst[m][k] = *(const PG8_LAS bf16x8*)(lds + PG8_SA(b, h) + aoff + m * 2048 + k * 1024); } while (0)
; #define PG8_LDB(dst, b, h) do { _Pragma("unroll") for (int n = 0; n < 2; ++n) _Pragma("unroll") for (int k = 0; k < 2; ++k) dst[n][k] = *(const PG8_LAS bf16x8*)(lds + PG8_SB(b, h) + boff + n * 2048 + k * 1024); } while (0)
; #define PG8_MMA(ai, bj, At, Bt) do { __builtin_amdgcn_s_setprio(1); _Pragma("unroll") for (int m = 0; m < 4; ++m) _Pragma("unroll") for (int n = 0; n < 2; ++n) _Pragma("unroll") for (int k = 0; k < 2; ++k) \
;         acc[ai][bj][m][n] = __builtin_amdgcn_mfma_f32_16x16x32_bf16(Bt[n][k], At[m][k], acc[ai][bj][m][n], 0, 0, 0); __builtin_amdgcn_s_setprio(0); } while (0)
; #define PG8_WAIT_V(n) asm volatile("s_waitcnt vmcnt(" #n ")" ::: "memory")
; #define PG8_WAIT_L(n) asm volatile("s_waitcnt lgkmcnt(" #n ")" ::: "memory")
; #define PG8_BAR __builtin_amdgcn_s_barrier()
; #define PG8_SCHED __builtin_amdgcn_sched_barrier(0)
; template <class Epi, class Sched, bool ALIGN_EPI = false, bool SP2 = false, bool KSEG = false>
; __device__ __forceinline__ void gemm_phase(PG8_LAS unsigned char* lds, const Gemm g, const Sched& S, const Epi& E) {
;     ...
;             PG8_WAIT_V(8); PG8_WAIT_L(0); PG8_BAR; PG8_MMA(1, 0, At, B0); PG8_MMA(1, 1, At, B1); PG8_BAR; PG8_SCHED;
;             PG8_LDB(B0, 1, 0); PG8_LDB(B1, 1, 1); PG8_SCHED; PG8_LDA(At, 1, 0); PG8_STAGE(PG8_SA(0, 1), a2 + hstep, voffA);
;             PG8_WAIT_V(8); PG8_WAIT_L(0); PG8_BAR; PG8_MMA(0, 0, At, B0); PG8_MMA(0, 1, At, B1); PG8_BAR; PG8_SCHED;
	s_setprio 1
	v_mfma_f32_16x16x32_bf16 v[62:65], v[154:157], v[200:203], v[62:65]
	v_mfma_f32_16x16x32_bf16 v[58:61], v[176:179], v[200:203], v[58:61]
	v_mfma_f32_16x16x32_bf16 v[46:49], v[154:157], v[208:211], v[46:49]
	v_mfma_f32_16x16x32_bf16 v[42:45], v[176:179], v[208:211], v[42:45]
	v_mfma_f32_16x16x32_bf16 v[30:33], v[154:157], v[216:219], v[30:33]
	v_mfma_f32_16x16x32_bf16 v[26:29], v[176:179], v[216:219], v[26:29]
	v_mfma_f32_16x16x32_bf16 v[14:17], v[154:157], v[224:227], v[14:17]
	v_mfma_f32_16x16x32_bf16 v[10:13], v[176:179], v[224:227], v[10:13]
	v_mfma_f32_16x16x32_bf16 v[62:65], v[172:175], v[204:207], v[62:65]
	v_mfma_f32_16x16x32_bf16 v[58:61], v[180:183], v[204:207], v[58:61]
	v_mfma_f32_16x16x32_bf16 v[46:49], v[172:175], v[212:215], v[46:49]
	v_mfma_f32_16x16x32_bf16 v[42:45], v[180:183], v[212:215], v[42:45]
	v_mfma_f32_16x16x32_bf16 v[30:33], v[172:175], v[220:223], v[30:33]
	v_mfma_f32_16x16x32_bf16 v[26:29], v[180:183], v[220:223], v[26:29]
	v_mfma_f32_16x16x32_bf16 v[14:17], v[172:175], v[228:231], v[14:17]
	v_mfma_f32_16x16x32_bf16 v[10:13], v[180:183], v[228:231], v[10:13]
	s_setprio 0
	s_setprio 1
	v_mfma_f32_16x16x32_bf16 v[54:57], v[184:187], v[200:203], v[54:57]
	v_mfma_f32_16x16x32_bf16 v[50:53], v[192:195], v[200:203], v[50:53]
	v_mfma_f32_16x16x32_bf16 v[38:41], v[184:187], v[208:211], v[38:41]
	v_mfma_f32_16x16x32_bf16 v[34:37], v[192:195], v[208:211], v[34:37]
	v_mfma_f32_16x16x32_bf16 v[22:25], v[184:187], v[216:219], v[22:25]
	v_mfma_f32_16x16x32_bf16 v[18:21], v[192:195], v[216:219], v[18:21]
	v_mfma_f32_16x16x32_bf16 v[6:9], v[184:187], v[224:227], v[6:9]
	v_mfma_f32_16x16x32_bf16 v[2:5], v[192:195], v[224:227], v[2:5]
	v_mfma_f32_16x16x32_bf16 v[54:57], v[188:191], v[204:207], v[54:57]
	v_mfma_f32_16x16x32_bf16 v[50:53], v[196:199], v[204:207], v[50:53]
	v_mfma_f32_16x16x32_bf16 v[38:41], v[188:191], v[212:215], v[38:41]
	v_mfma_f32_16x16x32_bf16 v[34:37], v[196:199], v[212:215], v[34:37]
	v_mfma_f32_16x16x32_bf16 v[22:25], v[188:191], v[220:223], v[22:25]
	v_mfma_f32_16x16x32_bf16 v[18:21], v[196:199], v[220:223], v[18:21]
	v_mfma_f32_16x16x32_bf16 v[6:9], v[188:191], v[228:231], v[6:9]
	v_mfma_f32_16x16x32_bf16 v[2:5], v[196:199], v[228:231], v[2:5]
	s_setprio 0
	s_barrier
	s_add_i32 s33, 0, 0x18000
	s_add_i32 s80, 0, 0x1c000
	v_add_u32_e32 v180, s33, v163
	v_add_u32_e32 v196, s80, v163
	ds_read_b128 v[154:157], v180
	ds_read_b128 v[172:175], v180 offset:1024
	ds_read_b128 v[176:179], v180 offset:2048
	ds_read_b128 v[180:183], v180 offset:3072
	ds_read_b128 v[184:187], v196
	ds_read_b128 v[188:191], v196 offset:1024
	ds_read_b128 v[192:195], v196 offset:2048
	ds_read_b128 v[196:199], v196 offset:3072
	s_mov_b32 m0, s55
	v_lshl_add_u64 v[240:241], s[44:45], 0, v[132:133]
	global_load_lds_dwordx4 v[240:241], off
	s_mov_b32 m0, s56
	v_lshl_add_u64 v[240:241], s[44:45], 0, v[136:137]
	global_load_lds_dwordx4 v[240:241], off
	s_add_u32 s44, s44, 0x80000
	s_addc_u32 s45, s45, 0
	s_mov_b32 m0, s57
	v_lshl_add_u64 v[240:241], s[44:45], 0, v[132:133]
	ds_read_b128 v[200:203], v164 offset:32768
	ds_read_b128 v[204:207], v164 offset:33792
	ds_read_b128 v[208:211], v164 offset:34816
	ds_read_b128 v[212:215], v164 offset:35840
	ds_read_b128 v[216:219], v164 offset:36864
	ds_read_b128 v[220:223], v164 offset:37888
	ds_read_b128 v[224:227], v164 offset:38912
	ds_read_b128 v[228:231], v164 offset:39936
	global_load_lds_dwordx4 v[240:241], off
	s_mov_b32 m0, s58
	v_lshl_add_u64 v[240:241], s[44:45], 0, v[136:137]
	global_load_lds_dwordx4 v[240:241], off
	s_waitcnt vmcnt(8) lgkmcnt(0)
	s_barrier
	s_setprio 1
	v_mfma_f32_16x16x32_bf16 v[126:129], v[154:157], v[200:203], v[126:129]
	v_mfma_f32_16x16x32_bf16 v[122:125], v[176:179], v[200:203], v[122:125]
	v_mfma_f32_16x16x32_bf16 v[110:113], v[154:157], v[208:211], v[110:113]
	v_mfma_f32_16x16x32_bf16 v[106:109], v[176:179], v[208:211], v[106:109]
	v_mfma_f32_16x16x32_bf16 v[94:97], v[154:157], v[216:219], v[94:97]
	v_mfma_f32_16x16x32_bf16 v[90:93], v[176:179], v[216:219], v[90:93]
	v_mfma_f32_16x16x32_bf16 v[78:81], v[154:157], v[224:227], v[78:81]
	v_mfma_f32_16x16x32_bf16 v[74:77], v[176:179], v[224:227], v[74:77]
	v_mfma_f32_16x16x32_bf16 v[126:129], v[172:175], v[204:207], v[126:129]
	v_mfma_f32_16x16x32_bf16 v[122:125], v[180:183], v[204:207], v[122:125]
	v_mfma_f32_16x16x32_bf16 v[110:113], v[172:175], v[212:215], v[110:113]
	v_mfma_f32_16x16x32_bf16 v[106:109], v[180:183], v[212:215], v[106:109]
	v_mfma_f32_16x16x32_bf16 v[94:97], v[172:175], v[220:223], v[94:97]
	v_mfma_f32_16x16x32_bf16 v[90:93], v[180:183], v[220:223], v[90:93]
	v_mfma_f32_16x16x32_bf16 v[78:81], v[172:175], v[228:231], v[78:81]
	v_mfma_f32_16x16x32_bf16 v[74:77], v[180:183], v[228:231], v[74:77]
	s_setprio 0
	s_setprio 1
	v_mfma_f32_16x16x32_bf16 v[118:121], v[184:187], v[200:203], v[118:121]
	v_mfma_f32_16x16x32_bf16 v[114:117], v[192:195], v[200:203], v[114:117]
	v_mfma_f32_16x16x32_bf16 v[102:105], v[184:187], v[208:211], v[102:105]
	v_mfma_f32_16x16x32_bf16 v[98:101], v[192:195], v[208:211], v[98:101]
	v_mfma_f32_16x16x32_bf16 v[86:89], v[184:187], v[216:219], v[86:89]
	v_mfma_f32_16x16x32_bf16 v[82:85], v[192:195], v[216:219], v[82:85]
	v_mfma_f32_16x16x32_bf16 v[70:73], v[184:187], v[224:227], v[70:73]
	v_mfma_f32_16x16x32_bf16 v[66:69], v[192:195], v[224:227], v[66:69]
	v_mfma_f32_16x16x32_bf16 v[118:121], v[188:191], v[204:207], v[118:121]
	v_mfma_f32_16x16x32_bf16 v[114:117], v[196:199], v[204:207], v[114:117]
	v_mfma_f32_16x16x32_bf16 v[102:105], v[188:191], v[212:215], v[102:105]
	v_mfma_f32_16x16x32_bf16 v[98:101], v[196:199], v[212:215], v[98:101]
	v_mfma_f32_16x16x32_bf16 v[86:89], v[188:191], v[220:223], v[86:89]
	v_mfma_f32_16x16x32_bf16 v[82:85], v[196:199], v[220:223], v[82:85]
	v_mfma_f32_16x16x32_bf16 v[70:73], v[188:191], v[228:231], v[70:73]
	v_mfma_f32_16x16x32_bf16 v[66:69], v[196:199], v[228:231], v[66:69]
	s_setprio 0
	s_barrier
; #define PG8_STAGE(bufoff, gbase, voff) do { _Pragma("unroll") for (int _i = 0; _i < 2; ++_i) \
;         __builtin_amdgcn_global_load_lds((const unsigned*)((const char*)(gbase) + (voff)[_i]), (PG8_LAS unsigned*)(lds + (bufoff) + ldsw + _i * 8192), 16, 0, 0); } while (0)
; #define PG8_LDA(dst, b, h) do { _Pragma("unroll") for (int m = 0; m < 4; ++m) _Pragma("unroll") for (int k = 0; k < 2; ++k) dst[m][k] = *(const PG8_LAS bf16x8*)(lds + PG8_SA(b, h) + aoff + m * 2048 + k * 1024); } while (0)
; #define PG8_MMA(ai, bj, At, Bt) do { __builtin_amdgcn_s_setprio(1); _Pragma("unroll") for (int m = 0; m < 4; ++m) _Pragma("unroll") for (int n = 0; n < 2; ++n) _Pragma("unroll") for (int k = 0; k < 2; ++k) \
;         acc[ai][bj][m][n] = __builtin_amdgcn_mfma_f32_16x16x32_bf16(Bt[n][k], At[m][k], acc[ai][bj][m][n], 0, 0, 0); __builtin_amdgcn_s_setprio(0); } while (0)
; #define PG8_WAIT_V(n) asm volatile("s_waitcnt vmcnt(" #n ")" ::: "memory")
; #define PG8_WAIT_L(n) asm volatile("s_waitcnt lgkmcnt(" #n ")" ::: "memory")
; #define PG8_BAR __builtin_amdgcn_s_barrier()
; #define PG8_SCHED __builtin_amdgcn_sched_barrier(0)
; template <class Epi, class Sched, bool ALIGN_EPI = false, bool SP2 = false, bool KSEG = false>
; __device__ __forceinline__ void gemm_phase(PG8_LAS unsigned char* lds, const Gemm g, const Sched& S, const Epi& E) {
;     ...
;             PG8_LDA(At, 1, 1); PG8_STAGE(PG8_SB(1, 0), b3, voffB); PG8_STAGE(PG8_SB(1, 1), b3 + hstep, voffB); PG8_STAGE(PG8_SA(1, 0), a3, voffA);
;             PG8_WAIT_V(8); PG8_WAIT_L(0); PG8_BAR; PG8_MMA(1, 0, At, B0); PG8_MMA(1, 1, At, B1); PG8_BAR; PG8_SCHED;
;     __device__ __forceinline__ void operator()(const f32x4 (&acc)[2][2][4][2], const Unit& u, int wr, int wc, int fr, int fq) const {
;         const int row0 = u.pm * BM + wr * 64 + fr, col0 = u.pn * HALF + wc * 32 + 8 * fq;
; #pragma unroll
;         for (int ai = 0; ai < 2; ++ai)
; #pragma unroll
;             for (int m = 0; m < 4; ++m) { const int row = row0 + ai * HALF + m * 16; const float rs = __builtin_amdgcn_rsqf(ss[row_base + row] * (1.0f / 2048.0f) + 1e-6f);
;                 float a[8];
	s_add_i32 s33, s33, s53
	v_lshl_add_u64 v[232:233], v[232:233], 0, s[12:13]
	s_mov_b32 m0, s33
	ds_read_b128 v[200:203], v164 offset:49152
	ds_read_b128 v[204:207], v164 offset:50176
	ds_read_b128 v[208:211], v164 offset:51200
	ds_read_b128 v[212:215], v164 offset:52224
	ds_read_b128 v[216:219], v164 offset:53248
	ds_read_b128 v[220:223], v164 offset:54272
	ds_read_b128 v[224:227], v164 offset:55296
	ds_read_b128 v[228:231], v164 offset:56320
	global_load_lds_dwordx4 v[232:233], off
	s_add_i32 m0, s33, 0x2000
	s_add_u32 s42, s42, 0x80080
	v_lshl_add_u64 v[232:233], v[234:235], 0, s[12:13]
	s_addc_u32 s43, s43, 0
	s_add_i32 s33, s80, s53
	global_load_lds_dwordx4 v[232:233], off
	s_mov_b32 m0, s33
	v_lshl_add_u64 v[232:233], s[42:43], 0, v[134:135]
	global_load_lds_dwordx4 v[232:233], off
	s_add_i32 m0, s33, 0x2000
	v_lshl_add_u64 v[232:233], s[42:43], 0, v[138:139]
	global_load_lds_dwordx4 v[232:233], off
	s_waitcnt vmcnt(6) lgkmcnt(0)
	s_barrier
	s_setprio 1
	v_mfma_f32_16x16x32_bf16 v[62:65], v[154:157], v[200:203], v[62:65]
	v_mfma_f32_16x16x32_bf16 v[58:61], v[176:179], v[200:203], v[58:61]
	v_mfma_f32_16x16x32_bf16 v[46:49], v[154:157], v[208:211], v[46:49]
	v_mfma_f32_16x16x32_bf16 v[42:45], v[176:179], v[208:211], v[42:45]
	v_mfma_f32_16x16x32_bf16 v[30:33], v[154:157], v[216:219], v[30:33]
	v_mfma_f32_16x16x32_bf16 v[26:29], v[176:179], v[216:219], v[26:29]
	v_mfma_f32_16x16x32_bf16 v[14:17], v[154:157], v[224:227], v[14:17]
	v_mfma_f32_16x16x32_bf16 v[10:13], v[176:179], v[224:227], v[10:13]
	v_mfma_f32_16x16x32_bf16 v[62:65], v[172:175], v[204:207], v[62:65]
	v_mfma_f32_16x16x32_bf16 v[58:61], v[180:183], v[204:207], v[58:61]
	v_mfma_f32_16x16x32_bf16 v[46:49], v[172:175], v[212:215], v[46:49]
	v_mfma_f32_16x16x32_bf16 v[42:45], v[180:183], v[212:215], v[42:45]
	v_mfma_f32_16x16x32_bf16 v[30:33], v[172:175], v[220:223], v[30:33]
	v_mfma_f32_16x16x32_bf16 v[26:29], v[180:183], v[220:223], v[26:29]
	v_mfma_f32_16x16x32_bf16 v[14:17], v[172:175], v[228:231], v[14:17]
	v_mfma_f32_16x16x32_bf16 v[10:13], v[180:183], v[228:231], v[10:13]
	s_setprio 0
	s_setprio 1
	v_mfma_f32_16x16x32_bf16 v[54:57], v[184:187], v[200:203], v[54:57]
	v_mfma_f32_16x16x32_bf16 v[50:53], v[192:195], v[200:203], v[50:53]
	v_mfma_f32_16x16x32_bf16 v[38:41], v[184:187], v[208:211], v[38:41]
	v_mfma_f32_16x16x32_bf16 v[34:37], v[192:195], v[208:211], v[34:37]
	v_mfma_f32_16x16x32_bf16 v[22:25], v[184:187], v[216:219], v[22:25]
	v_mfma_f32_16x16x32_bf16 v[18:21], v[192:195], v[216:219], v[18:21]
	v_mfma_f32_16x16x32_bf16 v[6:9], v[184:187], v[224:227], v[6:9]
	v_mfma_f32_16x16x32_bf16 v[2:5], v[192:195], v[224:227], v[2:5]
	v_mfma_f32_16x16x32_bf16 v[54:57], v[188:191], v[204:207], v[54:57]
	v_mfma_f32_16x16x32_bf16 v[50:53], v[196:199], v[204:207], v[50:53]
	v_mfma_f32_16x16x32_bf16 v[38:41], v[188:191], v[212:215], v[38:41]
	v_mfma_f32_16x16x32_bf16 v[34:37], v[196:199], v[212:215], v[34:37]
	v_mfma_f32_16x16x32_bf16 v[22:25], v[188:191], v[220:223], v[22:25]
	v_mfma_f32_16x16x32_bf16 v[18:21], v[196:199], v[220:223], v[18:21]
	v_mfma_f32_16x16x32_bf16 v[6:9], v[188:191], v[228:231], v[6:9]
	v_mfma_f32_16x16x32_bf16 v[2:5], v[196:199], v[228:231], v[2:5]
	s_setprio 0
	s_barrier
	s_add_i32 s79, s79, 2
	s_add_u32 s40, s40, 0x100
	s_addc_u32 s41, s41, 0
	s_add_u32 s67, s67, 0x100
	s_addc_u32 s78, s78, 0
	s_cmp_lt_u32 s79, 30
	s_cbranch_scc1 .LBB0_581
	s_andn2_b64 vcc, exec, s[24:25]
	s_cbranch_vccnz .LBB0_584
	s_barrier
.LBB0_584:
	v_lshl_add_u32 v154, s38, 8, v170
	v_ashrrev_i32_e32 v155, 31, v154
	v_lshl_add_u64 v[156:157], v[154:155], 2, s[18:19]
	v_add_co_u32_e32 v156, vcc, 0x10000, v156
	v_mov_b32_e32 v176, v124
	s_nop 0
	v_addc_co_u32_e32 v157, vcc, 0, v157, vcc
	global_load_dword v155, v[156:157], off
	global_load_dword v243, v[156:157], off offset:64
	global_load_dword v244, v[156:157], off offset:128
	global_load_dword v245, v[156:157], off offset:192
	global_load_dword v246, v[156:157], off offset:512
	global_load_dword v247, v[156:157], off offset:576
	global_load_dword v248, v[156:157], off offset:640
	global_load_dword v249, v[156:157], off offset:704
	v_mov_b32_e32 v177, v116
	v_mov_b32_e32 v116, v125
	v_mov_b32_e32 v174, v126
	v_mov_b32_e32 v175, v118
	v_mov_b32_e32 v118, v127
	v_mov_b32_e32 v126, v128
	v_mov_b32_e32 v127, v120
	v_mov_b32_e32 v120, v129
	v_mov_b32_e32 v128, v122
	v_mov_b32_e32 v129, v114
	v_mov_b32_e32 v114, v123
	v_lshl_or_b32 v172, s39, 7, v162
	v_mov_b64_e32 v[122:123], s[74:75]
	v_ashrrev_i32_e32 v173, 31, v172
	v_mad_i64_i32 v[180:181], s[38:39], v154, s64, v[122:123]
	s_and_b64 vcc, s[6:7], exec
	s_waitcnt vmcnt(0)
; __device__ __forceinline__ unsigned cvt_pk_bf16(float lo, float hi) { unsigned r; asm volatile("v_cvt_pk_bf16_f32 %0, %1, %2" : "=v"(r) : "v"(lo), "v"(hi)); return r; }
;     __device__ __forceinline__ void operator()(const f32x4 (&acc)[2][2][4][2], const Unit& u, int wr, int wc, int fr, int fq) const {
;     ...
;             for (int m = 0; m < 4; ++m) { const int row = row0 + ai * HALF + m * 16; const float rs = __builtin_amdgcn_rsqf(ss[row_base + row] * (1.0f / 2048.0f) + 1e-6f);
;                 float a[8];
; #pragma unroll
;                 for (int n = 0; n < 2; ++n)
; #pragma unroll
;                     for (int j = 0; j < 4; ++j) { const float g = acc[ai][0][m][n][j] * rs, uu = acc[ai][1][m][n][j] * rs;
;                         a[n * 4 + j] = g * uu * __builtin_amdgcn_rcpf(1.0f + __builtin_amdgcn_exp2f(-1.4426950408889634f * g)); }
;                 u32x4 w; w.x = cvt_pk_bf16(a[0], a[1]); w.y = cvt_pk_bf16(a[2], a[3]); w.z = cvt_pk_bf16(a[4], a[5]); w.w = cvt_pk_bf16(a[6], a[7]);
;                 *(u32x4*)(act + (size_t)row * 5632 + col0) = w; }
	v_fmamk_f32 v124, v155, 0x3a000000, v171
	v_rsq_f32_e32 v178, v124
	v_lshlrev_b64 v[124:125], 1, v[172:173]
	v_lshl_add_u64 v[172:173], v[180:181], 0, v[124:125]
	v_pk_mul_f32 v[116:117], v[116:117], v[178:179] op_sel_hi:[1,0]
	v_pk_mul_f32 v[174:175], v[174:175], v[178:179] op_sel_hi:[1,0]
	v_pk_mul_f32 v[118:119], v[118:119], v[178:179] op_sel_hi:[1,0]
	v_pk_mul_f32 v[126:127], v[126:127], v[178:179] op_sel_hi:[1,0]
	v_pk_mul_f32 v[120:121], v[120:121], v[178:179] op_sel_hi:[1,0]
	v_pk_mul_f32 v[128:129], v[128:129], v[178:179] op_sel_hi:[1,0]
	v_pk_mul_f32 v[114:115], v[114:115], v[178:179] op_sel_hi:[1,0]
	v_pk_mul_f32 v[176:177], v[176:177], v[178:179] op_sel_hi:[1,0]
	v_mul_f32_e32 v117, v116, v117
	v_mul_f32_e32 v116, 0xbfb8aa3b, v116
	v_mul_f32_e32 v155, v174, v175
	v_mul_f32_e32 v174, 0xbfb8aa3b, v174
	v_mul_f32_e32 v119, v118, v119
	v_mul_f32_e32 v118, 0xbfb8aa3b, v118
	v_mul_f32_e32 v127, v126, v127
	v_mul_f32_e32 v126, 0xbfb8aa3b, v126
	v_mul_f32_e32 v121, v120, v121
	v_mul_f32_e32 v120, 0xbfb8aa3b, v120
	v_mul_f32_e32 v129, v128, v129
	v_mul_f32_e32 v128, 0xbfb8aa3b, v128
	v_mul_f32_e32 v115, v114, v115
	v_mul_f32_e32 v114, 0xbfb8aa3b, v114
	v_mul_f32_e32 v175, v176, v177
	v_mul_f32_e32 v176, 0xbfb8aa3b, v176
	v_exp_f32_e32 v116, v116
	v_exp_f32_e32 v174, v174
	v_exp_f32_e32 v118, v118
	v_exp_f32_e32 v126, v126
	v_exp_f32_e32 v120, v120
	v_exp_f32_e32 v128, v128
	v_exp_f32_e32 v114, v114
	v_exp_f32_e32 v176, v176
	v_add_f32_e32 v116, 1.0, v116
	v_add_f32_e32 v174, 1.0, v174
	v_add_f32_e32 v118, 1.0, v118
	v_add_f32_e32 v126, 1.0, v126
	v_add_f32_e32 v120, 1.0, v120
	v_add_f32_e32 v128, 1.0, v128
	v_add_f32_e32 v114, 1.0, v114
	v_add_f32_e32 v176, 1.0, v176
	v_rcp_f32_e32 v116, v116
	v_rcp_f32_e32 v174, v174
	v_rcp_f32_e32 v118, v118
	v_rcp_f32_e32 v126, v126
	v_rcp_f32_e32 v120, v120
	v_rcp_f32_e32 v128, v128
	v_rcp_f32_e32 v114, v114
	v_rcp_f32_e32 v176, v176
	v_mul_f32_e32 v117, v117, v116
	v_mul_f32_e32 v155, v155, v174
	v_mul_f32_e32 v118, v119, v118
	v_mul_f32_e32 v119, v127, v126
	v_mul_f32_e32 v120, v121, v120
	v_mul_f32_e32 v121, v129, v128
	v_mul_f32_e32 v126, v115, v114
	v_mul_f32_e32 v127, v175, v176
	v_cvt_pk_bf16_f32 v114, v155, v118
	v_cvt_pk_bf16_f32 v115, v119, v120
	v_cvt_pk_bf16_f32 v116, v121, v126
	v_cvt_pk_bf16_f32 v117, v127, v117
	global_store_dwordx4 v[172:173], v[114:117], off
	s_nop 0
	s_nop 0
	v_mov_b32_e32 v114, v110
	v_mov_b32_e32 v110, v112
	v_mov_b32_e32 v112, v106
	v_mov_b32_e32 v106, v108
	v_mov_b32_e32 v115, v102
	v_mov_b32_e32 v102, v111
	v_mov_b32_e32 v111, v104
	v_mov_b32_e32 v104, v113
	v_mov_b32_e32 v113, v98
	v_mov_b32_e32 v98, v107
	v_mov_b32_e32 v107, v100
	v_mov_b32_e32 v100, v109
	v_or_b32_e32 v109, 16, v154
	v_fmamk_f32 v108, v243, 0x3a000000, v171
	v_rsq_f32_e32 v108, v108
	v_mad_i64_i32 v[116:117], s[38:39], v109, s64, v[122:123]
	v_lshl_add_u64 v[116:117], v[116:117], 0, v[124:125]
	v_pk_mul_f32 v[100:101], v[100:101], v[108:109] op_sel_hi:[1,0]
	v_pk_mul_f32 v[114:115], v[114:115], v[108:109] op_sel_hi:[1,0]
	v_pk_mul_f32 v[102:103], v[102:103], v[108:109] op_sel_hi:[1,0]
	v_pk_mul_f32 v[110:111], v[110:111], v[108:109] op_sel_hi:[1,0]
	v_pk_mul_f32 v[104:105], v[104:105], v[108:109] op_sel_hi:[1,0]
	v_pk_mul_f32 v[112:113], v[112:113], v[108:109] op_sel_hi:[1,0]
	v_pk_mul_f32 v[98:99], v[98:99], v[108:109] op_sel_hi:[1,0]
	v_pk_mul_f32 v[106:107], v[106:107], v[108:109] op_sel_hi:[1,0]
	v_mul_f32_e32 v101, v100, v101
	v_mul_f32_e32 v100, 0xbfb8aa3b, v100
	v_mul_f32_e32 v109, 0xbfb8aa3b, v114
	v_mul_f32_e32 v103, v102, v103
	v_mul_f32_e32 v102, 0xbfb8aa3b, v102
	v_mul_f32_e32 v111, v110, v111
	v_mul_f32_e32 v110, 0xbfb8aa3b, v110
	v_mul_f32_e32 v105, v104, v105
	v_mul_f32_e32 v104, 0xbfb8aa3b, v104
	v_mul_f32_e32 v113, v112, v113
	v_mul_f32_e32 v112, 0xbfb8aa3b, v112
	v_mul_f32_e32 v99, v98, v99
	v_mul_f32_e32 v98, 0xbfb8aa3b, v98
	v_mul_f32_e32 v107, v106, v107
	v_mul_f32_e32 v106, 0xbfb8aa3b, v106
	v_exp_f32_e32 v100, v100
	v_exp_f32_e32 v109, v109
	v_exp_f32_e32 v102, v102
	v_exp_f32_e32 v110, v110
	v_exp_f32_e32 v104, v104
	v_exp_f32_e32 v112, v112
	v_exp_f32_e32 v98, v98
	v_exp_f32_e32 v106, v106
	v_add_f32_e32 v100, 1.0, v100
	v_add_f32_e32 v109, 1.0, v109
	v_add_f32_e32 v102, 1.0, v102
	v_add_f32_e32 v110, 1.0, v110
	v_add_f32_e32 v104, 1.0, v104
	v_add_f32_e32 v112, 1.0, v112
	v_add_f32_e32 v98, 1.0, v98
	v_add_f32_e32 v106, 1.0, v106
	v_rcp_f32_e32 v100, v100
	v_rcp_f32_e32 v109, v109
	v_rcp_f32_e32 v102, v102
	v_rcp_f32_e32 v110, v110
	v_rcp_f32_e32 v104, v104
	v_rcp_f32_e32 v112, v112
	v_rcp_f32_e32 v98, v98
	v_rcp_f32_e32 v106, v106
	v_mul_f32_e32 v108, v114, v115
	v_mul_f32_e32 v101, v101, v100
	v_mul_f32_e32 v108, v108, v109
	v_mul_f32_e32 v102, v103, v102
	v_mul_f32_e32 v103, v111, v110
	v_mul_f32_e32 v104, v105, v104
	v_mul_f32_e32 v105, v113, v112
	v_mul_f32_e32 v109, v99, v98
	v_mul_f32_e32 v106, v107, v106
	v_cvt_pk_bf16_f32 v98, v108, v102
	v_cvt_pk_bf16_f32 v99, v103, v104
	v_cvt_pk_bf16_f32 v100, v105, v109
	v_cvt_pk_bf16_f32 v101, v106, v101
	global_store_dwordx4 v[116:117], v[98:101], off
	s_nop 0
	s_nop 0
	v_mov_b32_e32 v98, v94
	v_mov_b32_e32 v94, v96
	v_mov_b32_e32 v96, v90
	v_mov_b32_e32 v90, v92
	v_mov_b32_e32 v99, v86
	v_mov_b32_e32 v86, v95
	v_mov_b32_e32 v95, v88
	v_mov_b32_e32 v88, v97
	v_mov_b32_e32 v97, v82
	v_mov_b32_e32 v82, v91
	v_mov_b32_e32 v91, v84
	v_mov_b32_e32 v84, v93
	v_or_b32_e32 v93, 32, v154
	v_fmamk_f32 v92, v244, 0x3a000000, v171
	v_rsq_f32_e32 v92, v92
	v_mad_i64_i32 v[100:101], s[38:39], v93, s64, v[122:123]
	v_lshl_add_u64 v[100:101], v[100:101], 0, v[124:125]
	v_pk_mul_f32 v[84:85], v[84:85], v[92:93] op_sel_hi:[1,0]
; __device__ __forceinline__ unsigned cvt_pk_bf16(float lo, float hi) { unsigned r; asm volatile("v_cvt_pk_bf16_f32 %0, %1, %2" : "=v"(r) : "v"(lo), "v"(hi)); return r; }
;     __device__ __forceinline__ void operator()(const f32x4 (&acc)[2][2][4][2], const Unit& u, int wr, int wc, int fr, int fq) const {
;     ...
;             for (int m = 0; m < 4; ++m) { const int row = row0 + ai * HALF + m * 16; const float rs = __builtin_amdgcn_rsqf(ss[row_base + row] * (1.0f / 2048.0f) + 1e-6f);
;                 float a[8];
; #pragma unroll
;                 for (int n = 0; n < 2; ++n)
; #pragma unroll
;                     for (int j = 0; j < 4; ++j) { const float g = acc[ai][0][m][n][j] * rs, uu = acc[ai][1][m][n][j] * rs;
;                         a[n * 4 + j] = g * uu * __builtin_amdgcn_rcpf(1.0f + __builtin_amdgcn_exp2f(-1.4426950408889634f * g)); }
;                 u32x4 w; w.x = cvt_pk_bf16(a[0], a[1]); w.y = cvt_pk_bf16(a[2], a[3]); w.z = cvt_pk_bf16(a[4], a[5]); w.w = cvt_pk_bf16(a[6], a[7]);
;                 *(u32x4*)(act + (size_t)row * 5632 + col0) = w; }
	v_pk_mul_f32 v[98:99], v[98:99], v[92:93] op_sel_hi:[1,0]
	v_pk_mul_f32 v[86:87], v[86:87], v[92:93] op_sel_hi:[1,0]
	v_pk_mul_f32 v[94:95], v[94:95], v[92:93] op_sel_hi:[1,0]
	v_pk_mul_f32 v[88:89], v[88:89], v[92:93] op_sel_hi:[1,0]
	v_pk_mul_f32 v[96:97], v[96:97], v[92:93] op_sel_hi:[1,0]
	v_pk_mul_f32 v[82:83], v[82:83], v[92:93] op_sel_hi:[1,0]
	v_pk_mul_f32 v[90:91], v[90:91], v[92:93] op_sel_hi:[1,0]
	v_mul_f32_e32 v85, v84, v85
	v_mul_f32_e32 v84, 0xbfb8aa3b, v84
	v_mul_f32_e32 v93, 0xbfb8aa3b, v98
	v_mul_f32_e32 v87, v86, v87
	v_mul_f32_e32 v86, 0xbfb8aa3b, v86
	v_mul_f32_e32 v95, v94, v95
	v_mul_f32_e32 v94, 0xbfb8aa3b, v94
	v_mul_f32_e32 v89, v88, v89
	v_mul_f32_e32 v88, 0xbfb8aa3b, v88
	v_mul_f32_e32 v97, v96, v97
	v_mul_f32_e32 v96, 0xbfb8aa3b, v96
	v_mul_f32_e32 v83, v82, v83
	v_mul_f32_e32 v82, 0xbfb8aa3b, v82
	v_mul_f32_e32 v91, v90, v91
	v_mul_f32_e32 v90, 0xbfb8aa3b, v90
	v_exp_f32_e32 v84, v84
	v_exp_f32_e32 v93, v93
	v_exp_f32_e32 v86, v86
	v_exp_f32_e32 v94, v94
	v_exp_f32_e32 v88, v88
	v_exp_f32_e32 v96, v96
	v_exp_f32_e32 v82, v82
	v_exp_f32_e32 v90, v90
	v_add_f32_e32 v84, 1.0, v84
	v_add_f32_e32 v93, 1.0, v93
	v_add_f32_e32 v86, 1.0, v86
	v_add_f32_e32 v94, 1.0, v94
	v_add_f32_e32 v88, 1.0, v88
	v_add_f32_e32 v96, 1.0, v96
	v_add_f32_e32 v82, 1.0, v82
	v_add_f32_e32 v90, 1.0, v90
	v_rcp_f32_e32 v84, v84
	v_rcp_f32_e32 v93, v93
	v_rcp_f32_e32 v86, v86
	v_rcp_f32_e32 v94, v94
	v_rcp_f32_e32 v88, v88
	v_rcp_f32_e32 v96, v96
	v_rcp_f32_e32 v82, v82
	v_rcp_f32_e32 v90, v90
	v_mul_f32_e32 v92, v98, v99
	v_mul_f32_e32 v85, v85, v84
	v_mul_f32_e32 v92, v92, v93
	v_mul_f32_e32 v86, v87, v86
	v_mul_f32_e32 v87, v95, v94
	v_mul_f32_e32 v88, v89, v88
	v_mul_f32_e32 v89, v97, v96
	v_mul_f32_e32 v93, v83, v82
	v_mul_f32_e32 v90, v91, v90
	v_cvt_pk_bf16_f32 v82, v92, v86
	v_cvt_pk_bf16_f32 v83, v87, v88
	v_cvt_pk_bf16_f32 v84, v89, v93
	v_cvt_pk_bf16_f32 v85, v90, v85
	global_store_dwordx4 v[100:101], v[82:85], off
	s_nop 0
	s_nop 0
	v_mov_b32_e32 v82, v78
	v_mov_b32_e32 v78, v80
	v_mov_b32_e32 v80, v74
	v_mov_b32_e32 v74, v76
	v_mov_b32_e32 v83, v70
	v_mov_b32_e32 v70, v79
	v_mov_b32_e32 v79, v72
	v_mov_b32_e32 v72, v81
	v_mov_b32_e32 v81, v66
	v_mov_b32_e32 v66, v75
	v_mov_b32_e32 v75, v68
	v_mov_b32_e32 v68, v77
	v_or_b32_e32 v77, 48, v154
	v_fmamk_f32 v76, v245, 0x3a000000, v171
	v_rsq_f32_e32 v76, v76
	v_mad_i64_i32 v[84:85], s[38:39], v77, s64, v[122:123]
	v_lshl_add_u64 v[84:85], v[84:85], 0, v[124:125]
	v_pk_mul_f32 v[68:69], v[68:69], v[76:77] op_sel_hi:[1,0]
	v_pk_mul_f32 v[82:83], v[82:83], v[76:77] op_sel_hi:[1,0]
	v_pk_mul_f32 v[70:71], v[70:71], v[76:77] op_sel_hi:[1,0]
	v_pk_mul_f32 v[78:79], v[78:79], v[76:77] op_sel_hi:[1,0]
	v_pk_mul_f32 v[72:73], v[72:73], v[76:77] op_sel_hi:[1,0]
	v_pk_mul_f32 v[80:81], v[80:81], v[76:77] op_sel_hi:[1,0]
	v_pk_mul_f32 v[66:67], v[66:67], v[76:77] op_sel_hi:[1,0]
	v_pk_mul_f32 v[74:75], v[74:75], v[76:77] op_sel_hi:[1,0]
	v_mul_f32_e32 v69, v68, v69
	v_mul_f32_e32 v68, 0xbfb8aa3b, v68
	v_mul_f32_e32 v77, 0xbfb8aa3b, v82
	v_mul_f32_e32 v71, v70, v71
	v_mul_f32_e32 v70, 0xbfb8aa3b, v70
	v_mul_f32_e32 v79, v78, v79
	v_mul_f32_e32 v78, 0xbfb8aa3b, v78
	v_mul_f32_e32 v73, v72, v73
	v_mul_f32_e32 v72, 0xbfb8aa3b, v72
	v_mul_f32_e32 v81, v80, v81
	v_mul_f32_e32 v80, 0xbfb8aa3b, v80
	v_mul_f32_e32 v67, v66, v67
	v_mul_f32_e32 v66, 0xbfb8aa3b, v66
	v_mul_f32_e32 v75, v74, v75
	v_mul_f32_e32 v74, 0xbfb8aa3b, v74
	v_exp_f32_e32 v68, v68
	v_exp_f32_e32 v77, v77
	v_exp_f32_e32 v70, v70
	v_exp_f32_e32 v78, v78
	v_exp_f32_e32 v72, v72
	v_exp_f32_e32 v80, v80
	v_exp_f32_e32 v66, v66
	v_exp_f32_e32 v74, v74
	v_add_f32_e32 v68, 1.0, v68
	v_add_f32_e32 v77, 1.0, v77
	v_add_f32_e32 v70, 1.0, v70
	v_add_f32_e32 v78, 1.0, v78
	v_add_f32_e32 v72, 1.0, v72
	v_add_f32_e32 v80, 1.0, v80
	v_add_f32_e32 v66, 1.0, v66
	v_add_f32_e32 v74, 1.0, v74
	v_rcp_f32_e32 v68, v68
	v_rcp_f32_e32 v77, v77
	v_rcp_f32_e32 v70, v70
	v_rcp_f32_e32 v78, v78
	v_rcp_f32_e32 v72, v72
	v_rcp_f32_e32 v80, v80
	v_rcp_f32_e32 v66, v66
	v_rcp_f32_e32 v74, v74
	v_mul_f32_e32 v76, v82, v83
	v_mul_f32_e32 v69, v69, v68
	v_mul_f32_e32 v76, v76, v77
	v_mul_f32_e32 v70, v71, v70
	v_mul_f32_e32 v71, v79, v78
	v_mul_f32_e32 v72, v73, v72
	v_mul_f32_e32 v73, v81, v80
	v_mul_f32_e32 v77, v67, v66
	v_mul_f32_e32 v74, v75, v74
	v_cvt_pk_bf16_f32 v66, v76, v70
	v_cvt_pk_bf16_f32 v67, v71, v72
	v_cvt_pk_bf16_f32 v68, v73, v77
	v_cvt_pk_bf16_f32 v69, v74, v69
	global_store_dwordx4 v[84:85], v[66:69], off
	s_nop 0
	s_nop 0
	v_mov_b32_e32 v66, v62
	v_mov_b32_e32 v62, v64
	v_mov_b32_e32 v64, v58
	v_mov_b32_e32 v58, v60
	v_mov_b32_e32 v67, v54
	v_mov_b32_e32 v54, v63
	v_mov_b32_e32 v63, v56
	v_mov_b32_e32 v56, v65
	v_mov_b32_e32 v65, v50
	v_mov_b32_e32 v50, v59
	v_mov_b32_e32 v59, v52
	v_mov_b32_e32 v52, v61
	v_add_u32_e32 v61, 0x80, v154
	v_fmamk_f32 v60, v246, 0x3a000000, v171
	v_rsq_f32_e32 v60, v60
	v_mad_i64_i32 v[68:69], s[38:39], v61, s64, v[122:123]
	v_lshl_add_u64 v[68:69], v[68:69], 0, v[124:125]
	v_pk_mul_f32 v[52:53], v[52:53], v[60:61] op_sel_hi:[1,0]
	v_pk_mul_f32 v[66:67], v[66:67], v[60:61] op_sel_hi:[1,0]
	v_pk_mul_f32 v[54:55], v[54:55], v[60:61] op_sel_hi:[1,0]
	v_pk_mul_f32 v[62:63], v[62:63], v[60:61] op_sel_hi:[1,0]
	v_pk_mul_f32 v[56:57], v[56:57], v[60:61] op_sel_hi:[1,0]
	v_pk_mul_f32 v[64:65], v[64:65], v[60:61] op_sel_hi:[1,0]
	v_pk_mul_f32 v[50:51], v[50:51], v[60:61] op_sel_hi:[1,0]
	v_pk_mul_f32 v[58:59], v[58:59], v[60:61] op_sel_hi:[1,0]
	v_mul_f32_e32 v53, v52, v53
	v_mul_f32_e32 v52, 0xbfb8aa3b, v52
	v_mul_f32_e32 v61, 0xbfb8aa3b, v66
	v_mul_f32_e32 v55, v54, v55
	v_mul_f32_e32 v54, 0xbfb8aa3b, v54
; __device__ __forceinline__ unsigned cvt_pk_bf16(float lo, float hi) { unsigned r; asm volatile("v_cvt_pk_bf16_f32 %0, %1, %2" : "=v"(r) : "v"(lo), "v"(hi)); return r; }
;     __device__ __forceinline__ void operator()(const f32x4 (&acc)[2][2][4][2], const Unit& u, int wr, int wc, int fr, int fq) const {
;     ...
;             for (int m = 0; m < 4; ++m) { const int row = row0 + ai * HALF + m * 16; const float rs = __builtin_amdgcn_rsqf(ss[row_base + row] * (1.0f / 2048.0f) + 1e-6f);
;                 float a[8];
; #pragma unroll
;                 for (int n = 0; n < 2; ++n)
; #pragma unroll
;                     for (int j = 0; j < 4; ++j) { const float g = acc[ai][0][m][n][j] * rs, uu = acc[ai][1][m][n][j] * rs;
;                         a[n * 4 + j] = g * uu * __builtin_amdgcn_rcpf(1.0f + __builtin_amdgcn_exp2f(-1.4426950408889634f * g)); }
;                 u32x4 w; w.x = cvt_pk_bf16(a[0], a[1]); w.y = cvt_pk_bf16(a[2], a[3]); w.z = cvt_pk_bf16(a[4], a[5]); w.w = cvt_pk_bf16(a[6], a[7]);
;                 *(u32x4*)(act + (size_t)row * 5632 + col0) = w; }
	v_mul_f32_e32 v63, v62, v63
	v_mul_f32_e32 v62, 0xbfb8aa3b, v62
	v_mul_f32_e32 v57, v56, v57
	v_mul_f32_e32 v56, 0xbfb8aa3b, v56
	v_mul_f32_e32 v65, v64, v65
	v_mul_f32_e32 v64, 0xbfb8aa3b, v64
	v_mul_f32_e32 v51, v50, v51
	v_mul_f32_e32 v50, 0xbfb8aa3b, v50
	v_mul_f32_e32 v59, v58, v59
	v_mul_f32_e32 v58, 0xbfb8aa3b, v58
	v_exp_f32_e32 v52, v52
	v_exp_f32_e32 v61, v61
	v_exp_f32_e32 v54, v54
	v_exp_f32_e32 v62, v62
	v_exp_f32_e32 v56, v56
	v_exp_f32_e32 v64, v64
	v_exp_f32_e32 v50, v50
	v_exp_f32_e32 v58, v58
	v_add_f32_e32 v52, 1.0, v52
	v_add_f32_e32 v61, 1.0, v61
	v_add_f32_e32 v54, 1.0, v54
	v_add_f32_e32 v62, 1.0, v62
	v_add_f32_e32 v56, 1.0, v56
	v_add_f32_e32 v64, 1.0, v64
	v_add_f32_e32 v50, 1.0, v50
	v_add_f32_e32 v58, 1.0, v58
	v_rcp_f32_e32 v52, v52
	v_rcp_f32_e32 v61, v61
	v_rcp_f32_e32 v54, v54
	v_rcp_f32_e32 v62, v62
	v_rcp_f32_e32 v56, v56
	v_rcp_f32_e32 v64, v64
	v_rcp_f32_e32 v50, v50
	v_rcp_f32_e32 v58, v58
	v_mul_f32_e32 v60, v66, v67
	v_mul_f32_e32 v53, v53, v52
	v_mul_f32_e32 v60, v60, v61
	v_mul_f32_e32 v54, v55, v54
	v_mul_f32_e32 v55, v63, v62
	v_mul_f32_e32 v56, v57, v56
	v_mul_f32_e32 v57, v65, v64
	v_mul_f32_e32 v61, v51, v50
	v_mul_f32_e32 v58, v59, v58
	v_cvt_pk_bf16_f32 v50, v60, v54
	v_cvt_pk_bf16_f32 v51, v55, v56
	v_cvt_pk_bf16_f32 v52, v57, v61
	v_cvt_pk_bf16_f32 v53, v58, v53
	global_store_dwordx4 v[68:69], v[50:53], off
	s_nop 0
	s_nop 0
	v_mov_b32_e32 v50, v46
	v_mov_b32_e32 v46, v48
	v_mov_b32_e32 v48, v42
	v_mov_b32_e32 v42, v44
	v_mov_b32_e32 v51, v38
	v_mov_b32_e32 v38, v47
	v_mov_b32_e32 v47, v40
	v_mov_b32_e32 v40, v49
	v_mov_b32_e32 v49, v34
	v_mov_b32_e32 v34, v43
	v_mov_b32_e32 v43, v36
	v_mov_b32_e32 v36, v45
	v_add_u32_e32 v45, 0x90, v154
	v_fmamk_f32 v44, v247, 0x3a000000, v171
	v_rsq_f32_e32 v44, v44
	v_mad_i64_i32 v[52:53], s[38:39], v45, s64, v[122:123]
	v_lshl_add_u64 v[52:53], v[52:53], 0, v[124:125]
	v_pk_mul_f32 v[36:37], v[36:37], v[44:45] op_sel_hi:[1,0]
	v_pk_mul_f32 v[50:51], v[50:51], v[44:45] op_sel_hi:[1,0]
	v_pk_mul_f32 v[38:39], v[38:39], v[44:45] op_sel_hi:[1,0]
	v_pk_mul_f32 v[46:47], v[46:47], v[44:45] op_sel_hi:[1,0]
	v_pk_mul_f32 v[40:41], v[40:41], v[44:45] op_sel_hi:[1,0]
	v_pk_mul_f32 v[48:49], v[48:49], v[44:45] op_sel_hi:[1,0]
	v_pk_mul_f32 v[34:35], v[34:35], v[44:45] op_sel_hi:[1,0]
	v_pk_mul_f32 v[42:43], v[42:43], v[44:45] op_sel_hi:[1,0]
	v_mul_f32_e32 v37, v36, v37
	v_mul_f32_e32 v36, 0xbfb8aa3b, v36
	v_mul_f32_e32 v45, 0xbfb8aa3b, v50
	v_mul_f32_e32 v39, v38, v39
	v_mul_f32_e32 v38, 0xbfb8aa3b, v38
	v_mul_f32_e32 v47, v46, v47
	v_mul_f32_e32 v46, 0xbfb8aa3b, v46
	v_mul_f32_e32 v41, v40, v41
	v_mul_f32_e32 v40, 0xbfb8aa3b, v40
	v_mul_f32_e32 v49, v48, v49
	v_mul_f32_e32 v48, 0xbfb8aa3b, v48
	v_mul_f32_e32 v35, v34, v35
	v_mul_f32_e32 v34, 0xbfb8aa3b, v34
	v_mul_f32_e32 v43, v42, v43
	v_mul_f32_e32 v42, 0xbfb8aa3b, v42
	v_exp_f32_e32 v36, v36
	v_exp_f32_e32 v45, v45
	v_exp_f32_e32 v38, v38
	v_exp_f32_e32 v46, v46
	v_exp_f32_e32 v40, v40
	v_exp_f32_e32 v48, v48
	v_exp_f32_e32 v34, v34
	v_exp_f32_e32 v42, v42
	v_add_f32_e32 v36, 1.0, v36
	v_add_f32_e32 v45, 1.0, v45
	v_add_f32_e32 v38, 1.0, v38
	v_add_f32_e32 v46, 1.0, v46
	v_add_f32_e32 v40, 1.0, v40
	v_add_f32_e32 v48, 1.0, v48
	v_add_f32_e32 v34, 1.0, v34
	v_add_f32_e32 v42, 1.0, v42
	v_rcp_f32_e32 v36, v36
	v_rcp_f32_e32 v45, v45
	v_rcp_f32_e32 v38, v38
	v_rcp_f32_e32 v46, v46
	v_rcp_f32_e32 v40, v40
	v_rcp_f32_e32 v48, v48
	v_rcp_f32_e32 v34, v34
	v_rcp_f32_e32 v42, v42
	v_mul_f32_e32 v44, v50, v51
	v_mul_f32_e32 v37, v37, v36
	v_mul_f32_e32 v44, v44, v45
	v_mul_f32_e32 v38, v39, v38
	v_mul_f32_e32 v39, v47, v46
	v_mul_f32_e32 v40, v41, v40
	v_mul_f32_e32 v41, v49, v48
	v_mul_f32_e32 v45, v35, v34
	v_mul_f32_e32 v42, v43, v42
	v_cvt_pk_bf16_f32 v34, v44, v38
	v_cvt_pk_bf16_f32 v35, v39, v40
	v_cvt_pk_bf16_f32 v36, v41, v45
	v_cvt_pk_bf16_f32 v37, v42, v37
	global_store_dwordx4 v[52:53], v[34:37], off
	s_nop 0
	s_nop 0
	v_mov_b32_e32 v34, v30
	v_mov_b32_e32 v30, v32
	v_mov_b32_e32 v32, v26
	v_mov_b32_e32 v26, v28
	v_mov_b32_e32 v35, v22
	v_mov_b32_e32 v22, v31
	v_mov_b32_e32 v31, v24
	v_mov_b32_e32 v24, v33
	v_mov_b32_e32 v33, v18
	v_mov_b32_e32 v18, v27
	v_mov_b32_e32 v27, v20
	v_mov_b32_e32 v20, v29
	v_add_u32_e32 v29, 0xa0, v154
	v_fmamk_f32 v28, v248, 0x3a000000, v171
	v_rsq_f32_e32 v28, v28
	v_mad_i64_i32 v[36:37], s[38:39], v29, s64, v[122:123]
	v_lshl_add_u64 v[36:37], v[36:37], 0, v[124:125]
	v_pk_mul_f32 v[20:21], v[20:21], v[28:29] op_sel_hi:[1,0]
; __device__ __forceinline__ unsigned cvt_pk_bf16(float lo, float hi) { unsigned r; asm volatile("v_cvt_pk_bf16_f32 %0, %1, %2" : "=v"(r) : "v"(lo), "v"(hi)); return r; }
; #define PG8_BAR __builtin_amdgcn_s_barrier()
; template <class Epi, class Sched, bool ALIGN_EPI = false, bool SP2 = false, bool KSEG = false>
; __device__ __forceinline__ void gemm_phase(PG8_LAS unsigned char* lds, const Gemm g, const Sched& S, const Epi& E) {
;     ...
;         if (!has_next) break;
; #pragma unroll
;         for (int a = 0; a < 2; ++a)
; #pragma unroll
;             for (int b = 0; b < 2; ++b)
; #pragma unroll
;                 for (int m = 0; m < 4; ++m)
; #pragma unroll
;                     for (int n = 0; n < 2; ++n) acc[a][b][m][n] = (f32x4){0.f, 0.f, 0.f, 0.f};
;         cur = nxt; cA = nA; cB = nB; ++ui;
;         if constexpr (ALIGN_EPI) { if (wr == 1) PG8_BAR; }
;     __device__ __forceinline__ void operator()(const f32x4 (&acc)[2][2][4][2], const Unit& u, int wr, int wc, int fr, int fq) const {
;     ...
;             for (int m = 0; m < 4; ++m) { const int row = row0 + ai * HALF + m * 16; const float rs = __builtin_amdgcn_rsqf(ss[row_base + row] * (1.0f / 2048.0f) + 1e-6f);
;                 float a[8];
; #pragma unroll
;                 for (int n = 0; n < 2; ++n)
; #pragma unroll
;                     for (int j = 0; j < 4; ++j) { const float g = acc[ai][0][m][n][j] * rs, uu = acc[ai][1][m][n][j] * rs;
;                         a[n * 4 + j] = g * uu * __builtin_amdgcn_rcpf(1.0f + __builtin_amdgcn_exp2f(-1.4426950408889634f * g)); }
;                 u32x4 w; w.x = cvt_pk_bf16(a[0], a[1]); w.y = cvt_pk_bf16(a[2], a[3]); w.z = cvt_pk_bf16(a[4], a[5]); w.w = cvt_pk_bf16(a[6], a[7]);
;                 *(u32x4*)(act + (size_t)row * 5632 + col0) = w; }
	v_pk_mul_f32 v[34:35], v[34:35], v[28:29] op_sel_hi:[1,0]
	v_pk_mul_f32 v[22:23], v[22:23], v[28:29] op_sel_hi:[1,0]
	v_pk_mul_f32 v[30:31], v[30:31], v[28:29] op_sel_hi:[1,0]
	v_pk_mul_f32 v[24:25], v[24:25], v[28:29] op_sel_hi:[1,0]
	v_pk_mul_f32 v[32:33], v[32:33], v[28:29] op_sel_hi:[1,0]
	v_pk_mul_f32 v[18:19], v[18:19], v[28:29] op_sel_hi:[1,0]
	v_pk_mul_f32 v[26:27], v[26:27], v[28:29] op_sel_hi:[1,0]
	v_mul_f32_e32 v21, v20, v21
	v_mul_f32_e32 v20, 0xbfb8aa3b, v20
	v_mul_f32_e32 v29, 0xbfb8aa3b, v34
	v_mul_f32_e32 v23, v22, v23
	v_mul_f32_e32 v22, 0xbfb8aa3b, v22
	v_mul_f32_e32 v31, v30, v31
	v_mul_f32_e32 v30, 0xbfb8aa3b, v30
	v_mul_f32_e32 v25, v24, v25
	v_mul_f32_e32 v24, 0xbfb8aa3b, v24
	v_mul_f32_e32 v33, v32, v33
	v_mul_f32_e32 v32, 0xbfb8aa3b, v32
	v_mul_f32_e32 v19, v18, v19
	v_mul_f32_e32 v18, 0xbfb8aa3b, v18
	v_mul_f32_e32 v27, v26, v27
	v_mul_f32_e32 v26, 0xbfb8aa3b, v26
	v_exp_f32_e32 v20, v20
	v_exp_f32_e32 v29, v29
	v_exp_f32_e32 v22, v22
	v_exp_f32_e32 v30, v30
	v_exp_f32_e32 v24, v24
	v_exp_f32_e32 v32, v32
	v_exp_f32_e32 v18, v18
	v_exp_f32_e32 v26, v26
	v_add_f32_e32 v20, 1.0, v20
	v_add_f32_e32 v29, 1.0, v29
	v_add_f32_e32 v22, 1.0, v22
	v_add_f32_e32 v30, 1.0, v30
	v_add_f32_e32 v24, 1.0, v24
	v_add_f32_e32 v32, 1.0, v32
	v_add_f32_e32 v18, 1.0, v18
	v_add_f32_e32 v26, 1.0, v26
	v_rcp_f32_e32 v20, v20
	v_rcp_f32_e32 v29, v29
	v_rcp_f32_e32 v22, v22
	v_rcp_f32_e32 v30, v30
	v_rcp_f32_e32 v24, v24
	v_rcp_f32_e32 v32, v32
	v_rcp_f32_e32 v18, v18
	v_rcp_f32_e32 v26, v26
	v_mul_f32_e32 v28, v34, v35
	v_mul_f32_e32 v21, v21, v20
	v_mul_f32_e32 v28, v28, v29
	v_mul_f32_e32 v22, v23, v22
	v_mul_f32_e32 v23, v31, v30
	v_mul_f32_e32 v24, v25, v24
	v_mul_f32_e32 v25, v33, v32
	v_mul_f32_e32 v29, v19, v18
	v_mul_f32_e32 v26, v27, v26
	v_cvt_pk_bf16_f32 v18, v28, v22
	v_cvt_pk_bf16_f32 v19, v23, v24
	v_cvt_pk_bf16_f32 v20, v25, v29
	v_cvt_pk_bf16_f32 v21, v26, v21
	global_store_dwordx4 v[36:37], v[18:21], off
	s_nop 0
	s_mov_b64 s[38:39], -1
	v_mov_b32_e32 v18, v14
	v_mov_b32_e32 v14, v16
	v_mov_b32_e32 v16, v10
	v_mov_b32_e32 v10, v12
	v_mov_b32_e32 v19, v6
	v_mov_b32_e32 v6, v15
	v_mov_b32_e32 v15, v8
	v_mov_b32_e32 v8, v17
	v_mov_b32_e32 v17, v2
	v_mov_b32_e32 v2, v11
	v_mov_b32_e32 v11, v4
	v_mov_b32_e32 v4, v13
	v_add_u32_e32 v13, 0xb0, v154
	v_fmamk_f32 v12, v249, 0x3a000000, v171
	v_rsq_f32_e32 v12, v12
	v_mad_i64_i32 v[20:21], s[6:7], v13, s64, v[122:123]
	v_lshl_add_u64 v[20:21], v[20:21], 0, v[124:125]
	v_pk_mul_f32 v[4:5], v[4:5], v[12:13] op_sel_hi:[1,0]
	v_pk_mul_f32 v[18:19], v[18:19], v[12:13] op_sel_hi:[1,0]
	v_pk_mul_f32 v[6:7], v[6:7], v[12:13] op_sel_hi:[1,0]
	v_pk_mul_f32 v[14:15], v[14:15], v[12:13] op_sel_hi:[1,0]
	v_pk_mul_f32 v[8:9], v[8:9], v[12:13] op_sel_hi:[1,0]
	v_pk_mul_f32 v[16:17], v[16:17], v[12:13] op_sel_hi:[1,0]
	v_pk_mul_f32 v[2:3], v[2:3], v[12:13] op_sel_hi:[1,0]
	v_pk_mul_f32 v[10:11], v[10:11], v[12:13] op_sel_hi:[1,0]
	v_mul_f32_e32 v5, v4, v5
	v_mul_f32_e32 v4, 0xbfb8aa3b, v4
	v_mul_f32_e32 v13, 0xbfb8aa3b, v18
	v_mul_f32_e32 v7, v6, v7
	v_mul_f32_e32 v6, 0xbfb8aa3b, v6
	v_mul_f32_e32 v15, v14, v15
	v_mul_f32_e32 v14, 0xbfb8aa3b, v14
	v_mul_f32_e32 v9, v8, v9
	v_mul_f32_e32 v8, 0xbfb8aa3b, v8
	v_mul_f32_e32 v17, v16, v17
	v_mul_f32_e32 v16, 0xbfb8aa3b, v16
	v_mul_f32_e32 v3, v2, v3
	v_mul_f32_e32 v2, 0xbfb8aa3b, v2
	v_mul_f32_e32 v11, v10, v11
	v_mul_f32_e32 v10, 0xbfb8aa3b, v10
	v_exp_f32_e32 v4, v4
	v_exp_f32_e32 v13, v13
	v_exp_f32_e32 v6, v6
	v_exp_f32_e32 v14, v14
	v_exp_f32_e32 v8, v8
	v_exp_f32_e32 v16, v16
	v_exp_f32_e32 v2, v2
	v_exp_f32_e32 v10, v10
	v_add_f32_e32 v4, 1.0, v4
	v_add_f32_e32 v13, 1.0, v13
	v_add_f32_e32 v6, 1.0, v6
	v_add_f32_e32 v14, 1.0, v14
	v_add_f32_e32 v8, 1.0, v8
	v_add_f32_e32 v16, 1.0, v16
	v_add_f32_e32 v2, 1.0, v2
	v_add_f32_e32 v10, 1.0, v10
	v_rcp_f32_e32 v4, v4
	v_rcp_f32_e32 v13, v13
	v_rcp_f32_e32 v6, v6
	v_rcp_f32_e32 v14, v14
	v_rcp_f32_e32 v8, v8
	v_rcp_f32_e32 v16, v16
	v_rcp_f32_e32 v2, v2
	v_rcp_f32_e32 v10, v10
	v_mul_f32_e32 v12, v18, v19
	v_mul_f32_e32 v5, v5, v4
	v_mul_f32_e32 v12, v12, v13
	v_mul_f32_e32 v6, v7, v6
	v_mul_f32_e32 v7, v15, v14
	v_mul_f32_e32 v8, v9, v8
	v_mul_f32_e32 v9, v17, v16
	v_mul_f32_e32 v13, v3, v2
	v_mul_f32_e32 v10, v11, v10
	v_cvt_pk_bf16_f32 v2, v12, v6
	v_cvt_pk_bf16_f32 v3, v7, v8
	v_cvt_pk_bf16_f32 v4, v9, v13
	v_cvt_pk_bf16_f32 v5, v10, v5
	global_store_dwordx4 v[20:21], v[2:5], off
	s_cbranch_vccz .LBB0_577
	s_andn2_b64 vcc, exec, s[10:11]
	s_cbranch_vccnz .LBB0_576
	s_barrier
	s_branch .LBB0_576

; #define PG8_STAGE(bufoff, gbase, voff) do { _Pragma("unroll") for (int _i = 0; _i < 2; ++_i) \
;         __builtin_amdgcn_global_load_lds((const unsigned*)((const char*)(gbase) + (voff)[_i]), (PG8_LAS unsigned*)(lds + (bufoff) + ldsw + _i * 8192), 16, 0, 0); } while (0)
; #define PG8_LDA(dst, b, h) do { _Pragma("unroll") for (int m = 0; m < 4; ++m) _Pragma("unroll") for (int k = 0; k < 2; ++k) dst[m][k] = *(const PG8_LAS bf16x8*)(lds + PG8_SA(b, h) + aoff + m * 2048 + k * 1024); } while (0)
; #define PG8_LDB(dst, b, h) do { _Pragma("unroll") for (int n = 0; n < 2; ++n) _Pragma("unroll") for (int k = 0; k < 2; ++k) dst[n][k] = *(const PG8_LAS bf16x8*)(lds + PG8_SB(b, h) + boff + n * 2048 + k * 1024); } while (0)
; #define PG8_MMA(ai, bj, At, Bt) do { __builtin_amdgcn_s_setprio(1); _Pragma("unroll") for (int m = 0; m < 4; ++m) _Pragma("unroll") for (int n = 0; n < 2; ++n) _Pragma("unroll") for (int k = 0; k < 2; ++k) \
;         acc[ai][bj][m][n] = __builtin_amdgcn_mfma_f32_16x16x32_bf16(Bt[n][k], At[m][k], acc[ai][bj][m][n], 0, 0, 0); __builtin_amdgcn_s_setprio(0); } while (0)
; #define PG8_WAIT_V(n) asm volatile("s_waitcnt vmcnt(" #n ")" ::: "memory")
; #define PG8_WAIT_L(n) asm volatile("s_waitcnt lgkmcnt(" #n ")" ::: "memory")
; #define PG8_BAR __builtin_amdgcn_s_barrier()
; template <class Epi, class Sched, bool ALIGN_EPI = false, bool SP2 = false, bool KSEG = false>
; __device__ __forceinline__ void gemm_phase(PG8_LAS unsigned char* lds, const Gemm g, const Sched& S, const Epi& E) {
;     ...
;             const char* a1 = cA + (size_t)(t + 1) * kstep;
;             const char* a2 = last ? nA : cA + (size_t)(t + 2) * kstep; const char* b2 = last ? nB : cB + (size_t)(t + 2) * kstep;
;             const char* a3 = a2 + kstep; const char* b3 = b2 + kstep;
;             if (last && has_next) S.a_ready(nxt);
;             if constexpr (SP2) {
;             PG8_LDB(B0, 0, 0); PG8_LDB(B1, 0, 1); PG8_SCHED; PG8_LDA(At, 0, 0); PG8_STAGE(PG8_SA(1, 1), a1 + hstep, voffA);
;             PG8_WAIT_V(8); PG8_WAIT_L(0); PG8_BAR; PG8_MMA(0, 0, At, B0); PG8_MMA(0, 1, At, B1); PG8_BAR; PG8_SCHED;
;             PG8_LDA(At, 0, 1); PG8_STAGE(PG8_SB(0, 0), b2, voffB); PG8_STAGE(PG8_SB(0, 1), b2 + hstep, voffB); PG8_STAGE(PG8_SA(0, 0), a2, voffA);
;             PG8_WAIT_V(8); PG8_WAIT_L(0); PG8_BAR; PG8_MMA(1, 0, At, B0); PG8_MMA(1, 1, At, B1); PG8_BAR; PG8_SCHED;
.LBB0_621:
	ds_read_b128 v[146:149], v1
	ds_read_b128 v[156:159], v1 offset:1024
	ds_read_b128 v[160:163], v1 offset:2048
	ds_read_b128 v[164:167], v1 offset:3072
	ds_read_b128 v[168:171], v153
	ds_read_b128 v[172:175], v153 offset:1024
	ds_read_b128 v[176:179], v153 offset:2048
	ds_read_b128 v[180:183], v153 offset:3072
	s_add_u32 s26, s24, 0xffea0080
	s_addc_u32 s27, s25, -1
	s_cmpk_eq_i32 s50, 0x54
	s_cselect_b32 s29, s21, s27
	s_cselect_b32 s28, s20, s26
	s_cselect_b32 s27, s9, s49
	s_cselect_b32 s26, s8, s48
	s_add_u32 s98, s24, 0xffea0000
	s_addc_u32 s99, s25, -1
	s_mov_b32 m0, s40
	v_lshl_add_u64 v[216:217], s[98:99], 0, v[140:141]
	global_load_lds_dwordx4 v[216:217], off
	s_mov_b32 m0, s41
	v_lshl_add_u64 v[216:217], s[98:99], 0, v[142:143]
	global_load_lds_dwordx4 v[216:217], off
	v_lshl_add_u64 v[216:217], s[24:25], 0, v[132:133]
	s_add_i32 m0, s31, 0xc000
	ds_read_b128 v[184:187], v154
	ds_read_b128 v[188:191], v154 offset:1024
	ds_read_b128 v[192:195], v154 offset:2048
	ds_read_b128 v[196:199], v154 offset:3072
	ds_read_b128 v[200:203], v154 offset:4096
	ds_read_b128 v[204:207], v154 offset:5120
	ds_read_b128 v[208:211], v154 offset:6144
	ds_read_b128 v[212:215], v154 offset:7168
	global_load_lds_dwordx4 v[216:217], off
	s_add_i32 m0, s31, 0xe000
	v_lshl_add_u64 v[216:217], s[24:25], 0, v[134:135]
	global_load_lds_dwordx4 v[216:217], off
	s_waitcnt vmcnt(8) lgkmcnt(0)
	s_barrier
	s_setprio 1
	v_mfma_f32_16x16x32_bf16 v[126:129], v[146:149], v[184:187], v[126:129]
	v_mfma_f32_16x16x32_bf16 v[122:125], v[160:163], v[184:187], v[122:125]
	v_mfma_f32_16x16x32_bf16 v[110:113], v[146:149], v[192:195], v[110:113]
	v_mfma_f32_16x16x32_bf16 v[106:109], v[160:163], v[192:195], v[106:109]
	v_mfma_f32_16x16x32_bf16 v[94:97], v[146:149], v[200:203], v[94:97]
	v_mfma_f32_16x16x32_bf16 v[90:93], v[160:163], v[200:203], v[90:93]
	v_mfma_f32_16x16x32_bf16 v[78:81], v[146:149], v[208:211], v[78:81]
	v_mfma_f32_16x16x32_bf16 v[74:77], v[160:163], v[208:211], v[74:77]
	v_mfma_f32_16x16x32_bf16 v[126:129], v[156:159], v[188:191], v[126:129]
	v_mfma_f32_16x16x32_bf16 v[122:125], v[164:167], v[188:191], v[122:125]
	v_mfma_f32_16x16x32_bf16 v[110:113], v[156:159], v[196:199], v[110:113]
	v_mfma_f32_16x16x32_bf16 v[106:109], v[164:167], v[196:199], v[106:109]
	v_mfma_f32_16x16x32_bf16 v[94:97], v[156:159], v[204:207], v[94:97]
	v_mfma_f32_16x16x32_bf16 v[90:93], v[164:167], v[204:207], v[90:93]
	v_mfma_f32_16x16x32_bf16 v[78:81], v[156:159], v[212:215], v[78:81]
	v_mfma_f32_16x16x32_bf16 v[74:77], v[164:167], v[212:215], v[74:77]
	s_setprio 0
	s_setprio 1
	v_mfma_f32_16x16x32_bf16 v[118:121], v[168:171], v[184:187], v[118:121]
	v_mfma_f32_16x16x32_bf16 v[114:117], v[176:179], v[184:187], v[114:117]
	v_mfma_f32_16x16x32_bf16 v[102:105], v[168:171], v[192:195], v[102:105]
	v_mfma_f32_16x16x32_bf16 v[98:101], v[176:179], v[192:195], v[98:101]
	v_mfma_f32_16x16x32_bf16 v[86:89], v[168:171], v[200:203], v[86:89]
	v_mfma_f32_16x16x32_bf16 v[82:85], v[176:179], v[200:203], v[82:85]
	v_mfma_f32_16x16x32_bf16 v[70:73], v[168:171], v[208:211], v[70:73]
	v_mfma_f32_16x16x32_bf16 v[66:69], v[176:179], v[208:211], v[66:69]
	v_mfma_f32_16x16x32_bf16 v[118:121], v[172:175], v[188:191], v[118:121]
	v_mfma_f32_16x16x32_bf16 v[114:117], v[180:183], v[188:191], v[114:117]
	v_mfma_f32_16x16x32_bf16 v[102:105], v[172:175], v[196:199], v[102:105]
	v_mfma_f32_16x16x32_bf16 v[98:101], v[180:183], v[196:199], v[98:101]
	v_mfma_f32_16x16x32_bf16 v[86:89], v[172:175], v[204:207], v[86:89]
	v_mfma_f32_16x16x32_bf16 v[82:85], v[180:183], v[204:207], v[82:85]
	v_mfma_f32_16x16x32_bf16 v[70:73], v[172:175], v[212:215], v[70:73]
	v_mfma_f32_16x16x32_bf16 v[66:69], v[180:183], v[212:215], v[66:69]
	s_setprio 0
	s_barrier
	s_add_i32 s33, s42, s30
	v_lshl_add_u64 v[216:217], s[26:27], 0, v[130:131]
	s_mov_b32 m0, s33
	ds_read_b128 v[184:187], v154 offset:16384
	ds_read_b128 v[188:191], v154 offset:17408
	ds_read_b128 v[192:195], v154 offset:18432
	ds_read_b128 v[196:199], v154 offset:19456
	ds_read_b128 v[200:203], v154 offset:20480
	ds_read_b128 v[204:207], v154 offset:21504
	ds_read_b128 v[208:211], v154 offset:22528
	ds_read_b128 v[212:215], v154 offset:23552
	global_load_lds_dwordx4 v[216:217], off
	s_add_i32 m0, s33, 0x2000
	s_add_u32 s54, s26, 0x160000
	v_lshl_add_u64 v[218:219], s[26:27], 0, v[144:145]
	s_addc_u32 s55, s27, 0
	s_add_i32 s33, s43, s30
	global_load_lds_dwordx4 v[218:219], off
	s_mov_b32 m0, s33
	v_lshl_add_u64 v[220:221], s[54:55], 0, v[130:131]
	global_load_lds_dwordx4 v[220:221], off
	s_add_i32 m0, s33, 0x2000
	v_lshl_add_u64 v[220:221], s[54:55], 0, v[144:145]
	global_load_lds_dwordx4 v[220:221], off
	s_waitcnt vmcnt(6) lgkmcnt(0)
	s_barrier
; #define PG8_STAGE(bufoff, gbase, voff) do { _Pragma("unroll") for (int _i = 0; _i < 2; ++_i) \
;         __builtin_amdgcn_global_load_lds((const unsigned*)((const char*)(gbase) + (voff)[_i]), (PG8_LAS unsigned*)(lds + (bufoff) + ldsw + _i * 8192), 16, 0, 0); } while (0)
; #define PG8_LDA(dst, b, h) do { _Pragma("unroll") for (int m = 0; m < 4; ++m) _Pragma("unroll") for (int k = 0; k < 2; ++k) dst[m][k] = *(const PG8_LAS bf16x8*)(lds + PG8_SA(b, h) + aoff + m * 2048 + k * 1024); } while (0)
; #define PG8_LDB(dst, b, h) do { _Pragma("unroll") for (int n = 0; n < 2; ++n) _Pragma("unroll") for (int k = 0; k < 2; ++k) dst[n][k] = *(const PG8_LAS bf16x8*)(lds + PG8_SB(b, h) + boff + n * 2048 + k * 1024); } while (0)
; #define PG8_MMA(ai, bj, At, Bt) do { __builtin_amdgcn_s_setprio(1); _Pragma("unroll") for (int m = 0; m < 4; ++m) _Pragma("unroll") for (int n = 0; n < 2; ++n) _Pragma("unroll") for (int k = 0; k < 2; ++k) \
;         acc[ai][bj][m][n] = __builtin_amdgcn_mfma_f32_16x16x32_bf16(Bt[n][k], At[m][k], acc[ai][bj][m][n], 0, 0, 0); __builtin_amdgcn_s_setprio(0); } while (0)
; #define PG8_WAIT_V(n) asm volatile("s_waitcnt vmcnt(" #n ")" ::: "memory")
; #define PG8_WAIT_L(n) asm volatile("s_waitcnt lgkmcnt(" #n ")" ::: "memory")
; #define PG8_BAR __builtin_amdgcn_s_barrier()
; #define PG8_SCHED __builtin_amdgcn_sched_barrier(0)
; template <class Epi, class Sched, bool ALIGN_EPI = false, bool SP2 = false, bool KSEG = false>
; __device__ __forceinline__ void gemm_phase(PG8_LAS unsigned char* lds, const Gemm g, const Sched& S, const Epi& E) {
;     ...
;             PG8_WAIT_V(8); PG8_WAIT_L(0); PG8_BAR; PG8_MMA(1, 0, At, B0); PG8_MMA(1, 1, At, B1); PG8_BAR; PG8_SCHED;
;             PG8_LDB(B0, 1, 0); PG8_LDB(B1, 1, 1); PG8_SCHED; PG8_LDA(At, 1, 0); PG8_STAGE(PG8_SA(0, 1), a2 + hstep, voffA);
;             PG8_WAIT_V(8); PG8_WAIT_L(0); PG8_BAR; PG8_MMA(0, 0, At, B0); PG8_MMA(0, 1, At, B1); PG8_BAR; PG8_SCHED;
;             PG8_LDA(At, 1, 1); PG8_STAGE(PG8_SB(1, 0), b3, voffB); PG8_STAGE(PG8_SB(1, 1), b3 + hstep, voffB); PG8_STAGE(PG8_SA(1, 0), a3, voffA);
	s_setprio 1
	v_mfma_f32_16x16x32_bf16 v[62:65], v[146:149], v[184:187], v[62:65]
	v_mfma_f32_16x16x32_bf16 v[58:61], v[160:163], v[184:187], v[58:61]
	v_mfma_f32_16x16x32_bf16 v[46:49], v[146:149], v[192:195], v[46:49]
	v_mfma_f32_16x16x32_bf16 v[42:45], v[160:163], v[192:195], v[42:45]
	v_mfma_f32_16x16x32_bf16 v[30:33], v[146:149], v[200:203], v[30:33]
	v_mfma_f32_16x16x32_bf16 v[26:29], v[160:163], v[200:203], v[26:29]
	v_mfma_f32_16x16x32_bf16 v[14:17], v[146:149], v[208:211], v[14:17]
	v_mfma_f32_16x16x32_bf16 v[10:13], v[160:163], v[208:211], v[10:13]
	v_mfma_f32_16x16x32_bf16 v[62:65], v[156:159], v[188:191], v[62:65]
	v_mfma_f32_16x16x32_bf16 v[58:61], v[164:167], v[188:191], v[58:61]
	v_mfma_f32_16x16x32_bf16 v[46:49], v[156:159], v[196:199], v[46:49]
	v_mfma_f32_16x16x32_bf16 v[42:45], v[164:167], v[196:199], v[42:45]
	v_mfma_f32_16x16x32_bf16 v[30:33], v[156:159], v[204:207], v[30:33]
	v_mfma_f32_16x16x32_bf16 v[26:29], v[164:167], v[204:207], v[26:29]
	v_mfma_f32_16x16x32_bf16 v[14:17], v[156:159], v[212:215], v[14:17]
	v_mfma_f32_16x16x32_bf16 v[10:13], v[164:167], v[212:215], v[10:13]
	s_setprio 0
	s_setprio 1
	v_mfma_f32_16x16x32_bf16 v[54:57], v[168:171], v[184:187], v[54:57]
	v_mfma_f32_16x16x32_bf16 v[50:53], v[176:179], v[184:187], v[50:53]
	v_mfma_f32_16x16x32_bf16 v[38:41], v[168:171], v[192:195], v[38:41]
	v_mfma_f32_16x16x32_bf16 v[34:37], v[176:179], v[192:195], v[34:37]
	v_mfma_f32_16x16x32_bf16 v[22:25], v[168:171], v[200:203], v[22:25]
	v_mfma_f32_16x16x32_bf16 v[18:21], v[176:179], v[200:203], v[18:21]
	v_mfma_f32_16x16x32_bf16 v[6:9], v[168:171], v[208:211], v[6:9]
	v_mfma_f32_16x16x32_bf16 v[2:5], v[176:179], v[208:211], v[2:5]
	v_mfma_f32_16x16x32_bf16 v[54:57], v[172:175], v[188:191], v[54:57]
	v_mfma_f32_16x16x32_bf16 v[50:53], v[180:183], v[188:191], v[50:53]
	v_mfma_f32_16x16x32_bf16 v[38:41], v[172:175], v[196:199], v[38:41]
	v_mfma_f32_16x16x32_bf16 v[34:37], v[180:183], v[196:199], v[34:37]
	v_mfma_f32_16x16x32_bf16 v[22:25], v[172:175], v[204:207], v[22:25]
	v_mfma_f32_16x16x32_bf16 v[18:21], v[180:183], v[204:207], v[18:21]
	v_mfma_f32_16x16x32_bf16 v[6:9], v[172:175], v[212:215], v[6:9]
	v_mfma_f32_16x16x32_bf16 v[2:5], v[180:183], v[212:215], v[2:5]
	s_setprio 0
	s_barrier
	s_add_i32 s33, 0, 0x18000
	v_add_u32_e32 v155, s33, v150
	s_add_i32 s53, 0, 0x1c000
	ds_read_b128 v[146:149], v155
	ds_read_b128 v[156:159], v155 offset:1024
	ds_read_b128 v[160:163], v155 offset:2048
	ds_read_b128 v[164:167], v155 offset:3072
	v_add_u32_e32 v155, s53, v150
	ds_read_b128 v[168:171], v155
	ds_read_b128 v[172:175], v155 offset:1024
	ds_read_b128 v[176:179], v155 offset:2048
	ds_read_b128 v[180:183], v155 offset:3072
	s_mov_b32 m0, s31
	v_lshl_add_u64 v[224:225], s[28:29], 0, v[140:141]
	global_load_lds_dwordx4 v[224:225], off
	s_mov_b32 m0, s36
	v_lshl_add_u64 v[224:225], s[28:29], 0, v[142:143]
	global_load_lds_dwordx4 v[224:225], off
	s_add_u32 s28, s28, 0x160000
	s_addc_u32 s29, s29, 0
	s_mov_b32 m0, s37
	v_lshl_add_u64 v[224:225], s[28:29], 0, v[140:141]
	ds_read_b128 v[184:187], v154 offset:32768
	ds_read_b128 v[188:191], v154 offset:33792
	ds_read_b128 v[192:195], v154 offset:34816
	ds_read_b128 v[196:199], v154 offset:35840
	ds_read_b128 v[200:203], v154 offset:36864
	ds_read_b128 v[204:207], v154 offset:37888
	ds_read_b128 v[208:211], v154 offset:38912
	ds_read_b128 v[212:215], v154 offset:39936
	global_load_lds_dwordx4 v[224:225], off
	s_mov_b32 m0, s38
	v_lshl_add_u64 v[224:225], s[28:29], 0, v[142:143]
	global_load_lds_dwordx4 v[224:225], off
	s_waitcnt vmcnt(8) lgkmcnt(0)
	s_barrier
; #define PG8_STAGE(bufoff, gbase, voff) do { _Pragma("unroll") for (int _i = 0; _i < 2; ++_i) \
;         __builtin_amdgcn_global_load_lds((const unsigned*)((const char*)(gbase) + (voff)[_i]), (PG8_LAS unsigned*)(lds + (bufoff) + ldsw + _i * 8192), 16, 0, 0); } while (0)
; #define PG8_LDA(dst, b, h) do { _Pragma("unroll") for (int m = 0; m < 4; ++m) _Pragma("unroll") for (int k = 0; k < 2; ++k) dst[m][k] = *(const PG8_LAS bf16x8*)(lds + PG8_SA(b, h) + aoff + m * 2048 + k * 1024); } while (0)
; #define PG8_MMA(ai, bj, At, Bt) do { __builtin_amdgcn_s_setprio(1); _Pragma("unroll") for (int m = 0; m < 4; ++m) _Pragma("unroll") for (int n = 0; n < 2; ++n) _Pragma("unroll") for (int k = 0; k < 2; ++k) \
;         acc[ai][bj][m][n] = __builtin_amdgcn_mfma_f32_16x16x32_bf16(Bt[n][k], At[m][k], acc[ai][bj][m][n], 0, 0, 0); __builtin_amdgcn_s_setprio(0); } while (0)
; #define PG8_WAIT_V(n) asm volatile("s_waitcnt vmcnt(" #n ")" ::: "memory")
; #define PG8_WAIT_L(n) asm volatile("s_waitcnt lgkmcnt(" #n ")" ::: "memory")
; #define PG8_BAR __builtin_amdgcn_s_barrier()
; #define PG8_SCHED __builtin_amdgcn_sched_barrier(0)
; template <class Epi, class Sched, bool ALIGN_EPI = false, bool SP2 = false, bool KSEG = false>
; __device__ __forceinline__ void gemm_phase(PG8_LAS unsigned char* lds, const Gemm g, const Sched& S, const Epi& E) {
;     ...
;             PG8_WAIT_V(8); PG8_WAIT_L(0); PG8_BAR; PG8_MMA(0, 0, At, B0); PG8_MMA(0, 1, At, B1); PG8_BAR; PG8_SCHED;
;             PG8_LDA(At, 1, 1); PG8_STAGE(PG8_SB(1, 0), b3, voffB); PG8_STAGE(PG8_SB(1, 1), b3 + hstep, voffB); PG8_STAGE(PG8_SA(1, 0), a3, voffA);
;             PG8_WAIT_V(8); PG8_WAIT_L(0); PG8_BAR; PG8_MMA(1, 0, At, B0); PG8_MMA(1, 1, At, B1); PG8_BAR; PG8_SCHED;
;     ...
;         }
;         if constexpr (ALIGN_EPI) { if (wr == 0) PG8_BAR; }
	s_setprio 1
	v_mfma_f32_16x16x32_bf16 v[126:129], v[146:149], v[184:187], v[126:129]
	v_mfma_f32_16x16x32_bf16 v[122:125], v[160:163], v[184:187], v[122:125]
	v_mfma_f32_16x16x32_bf16 v[110:113], v[146:149], v[192:195], v[110:113]
	v_mfma_f32_16x16x32_bf16 v[106:109], v[160:163], v[192:195], v[106:109]
	v_mfma_f32_16x16x32_bf16 v[94:97], v[146:149], v[200:203], v[94:97]
	v_mfma_f32_16x16x32_bf16 v[90:93], v[160:163], v[200:203], v[90:93]
	v_mfma_f32_16x16x32_bf16 v[78:81], v[146:149], v[208:211], v[78:81]
	v_mfma_f32_16x16x32_bf16 v[74:77], v[160:163], v[208:211], v[74:77]
	v_mfma_f32_16x16x32_bf16 v[126:129], v[156:159], v[188:191], v[126:129]
	v_mfma_f32_16x16x32_bf16 v[122:125], v[164:167], v[188:191], v[122:125]
	v_mfma_f32_16x16x32_bf16 v[110:113], v[156:159], v[196:199], v[110:113]
	v_mfma_f32_16x16x32_bf16 v[106:109], v[164:167], v[196:199], v[106:109]
	v_mfma_f32_16x16x32_bf16 v[94:97], v[156:159], v[204:207], v[94:97]
	v_mfma_f32_16x16x32_bf16 v[90:93], v[164:167], v[204:207], v[90:93]
	v_mfma_f32_16x16x32_bf16 v[78:81], v[156:159], v[212:215], v[78:81]
	v_mfma_f32_16x16x32_bf16 v[74:77], v[164:167], v[212:215], v[74:77]
	s_setprio 0
	s_setprio 1
	v_mfma_f32_16x16x32_bf16 v[118:121], v[168:171], v[184:187], v[118:121]
	v_mfma_f32_16x16x32_bf16 v[114:117], v[176:179], v[184:187], v[114:117]
	v_mfma_f32_16x16x32_bf16 v[102:105], v[168:171], v[192:195], v[102:105]
	v_mfma_f32_16x16x32_bf16 v[98:101], v[176:179], v[192:195], v[98:101]
	v_mfma_f32_16x16x32_bf16 v[86:89], v[168:171], v[200:203], v[86:89]
	v_mfma_f32_16x16x32_bf16 v[82:85], v[176:179], v[200:203], v[82:85]
	v_mfma_f32_16x16x32_bf16 v[70:73], v[168:171], v[208:211], v[70:73]
	v_mfma_f32_16x16x32_bf16 v[66:69], v[176:179], v[208:211], v[66:69]
	v_mfma_f32_16x16x32_bf16 v[118:121], v[172:175], v[188:191], v[118:121]
	v_mfma_f32_16x16x32_bf16 v[114:117], v[180:183], v[188:191], v[114:117]
	v_mfma_f32_16x16x32_bf16 v[102:105], v[172:175], v[196:199], v[102:105]
	v_mfma_f32_16x16x32_bf16 v[98:101], v[180:183], v[196:199], v[98:101]
	v_mfma_f32_16x16x32_bf16 v[86:89], v[172:175], v[204:207], v[86:89]
	v_mfma_f32_16x16x32_bf16 v[82:85], v[180:183], v[204:207], v[82:85]
	v_mfma_f32_16x16x32_bf16 v[70:73], v[172:175], v[212:215], v[70:73]
	v_mfma_f32_16x16x32_bf16 v[66:69], v[180:183], v[212:215], v[66:69]
	s_setprio 0
	s_barrier
	s_add_i32 s28, s33, s30
	v_lshl_add_u64 v[216:217], v[216:217], 0, s[12:13]
	s_mov_b32 m0, s28
	ds_read_b128 v[184:187], v154 offset:49152
	ds_read_b128 v[188:191], v154 offset:50176
	ds_read_b128 v[192:195], v154 offset:51200
	ds_read_b128 v[196:199], v154 offset:52224
	ds_read_b128 v[200:203], v154 offset:53248
	ds_read_b128 v[204:207], v154 offset:54272
	ds_read_b128 v[208:211], v154 offset:55296
	ds_read_b128 v[212:215], v154 offset:56320
	global_load_lds_dwordx4 v[216:217], off
	s_add_i32 m0, s28, 0x2000
	s_add_u32 s26, s26, 0x160080
	v_lshl_add_u64 v[216:217], v[218:219], 0, s[12:13]
	s_addc_u32 s27, s27, 0
	s_add_i32 s28, s53, s30
	global_load_lds_dwordx4 v[216:217], off
	s_mov_b32 m0, s28
	v_lshl_add_u64 v[216:217], s[26:27], 0, v[130:131]
	global_load_lds_dwordx4 v[216:217], off
	s_add_i32 m0, s28, 0x2000
	v_lshl_add_u64 v[216:217], s[26:27], 0, v[144:145]
	global_load_lds_dwordx4 v[216:217], off
	s_waitcnt vmcnt(6) lgkmcnt(0)
	s_barrier
	s_setprio 1
	v_mfma_f32_16x16x32_bf16 v[62:65], v[146:149], v[184:187], v[62:65]
	v_mfma_f32_16x16x32_bf16 v[58:61], v[160:163], v[184:187], v[58:61]
	v_mfma_f32_16x16x32_bf16 v[46:49], v[146:149], v[192:195], v[46:49]
	v_mfma_f32_16x16x32_bf16 v[42:45], v[160:163], v[192:195], v[42:45]
	v_mfma_f32_16x16x32_bf16 v[30:33], v[146:149], v[200:203], v[30:33]
	v_mfma_f32_16x16x32_bf16 v[26:29], v[160:163], v[200:203], v[26:29]
	v_mfma_f32_16x16x32_bf16 v[14:17], v[146:149], v[208:211], v[14:17]
	v_mfma_f32_16x16x32_bf16 v[10:13], v[160:163], v[208:211], v[10:13]
	v_mfma_f32_16x16x32_bf16 v[62:65], v[156:159], v[188:191], v[62:65]
	v_mfma_f32_16x16x32_bf16 v[58:61], v[164:167], v[188:191], v[58:61]
	v_mfma_f32_16x16x32_bf16 v[46:49], v[156:159], v[196:199], v[46:49]
	v_mfma_f32_16x16x32_bf16 v[42:45], v[164:167], v[196:199], v[42:45]
	v_mfma_f32_16x16x32_bf16 v[30:33], v[156:159], v[204:207], v[30:33]
	v_mfma_f32_16x16x32_bf16 v[26:29], v[164:167], v[204:207], v[26:29]
	v_mfma_f32_16x16x32_bf16 v[14:17], v[156:159], v[212:215], v[14:17]
	v_mfma_f32_16x16x32_bf16 v[10:13], v[164:167], v[212:215], v[10:13]
	s_setprio 0
	s_setprio 1
	v_mfma_f32_16x16x32_bf16 v[54:57], v[168:171], v[184:187], v[54:57]
	v_mfma_f32_16x16x32_bf16 v[50:53], v[176:179], v[184:187], v[50:53]
	v_mfma_f32_16x16x32_bf16 v[38:41], v[168:171], v[192:195], v[38:41]
	v_mfma_f32_16x16x32_bf16 v[34:37], v[176:179], v[192:195], v[34:37]
	v_mfma_f32_16x16x32_bf16 v[22:25], v[168:171], v[200:203], v[22:25]
	v_mfma_f32_16x16x32_bf16 v[18:21], v[176:179], v[200:203], v[18:21]
	v_mfma_f32_16x16x32_bf16 v[6:9], v[168:171], v[208:211], v[6:9]
	v_mfma_f32_16x16x32_bf16 v[2:5], v[176:179], v[208:211], v[2:5]
	v_mfma_f32_16x16x32_bf16 v[54:57], v[172:175], v[188:191], v[54:57]
	v_mfma_f32_16x16x32_bf16 v[50:53], v[180:183], v[188:191], v[50:53]
	v_mfma_f32_16x16x32_bf16 v[38:41], v[172:175], v[196:199], v[38:41]
	v_mfma_f32_16x16x32_bf16 v[34:37], v[180:183], v[196:199], v[34:37]
	v_mfma_f32_16x16x32_bf16 v[22:25], v[172:175], v[204:207], v[22:25]
	v_mfma_f32_16x16x32_bf16 v[18:21], v[180:183], v[204:207], v[18:21]
	v_mfma_f32_16x16x32_bf16 v[6:9], v[172:175], v[212:215], v[6:9]
	v_mfma_f32_16x16x32_bf16 v[2:5], v[180:183], v[212:215], v[2:5]
	s_setprio 0
	s_barrier
	s_add_i32 s50, s50, 2
	s_add_u32 s24, s24, 0x100
	s_addc_u32 s25, s25, 0
	s_add_u32 s48, s48, 0x100
	s_addc_u32 s49, s49, 0
	s_cmpk_lt_u32 s50, 0x56
	s_cbranch_scc1 .LBB0_621
	s_andn2_b64 vcc, exec, s[18:19]
	s_cbranch_vccnz .LBB0_624
	s_barrier
